# finalize: 16-lane sum-of-squares reductions via DPP row adds instead of dependent ds_bpermute round trips (32 of 64 chains)
# speedup vs baseline: 1.0014x; 1.0014x over previous
; template <int NCH, bool ROPE>
; DI void norm_rows16(int lane, size_t row0, bool is_ctx, int t0, const bf16_t* srcA, size_t ldA, int nA, const bf16_t* srcB, size_t ldB,
;                     const float* st, int st_idx, const float* gain, float inv_n, bf16_t* dst, size_t ldd, const float* tab) {
;     ...
;   for (int it = 0; it < 16; ++it) {
;     const int tk = it * 4 + tq;
;     const size_t row = row0 + tk;
;     const u32x4 u = ua[it];
;     const float pre = prea[it];
;     float f[8];
;     unpack8(u, f);
;     float ss = 0.f;
; #pragma unroll
;     for (int j = 0; j < 8; ++j) { f[j] *= pre; ss += f[j] * f[j]; }
;     ss += __shfl_xor(ss, 1); ss += __shfl_xor(ss, 2); ss += __shfl_xor(ss, 4); ss += __shfl_xor(ss, 8);
;     const float rs = rsqrtf(ss * inv_n + EPS);
; #pragma unroll
;     for (int j = 0; j < 8; ++j) f[j] *= rs * gv[j];
;     if (ROPE) {
;       float pf[8];
; #pragma unroll
;       for (int j = 0; j < 8; ++j) pf[j] = __shfl_xor(f[j], 1);
;       if (!is_ctx && sub >= 8 && sub < 12) {
;         const int pos = t0 + tk - CTXL;
;         const float* tr = (const float*)smem + ((sub < 10) ? (pos >> 6) : (pos & 63)) * 16;
; #pragma unroll
;         for (int j = 0; j < 8; ++j) {
;           const float c = tr[2 * j], sn = tr[2 * j + 1];
;           f[j] = (sub & 1) ? (pf[j] * sn + f[j] * c) : (f[j] * c - pf[j] * sn);
;         }
;       }
.LBB0_545:
	s_or_b64 exec, exec, s[0:1]
	s_waitcnt vmcnt(0)
	v_lshlrev_b32_e32 v114, 16, v62
	v_and_b32_e32 v115, 0xffff0000, v62
	v_pk_mul_f32 v[114:115], v[112:113], v[114:115] op_sel_hi:[0,1]
	v_lshlrev_b32_e32 v62, 16, v63
	v_and_b32_e32 v63, 0xffff0000, v63
	v_and_b32_e32 v85, 64, v192
	v_pk_mul_f32 v[116:117], v[114:115], v[114:115]
	v_pk_mul_f32 v[62:63], v[112:113], v[62:63] op_sel_hi:[0,1]
	v_add_u32_e32 v89, 64, v85
	v_pk_mul_f32 v[118:119], v[62:63], v[62:63]
	v_lshlrev_b32_e32 v120, 16, v64
	v_and_b32_e32 v121, 0xffff0000, v64
	v_add_f32_e32 v85, v116, v117
	v_pk_mul_f32 v[120:121], v[112:113], v[120:121] op_sel_hi:[0,1]
	v_add_f32_e32 v85, v118, v85
	v_pk_mul_f32 v[122:123], v[120:121], v[120:121]
	v_lshlrev_b32_e32 v64, 16, v65
	v_and_b32_e32 v65, 0xffff0000, v65
	v_add_f32_e32 v85, v119, v85
	v_xor_b32_e32 v81, 1, v192
	v_pk_mul_f32 v[128:129], v[112:113], v[64:65] op_sel_hi:[0,1]
	v_add_f32_e32 v85, v122, v85
	v_cmp_lt_i32_e64 s[0:1], v81, v89
	v_pk_mul_f32 v[64:65], v[128:129], v[128:129]
	v_add_f32_e32 v85, v123, v85
	v_cndmask_b32_e64 v81, v192, v81, s[0:1]
	v_add_f32_e32 v64, v64, v85
	v_lshlrev_b32_e32 v81, 2, v81
	v_add_f32_e32 v64, v65, v64
	v_xor_b32_e32 v85, 2, v192
	v_cmp_lt_i32_e64 s[0:1], v85, v89
	v_xor_b32_e32 v87, 4, v192
	v_xor_b32_e32 v93, 8, v192
	v_cndmask_b32_e64 v85, v192, v85, s[0:1]
	v_lshlrev_b32_e32 v85, 2, v85
	s_waitcnt lgkmcnt(0)
	s_nop 1
	v_add_f32_dpp v64, v64, v64 quad_perm:[1,0,3,2] row_mask:0xf bank_mask:0xf
	v_cmp_lt_i32_e64 s[0:1], v87, v89
	s_xor_b64 s[18:19], s[42:43], -1
	v_cmp_gt_u32_e64 s[46:47], 10, v91
	v_cndmask_b32_e64 v87, v192, v87, s[0:1]
	v_lshlrev_b32_e32 v87, 2, v87
	s_waitcnt lgkmcnt(0)
	s_nop 1
	v_add_f32_dpp v64, v64, v64 quad_perm:[2,3,0,1] row_mask:0xf bank_mask:0xf
	v_cmp_lt_i32_e64 s[0:1], v93, v89
	v_and_b32_e32 v91, 1, v124
	v_cmp_eq_u32_e64 s[44:45], 0, v91
	v_cndmask_b32_e64 v89, v192, v93, s[0:1]
	v_lshlrev_b32_e32 v89, 2, v89
	s_waitcnt lgkmcnt(0)
	s_nop 1
	v_add_f32_dpp v64, v64, v64 row_ror:4 row_mask:0xf bank_mask:0xf
	s_waitcnt lgkmcnt(0)
	s_nop 1
	v_add_f32_dpp v64, v64, v64 row_ror:8 row_mask:0xf bank_mask:0xf
	v_fmamk_f32 v64, v64, 0x3c2aaaab, v148
	v_mul_f32_e32 v65, 0x4b800000, v64
	v_cmp_gt_f32_e64 s[0:1], s2, v64
	s_nop 1
	v_cndmask_b32_e64 v64, v64, v65, s[0:1]
	v_rsq_f32_e32 v64, v64
	v_and_b32_e32 v65, 12, v124
	v_cmp_eq_u32_e64 s[40:41], 8, v65
	s_and_b64 s[40:41], s[18:19], s[40:41]
	v_mul_f32_e32 v65, 0x45800000, v64
	v_cndmask_b32_e64 v116, v64, v65, s[0:1]
	v_pk_mul_f32 v[112:113], v[74:75], v[116:117] op_sel_hi:[1,0]
	v_pk_mul_f32 v[64:65], v[72:73], v[116:117] op_sel_hi:[1,0]
	v_pk_mul_f32 v[112:113], v[62:63], v[112:113]
	v_pk_mul_f32 v[62:63], v[76:77], v[116:117] op_sel_hi:[1,0]
	v_pk_mul_f32 v[64:65], v[114:115], v[64:65]
	v_pk_mul_f32 v[114:115], v[120:121], v[62:63]
	v_pk_mul_f32 v[62:63], v[78:79], v[116:117] op_sel_hi:[1,0]
	ds_bpermute_b32 v122, v81, v64
	v_pk_mul_f32 v[116:117], v[128:129], v[62:63]
	ds_bpermute_b32 v123, v81, v65
	ds_bpermute_b32 v120, v81, v112
	ds_bpermute_b32 v121, v81, v113
	ds_bpermute_b32 v118, v81, v114
	ds_bpermute_b32 v119, v81, v115
	ds_bpermute_b32 v62, v81, v116
	ds_bpermute_b32 v63, v81, v117
	s_and_saveexec_b64 s[0:1], s[40:41]
	s_cbranch_execz .LBB0_547
	v_add_u32_e32 v91, 0xffffff00, v67
	v_lshlrev_b32_e32 v93, 6, v83
	v_cndmask_b32_e64 v91, v93, v91, s[46:47]
	v_add_u32_e32 v91, 0, v91
	ds_read_b128 v[128:131], v91
	ds_read_b128 v[132:135], v91 offset:16
	ds_read_b128 v[136:139], v91 offset:32
	ds_read_b128 v[140:143], v91 offset:48
	s_waitcnt lgkmcnt(3)
	v_mov_b32_e32 v144, v129
	v_mov_b32_e32 v145, v131
	v_pk_mul_f32 v[122:123], v[144:145], v[122:123]
	v_mov_b32_e32 v129, v130
	v_cndmask_b32_e64 v123, v123, -v123, s[44:45]
	v_cndmask_b32_e64 v122, v122, -v122, s[44:45]
	v_pk_fma_f32 v[64:65], v[64:65], v[128:129], v[122:123]
	s_waitcnt lgkmcnt(2)
	v_mov_b32_e32 v122, v133
	v_mov_b32_e32 v123, v135
	v_pk_mul_f32 v[120:121], v[122:123], v[120:121]
	v_mov_b32_e32 v133, v134
	v_cndmask_b32_e64 v121, v121, -v121, s[44:45]
	v_cndmask_b32_e64 v120, v120, -v120, s[44:45]
	v_pk_fma_f32 v[112:113], v[112:113], v[132:133], v[120:121]
	s_waitcnt lgkmcnt(1)
	v_mov_b32_e32 v120, v137
	v_mov_b32_e32 v121, v139
	v_pk_mul_f32 v[118:119], v[120:121], v[118:119]
	v_mov_b32_e32 v137, v138
	v_cndmask_b32_e64 v119, v119, -v119, s[44:45]
	v_cndmask_b32_e64 v118, v118, -v118, s[44:45]
	v_pk_fma_f32 v[114:115], v[114:115], v[136:137], v[118:119]
	s_waitcnt lgkmcnt(0)
	v_mov_b32_e32 v118, v141
	v_mov_b32_e32 v119, v143
	v_pk_mul_f32 v[62:63], v[118:119], v[62:63]
	v_mov_b32_e32 v141, v142
	v_cndmask_b32_e64 v63, v63, -v63, s[44:45]
	v_cndmask_b32_e64 v62, v62, -v62, s[44:45]
	v_pk_fma_f32 v[116:117], v[116:117], v[140:141], v[62:63]

; template <int NCH, bool ROPE>
; DI void norm_rows16(int lane, size_t row0, bool is_ctx, int t0, const bf16_t* srcA, size_t ldA, int nA, const bf16_t* srcB, size_t ldB,
;                     const float* st, int st_idx, const float* gain, float inv_n, bf16_t* dst, size_t ldd, const float* tab) {
;     ...
;   for (int it = 0; it < 16; ++it) {
;     const int tk = it * 4 + tq;
;     const size_t row = row0 + tk;
;     const u32x4 u = ua[it];
;     const float pre = prea[it];
;     float f[8];
;     unpack8(u, f);
;     float ss = 0.f;
; #pragma unroll
;     for (int j = 0; j < 8; ++j) { f[j] *= pre; ss += f[j] * f[j]; }
;     ss += __shfl_xor(ss, 1); ss += __shfl_xor(ss, 2); ss += __shfl_xor(ss, 4); ss += __shfl_xor(ss, 8);
;     const float rs = rsqrtf(ss * inv_n + EPS);
; #pragma unroll
;     for (int j = 0; j < 8; ++j) f[j] *= rs * gv[j];
;     if (ROPE) {
;       float pf[8];
; #pragma unroll
;       for (int j = 0; j < 8; ++j) pf[j] = __shfl_xor(f[j], 1);
;       if (!is_ctx && sub >= 8 && sub < 12) {
;         const int pos = t0 + tk - CTXL;
;         const float* tr = (const float*)smem + ((sub < 10) ? (pos >> 6) : (pos & 63)) * 16;
; #pragma unroll
;         for (int j = 0; j < 8; ++j) {
;           const float c = tr[2 * j], sn = tr[2 * j + 1];
;           f[j] = (sub & 1) ? (pf[j] * sn + f[j] * c) : (f[j] * c - pf[j] * sn);
;         }
;       }
.LBB0_549:
	s_or_b64 exec, exec, s[0:1]
	v_lshlrev_b32_e32 v64, 16, v58
	v_and_b32_e32 v65, 0xffff0000, v58
	v_pk_mul_f32 v[64:65], v[110:111], v[64:65] op_sel_hi:[0,1]
	v_lshlrev_b32_e32 v58, 16, v59
	v_and_b32_e32 v59, 0xffff0000, v59
	v_pk_mul_f32 v[108:109], v[64:65], v[64:65]
	v_pk_mul_f32 v[112:113], v[110:111], v[58:59] op_sel_hi:[0,1]
	v_pk_mul_f32 v[58:59], v[112:113], v[112:113]
	v_lshlrev_b32_e32 v114, 16, v60
	v_and_b32_e32 v115, 0xffff0000, v60
	v_add_f32_e32 v0, v108, v109
	v_pk_mul_f32 v[114:115], v[110:111], v[114:115] op_sel_hi:[0,1]
	v_add_f32_e32 v0, v58, v0
	v_pk_mul_f32 v[116:117], v[114:115], v[114:115]
	v_lshlrev_b32_e32 v60, 16, v61
	v_and_b32_e32 v61, 0xffff0000, v61
	v_add_f32_e32 v0, v59, v0
	v_pk_mul_f32 v[110:111], v[110:111], v[60:61] op_sel_hi:[0,1]
	v_add_f32_e32 v0, v116, v0
	v_pk_mul_f32 v[60:61], v[110:111], v[110:111]
	v_add_f32_e32 v0, v117, v0
	v_add_f32_e32 v0, v60, v0
	v_add_f32_e32 v0, v61, v0
	s_waitcnt lgkmcnt(0)
	s_nop 1
	v_add_f32_dpp v0, v0, v0 quad_perm:[1,0,3,2] row_mask:0xf bank_mask:0xf
	s_waitcnt lgkmcnt(0)
	s_nop 1
	v_add_f32_dpp v0, v0, v0 quad_perm:[2,3,0,1] row_mask:0xf bank_mask:0xf
	s_waitcnt lgkmcnt(0)
	s_nop 1
	v_add_f32_dpp v0, v0, v0 row_ror:4 row_mask:0xf bank_mask:0xf
	s_waitcnt lgkmcnt(0)
	s_nop 1
	v_add_f32_dpp v0, v0, v0 row_ror:8 row_mask:0xf bank_mask:0xf
	v_fmamk_f32 v0, v0, 0x3c2aaaab, v148
	v_mul_f32_e32 v58, 0x4b800000, v0
	v_cmp_gt_f32_e64 s[0:1], s2, v0
	s_nop 1
	v_cndmask_b32_e64 v0, v0, v58, s[0:1]
	v_rsq_f32_e32 v0, v0
	s_nop 0
	v_mul_f32_e32 v58, 0x45800000, v0
	v_cndmask_b32_e64 v0, v0, v58, s[0:1]
	v_pk_mul_f32 v[58:59], v[72:73], v[0:1] op_sel_hi:[1,0]
	v_pk_mul_f32 v[60:61], v[74:75], v[0:1] op_sel_hi:[1,0]
	v_pk_mul_f32 v[108:109], v[76:77], v[0:1] op_sel_hi:[1,0]
	v_pk_mul_f32 v[116:117], v[78:79], v[0:1] op_sel_hi:[1,0]
	v_pk_mul_f32 v[58:59], v[64:65], v[58:59]
	v_pk_mul_f32 v[60:61], v[112:113], v[60:61]
	v_pk_mul_f32 v[64:65], v[114:115], v[108:109]
	v_pk_mul_f32 v[108:109], v[110:111], v[116:117]
	ds_bpermute_b32 v116, v81, v58
	ds_bpermute_b32 v117, v81, v59
	ds_bpermute_b32 v114, v81, v60
	ds_bpermute_b32 v115, v81, v61
	ds_bpermute_b32 v112, v81, v64
	ds_bpermute_b32 v113, v81, v65
	ds_bpermute_b32 v110, v81, v108
	ds_bpermute_b32 v111, v81, v109
	v_or_b32_e32 v0, 4, v83
	s_and_saveexec_b64 s[0:1], s[40:41]
	s_cbranch_execz .LBB0_551
	v_add_u32_e32 v91, 0xffffff00, v67
	v_lshlrev_b32_e32 v93, 6, v0
	v_cndmask_b32_e64 v91, v93, v91, s[46:47]
	v_add_u32_e32 v91, 0, v91
	ds_read_b128 v[118:121], v91
	ds_read_b128 v[128:131], v91 offset:16
	ds_read_b128 v[132:135], v91 offset:32
	ds_read_b128 v[136:139], v91 offset:48
	s_waitcnt lgkmcnt(3)
	v_mov_b32_e32 v122, v119
	v_mov_b32_e32 v123, v121
	v_pk_mul_f32 v[116:117], v[122:123], v[116:117]
	v_mov_b32_e32 v119, v120
	v_cndmask_b32_e64 v117, v117, -v117, s[44:45]
	v_cndmask_b32_e64 v116, v116, -v116, s[44:45]
	v_pk_fma_f32 v[58:59], v[58:59], v[118:119], v[116:117]
	s_waitcnt lgkmcnt(2)
	v_mov_b32_e32 v116, v129
	v_mov_b32_e32 v117, v131
	v_pk_mul_f32 v[114:115], v[116:117], v[114:115]
	v_mov_b32_e32 v129, v130
	v_cndmask_b32_e64 v115, v115, -v115, s[44:45]
	v_cndmask_b32_e64 v114, v114, -v114, s[44:45]
	v_pk_fma_f32 v[60:61], v[60:61], v[128:129], v[114:115]
	s_waitcnt lgkmcnt(1)
	v_mov_b32_e32 v114, v133
	v_mov_b32_e32 v115, v135
	v_pk_mul_f32 v[112:113], v[114:115], v[112:113]
	v_mov_b32_e32 v133, v134
	v_cndmask_b32_e64 v113, v113, -v113, s[44:45]
	v_cndmask_b32_e64 v112, v112, -v112, s[44:45]
	v_pk_fma_f32 v[64:65], v[64:65], v[132:133], v[112:113]
	s_waitcnt lgkmcnt(0)
	v_mov_b32_e32 v112, v137
	v_mov_b32_e32 v113, v139
	v_pk_mul_f32 v[110:111], v[112:113], v[110:111]
	v_mov_b32_e32 v137, v138
	v_cndmask_b32_e64 v111, v111, -v111, s[44:45]
	v_cndmask_b32_e64 v110, v110, -v110, s[44:45]
	v_pk_fma_f32 v[108:109], v[108:109], v[136:137], v[110:111]

; template <int NCH, bool ROPE>
; DI void norm_rows16(int lane, size_t row0, bool is_ctx, int t0, const bf16_t* srcA, size_t ldA, int nA, const bf16_t* srcB, size_t ldB,
;                     const float* st, int st_idx, const float* gain, float inv_n, bf16_t* dst, size_t ldd, const float* tab) {
;     ...
;   for (int it = 0; it < 16; ++it) {
;     const int tk = it * 4 + tq;
;     const size_t row = row0 + tk;
;     const u32x4 u = ua[it];
;     const float pre = prea[it];
;     float f[8];
;     unpack8(u, f);
;     float ss = 0.f;
; #pragma unroll
;     for (int j = 0; j < 8; ++j) { f[j] *= pre; ss += f[j] * f[j]; }
;     ss += __shfl_xor(ss, 1); ss += __shfl_xor(ss, 2); ss += __shfl_xor(ss, 4); ss += __shfl_xor(ss, 8);
;     const float rs = rsqrtf(ss * inv_n + EPS);
; #pragma unroll
;     for (int j = 0; j < 8; ++j) f[j] *= rs * gv[j];
;     if (ROPE) {
;       float pf[8];
; #pragma unroll
;       for (int j = 0; j < 8; ++j) pf[j] = __shfl_xor(f[j], 1);
;       if (!is_ctx && sub >= 8 && sub < 12) {
;         const int pos = t0 + tk - CTXL;
;         const float* tr = (const float*)smem + ((sub < 10) ? (pos >> 6) : (pos & 63)) * 16;
; #pragma unroll
;         for (int j = 0; j < 8; ++j) {
;           const float c = tr[2 * j], sn = tr[2 * j + 1];
;           f[j] = (sub & 1) ? (pf[j] * sn + f[j] * c) : (f[j] * c - pf[j] * sn);
;         }
;       }
.LBB0_553:
	s_or_b64 exec, exec, s[0:1]
	s_nop 0
	v_lshlrev_b32_e32 v58, 16, v54
	v_and_b32_e32 v59, 0xffff0000, v54
	v_pk_mul_f32 v[58:59], v[106:107], v[58:59] op_sel_hi:[0,1]
	v_lshlrev_b32_e32 v54, 16, v55
	v_and_b32_e32 v55, 0xffff0000, v55
	v_pk_mul_f32 v[60:61], v[58:59], v[58:59]
	v_pk_mul_f32 v[64:65], v[106:107], v[54:55] op_sel_hi:[0,1]
	v_pk_mul_f32 v[54:55], v[64:65], v[64:65]
	v_lshlrev_b32_e32 v108, 16, v56
	v_and_b32_e32 v109, 0xffff0000, v56
	v_add_f32_e32 v0, v60, v61
	v_pk_mul_f32 v[108:109], v[106:107], v[108:109] op_sel_hi:[0,1]
	v_add_f32_e32 v0, v54, v0
	s_waitcnt lgkmcnt(0)
	v_pk_mul_f32 v[110:111], v[108:109], v[108:109]
	v_lshlrev_b32_e32 v56, 16, v57
	v_and_b32_e32 v57, 0xffff0000, v57
	v_add_f32_e32 v0, v55, v0
	v_pk_mul_f32 v[106:107], v[106:107], v[56:57] op_sel_hi:[0,1]
	v_add_f32_e32 v0, v110, v0
	v_pk_mul_f32 v[56:57], v[106:107], v[106:107]
	v_add_f32_e32 v0, v111, v0
	v_add_f32_e32 v0, v56, v0
	v_add_f32_e32 v0, v57, v0
	s_waitcnt lgkmcnt(0)
	s_nop 1
	v_add_f32_dpp v0, v0, v0 quad_perm:[1,0,3,2] row_mask:0xf bank_mask:0xf
	s_waitcnt lgkmcnt(0)
	s_nop 1
	v_add_f32_dpp v0, v0, v0 quad_perm:[2,3,0,1] row_mask:0xf bank_mask:0xf
	s_waitcnt lgkmcnt(0)
	s_nop 1
	v_add_f32_dpp v0, v0, v0 row_ror:4 row_mask:0xf bank_mask:0xf
	s_waitcnt lgkmcnt(0)
	s_nop 1
	v_add_f32_dpp v0, v0, v0 row_ror:8 row_mask:0xf bank_mask:0xf
	v_fmamk_f32 v0, v0, 0x3c2aaaab, v148
	v_mul_f32_e32 v54, 0x4b800000, v0
	v_cmp_gt_f32_e64 s[0:1], s2, v0
	s_nop 1
	v_cndmask_b32_e64 v0, v0, v54, s[0:1]
	v_rsq_f32_e32 v0, v0
	s_nop 0
	v_mul_f32_e32 v54, 0x45800000, v0
	v_cndmask_b32_e64 v0, v0, v54, s[0:1]
	v_pk_mul_f32 v[54:55], v[72:73], v[0:1] op_sel_hi:[1,0]
	v_pk_mul_f32 v[56:57], v[74:75], v[0:1] op_sel_hi:[1,0]
	v_pk_mul_f32 v[60:61], v[76:77], v[0:1] op_sel_hi:[1,0]
	v_pk_mul_f32 v[110:111], v[78:79], v[0:1] op_sel_hi:[1,0]
	v_pk_mul_f32 v[54:55], v[58:59], v[54:55]
	v_pk_mul_f32 v[56:57], v[64:65], v[56:57]
	v_pk_mul_f32 v[58:59], v[108:109], v[60:61]
	v_pk_mul_f32 v[60:61], v[106:107], v[110:111]
	ds_bpermute_b32 v110, v81, v54
	ds_bpermute_b32 v111, v81, v55
	ds_bpermute_b32 v108, v81, v56
	ds_bpermute_b32 v109, v81, v57
	ds_bpermute_b32 v106, v81, v58
	ds_bpermute_b32 v107, v81, v59
	ds_bpermute_b32 v64, v81, v60
	ds_bpermute_b32 v65, v81, v61
	v_or_b32_e32 v0, 8, v83
	s_and_saveexec_b64 s[0:1], s[40:41]
	s_cbranch_execz .LBB0_555
	v_add_u32_e32 v91, 0xffffff00, v67
	v_lshlrev_b32_e32 v93, 6, v0
	v_cndmask_b32_e64 v91, v93, v91, s[46:47]
	v_add_u32_e32 v91, 0, v91
	ds_read_b128 v[112:115], v91
	ds_read_b128 v[116:119], v91 offset:16
	ds_read_b128 v[120:123], v91 offset:32
	ds_read_b128 v[128:131], v91 offset:48
	s_waitcnt lgkmcnt(3)
	v_mov_b32_e32 v132, v113
	v_mov_b32_e32 v133, v115
	v_pk_mul_f32 v[110:111], v[132:133], v[110:111]
	v_mov_b32_e32 v113, v114
	v_cndmask_b32_e64 v111, v111, -v111, s[44:45]
	v_cndmask_b32_e64 v110, v110, -v110, s[44:45]
	v_pk_fma_f32 v[54:55], v[54:55], v[112:113], v[110:111]
	s_waitcnt lgkmcnt(2)
	v_mov_b32_e32 v110, v117
	v_mov_b32_e32 v111, v119
	v_pk_mul_f32 v[108:109], v[110:111], v[108:109]
	v_mov_b32_e32 v117, v118
	v_cndmask_b32_e64 v109, v109, -v109, s[44:45]
	v_cndmask_b32_e64 v108, v108, -v108, s[44:45]
	v_pk_fma_f32 v[56:57], v[56:57], v[116:117], v[108:109]
	s_waitcnt lgkmcnt(1)
	v_mov_b32_e32 v108, v121
	v_mov_b32_e32 v109, v123
	v_pk_mul_f32 v[106:107], v[108:109], v[106:107]
	v_mov_b32_e32 v121, v122
	v_cndmask_b32_e64 v107, v107, -v107, s[44:45]
	v_cndmask_b32_e64 v106, v106, -v106, s[44:45]
	v_pk_fma_f32 v[58:59], v[58:59], v[120:121], v[106:107]
	s_waitcnt lgkmcnt(0)
	v_mov_b32_e32 v106, v129
	v_mov_b32_e32 v107, v131
	v_pk_mul_f32 v[64:65], v[106:107], v[64:65]
	v_mov_b32_e32 v129, v130
	v_cndmask_b32_e64 v65, v65, -v65, s[44:45]
	v_cndmask_b32_e64 v64, v64, -v64, s[44:45]
	v_pk_fma_f32 v[60:61], v[60:61], v[128:129], v[64:65]

; template <int NCH, bool ROPE>
; DI void norm_rows16(int lane, size_t row0, bool is_ctx, int t0, const bf16_t* srcA, size_t ldA, int nA, const bf16_t* srcB, size_t ldB,
;                     const float* st, int st_idx, const float* gain, float inv_n, bf16_t* dst, size_t ldd, const float* tab) {
;     ...
;   for (int it = 0; it < 16; ++it) {
;     const int tk = it * 4 + tq;
;     const size_t row = row0 + tk;
;     const u32x4 u = ua[it];
;     const float pre = prea[it];
;     float f[8];
;     unpack8(u, f);
;     float ss = 0.f;
; #pragma unroll
;     for (int j = 0; j < 8; ++j) { f[j] *= pre; ss += f[j] * f[j]; }
;     ss += __shfl_xor(ss, 1); ss += __shfl_xor(ss, 2); ss += __shfl_xor(ss, 4); ss += __shfl_xor(ss, 8);
;     const float rs = rsqrtf(ss * inv_n + EPS);
; #pragma unroll
;     for (int j = 0; j < 8; ++j) f[j] *= rs * gv[j];
;     if (ROPE) {
;       float pf[8];
; #pragma unroll
;       for (int j = 0; j < 8; ++j) pf[j] = __shfl_xor(f[j], 1);
;       if (!is_ctx && sub >= 8 && sub < 12) {
;         const int pos = t0 + tk - CTXL;
;         const float* tr = (const float*)smem + ((sub < 10) ? (pos >> 6) : (pos & 63)) * 16;
; #pragma unroll
;         for (int j = 0; j < 8; ++j) {
;           const float c = tr[2 * j], sn = tr[2 * j + 1];
;           f[j] = (sub & 1) ? (pf[j] * sn + f[j] * c) : (f[j] * c - pf[j] * sn);
;         }
;       }
.LBB0_557:
	s_or_b64 exec, exec, s[0:1]
	s_nop 0
	v_lshlrev_b32_e32 v54, 16, v50
	v_and_b32_e32 v55, 0xffff0000, v50
	v_pk_mul_f32 v[54:55], v[104:105], v[54:55] op_sel_hi:[0,1]
	v_lshlrev_b32_e32 v50, 16, v51
	v_and_b32_e32 v51, 0xffff0000, v51
	v_pk_mul_f32 v[56:57], v[54:55], v[54:55]
	v_pk_mul_f32 v[58:59], v[104:105], v[50:51] op_sel_hi:[0,1]
	v_pk_mul_f32 v[50:51], v[58:59], v[58:59]
	v_lshlrev_b32_e32 v60, 16, v52
	v_and_b32_e32 v61, 0xffff0000, v52
	v_add_f32_e32 v0, v56, v57
	v_pk_mul_f32 v[60:61], v[104:105], v[60:61] op_sel_hi:[0,1]
	v_add_f32_e32 v0, v50, v0
	s_waitcnt lgkmcnt(0)
	v_pk_mul_f32 v[64:65], v[60:61], v[60:61]
	v_lshlrev_b32_e32 v52, 16, v53
	v_and_b32_e32 v53, 0xffff0000, v53
	v_add_f32_e32 v0, v51, v0
	v_pk_mul_f32 v[104:105], v[104:105], v[52:53] op_sel_hi:[0,1]
	v_add_f32_e32 v0, v64, v0
	v_pk_mul_f32 v[52:53], v[104:105], v[104:105]
	v_add_f32_e32 v0, v65, v0
	v_add_f32_e32 v0, v52, v0
	v_add_f32_e32 v0, v53, v0
	s_waitcnt lgkmcnt(0)
	s_nop 1
	v_add_f32_dpp v0, v0, v0 quad_perm:[1,0,3,2] row_mask:0xf bank_mask:0xf
	s_waitcnt lgkmcnt(0)
	s_nop 1
	v_add_f32_dpp v0, v0, v0 quad_perm:[2,3,0,1] row_mask:0xf bank_mask:0xf
	s_waitcnt lgkmcnt(0)
	s_nop 1
	v_add_f32_dpp v0, v0, v0 row_ror:4 row_mask:0xf bank_mask:0xf
	s_waitcnt lgkmcnt(0)
	s_nop 1
	v_add_f32_dpp v0, v0, v0 row_ror:8 row_mask:0xf bank_mask:0xf
	v_fmamk_f32 v0, v0, 0x3c2aaaab, v148
	v_mul_f32_e32 v50, 0x4b800000, v0
	v_cmp_gt_f32_e64 s[0:1], s2, v0
	s_nop 1
	v_cndmask_b32_e64 v0, v0, v50, s[0:1]
	v_rsq_f32_e32 v0, v0
	s_nop 0
	v_mul_f32_e32 v50, 0x45800000, v0
	v_cndmask_b32_e64 v0, v0, v50, s[0:1]
	v_pk_mul_f32 v[50:51], v[72:73], v[0:1] op_sel_hi:[1,0]
	v_pk_mul_f32 v[52:53], v[74:75], v[0:1] op_sel_hi:[1,0]
	v_pk_mul_f32 v[56:57], v[76:77], v[0:1] op_sel_hi:[1,0]
	v_pk_mul_f32 v[64:65], v[78:79], v[0:1] op_sel_hi:[1,0]
	v_pk_mul_f32 v[50:51], v[54:55], v[50:51]
	v_pk_mul_f32 v[52:53], v[58:59], v[52:53]
	v_pk_mul_f32 v[54:55], v[60:61], v[56:57]
	v_pk_mul_f32 v[56:57], v[104:105], v[64:65]
	ds_bpermute_b32 v104, v81, v50
	ds_bpermute_b32 v105, v81, v51
	ds_bpermute_b32 v64, v81, v52
	ds_bpermute_b32 v65, v81, v53
	ds_bpermute_b32 v60, v81, v54
	ds_bpermute_b32 v61, v81, v55
	ds_bpermute_b32 v58, v81, v56
	ds_bpermute_b32 v59, v81, v57
	v_or_b32_e32 v0, 12, v83
	s_and_saveexec_b64 s[0:1], s[40:41]
	s_cbranch_execz .LBB0_559
	v_add_u32_e32 v91, 0xffffff00, v67
	v_lshlrev_b32_e32 v93, 6, v0
	v_cndmask_b32_e64 v91, v93, v91, s[46:47]
	v_add_u32_e32 v91, 0, v91
	ds_read_b128 v[106:109], v91
	ds_read_b128 v[110:113], v91 offset:16
	ds_read_b128 v[114:117], v91 offset:32
	ds_read_b128 v[118:121], v91 offset:48
	s_waitcnt lgkmcnt(3)
	v_mov_b32_e32 v122, v107
	v_mov_b32_e32 v123, v109
	v_pk_mul_f32 v[104:105], v[122:123], v[104:105]
	v_mov_b32_e32 v107, v108
	v_cndmask_b32_e64 v105, v105, -v105, s[44:45]
	v_cndmask_b32_e64 v104, v104, -v104, s[44:45]
	v_pk_fma_f32 v[50:51], v[50:51], v[106:107], v[104:105]
	s_waitcnt lgkmcnt(2)
	v_mov_b32_e32 v104, v111
	v_mov_b32_e32 v105, v113
	v_pk_mul_f32 v[64:65], v[104:105], v[64:65]
	v_mov_b32_e32 v111, v112
	v_cndmask_b32_e64 v65, v65, -v65, s[44:45]
	v_cndmask_b32_e64 v64, v64, -v64, s[44:45]
	v_pk_fma_f32 v[52:53], v[52:53], v[110:111], v[64:65]
	s_waitcnt lgkmcnt(1)
	v_mov_b32_e32 v64, v115
	v_mov_b32_e32 v65, v117
	v_pk_mul_f32 v[60:61], v[64:65], v[60:61]
	v_mov_b32_e32 v115, v116
	v_cndmask_b32_e64 v61, v61, -v61, s[44:45]
	v_cndmask_b32_e64 v60, v60, -v60, s[44:45]
	v_pk_fma_f32 v[54:55], v[54:55], v[114:115], v[60:61]
	s_waitcnt lgkmcnt(0)
	v_mov_b32_e32 v60, v119
	v_mov_b32_e32 v61, v121
	v_pk_mul_f32 v[58:59], v[60:61], v[58:59]
	v_mov_b32_e32 v119, v120
	v_cndmask_b32_e64 v59, v59, -v59, s[44:45]
	v_cndmask_b32_e64 v58, v58, -v58, s[44:45]
	v_pk_fma_f32 v[56:57], v[56:57], v[118:119], v[58:59]

; template <int NCH, bool ROPE>
; DI void norm_rows16(int lane, size_t row0, bool is_ctx, int t0, const bf16_t* srcA, size_t ldA, int nA, const bf16_t* srcB, size_t ldB,
;                     const float* st, int st_idx, const float* gain, float inv_n, bf16_t* dst, size_t ldd, const float* tab) {
;     ...
;   for (int it = 0; it < 16; ++it) {
;     const int tk = it * 4 + tq;
;     const size_t row = row0 + tk;
;     const u32x4 u = ua[it];
;     const float pre = prea[it];
;     float f[8];
;     unpack8(u, f);
;     float ss = 0.f;
; #pragma unroll
;     for (int j = 0; j < 8; ++j) { f[j] *= pre; ss += f[j] * f[j]; }
;     ss += __shfl_xor(ss, 1); ss += __shfl_xor(ss, 2); ss += __shfl_xor(ss, 4); ss += __shfl_xor(ss, 8);
;     const float rs = rsqrtf(ss * inv_n + EPS);
; #pragma unroll
;     for (int j = 0; j < 8; ++j) f[j] *= rs * gv[j];
;     if (ROPE) {
;       float pf[8];
; #pragma unroll
;       for (int j = 0; j < 8; ++j) pf[j] = __shfl_xor(f[j], 1);
;       if (!is_ctx && sub >= 8 && sub < 12) {
;         const int pos = t0 + tk - CTXL;
;         const float* tr = (const float*)smem + ((sub < 10) ? (pos >> 6) : (pos & 63)) * 16;
; #pragma unroll
;         for (int j = 0; j < 8; ++j) {
;           const float c = tr[2 * j], sn = tr[2 * j + 1];
;           f[j] = (sub & 1) ? (pf[j] * sn + f[j] * c) : (f[j] * c - pf[j] * sn);
;         }
;       }
.LBB0_561:
	s_or_b64 exec, exec, s[0:1]
	s_nop 0
	v_lshlrev_b32_e32 v50, 16, v46
	v_and_b32_e32 v51, 0xffff0000, v46
	v_pk_mul_f32 v[50:51], v[102:103], v[50:51] op_sel_hi:[0,1]
	v_lshlrev_b32_e32 v46, 16, v47
	v_and_b32_e32 v47, 0xffff0000, v47
	v_pk_mul_f32 v[52:53], v[50:51], v[50:51]
	v_pk_mul_f32 v[54:55], v[102:103], v[46:47] op_sel_hi:[0,1]
	v_pk_mul_f32 v[46:47], v[54:55], v[54:55]
	v_lshlrev_b32_e32 v56, 16, v48
	v_and_b32_e32 v57, 0xffff0000, v48
	v_add_f32_e32 v0, v52, v53
	v_pk_mul_f32 v[56:57], v[102:103], v[56:57] op_sel_hi:[0,1]
	v_add_f32_e32 v0, v46, v0
	s_waitcnt lgkmcnt(0)
	v_pk_mul_f32 v[58:59], v[56:57], v[56:57]
	v_lshlrev_b32_e32 v48, 16, v49
	v_and_b32_e32 v49, 0xffff0000, v49
	v_add_f32_e32 v0, v47, v0
	v_pk_mul_f32 v[60:61], v[102:103], v[48:49] op_sel_hi:[0,1]
	v_add_f32_e32 v0, v58, v0
	v_pk_mul_f32 v[48:49], v[60:61], v[60:61]
	v_add_f32_e32 v0, v59, v0
	v_add_f32_e32 v0, v48, v0
	v_add_f32_e32 v0, v49, v0
	s_waitcnt lgkmcnt(0)
	s_nop 1
	v_add_f32_dpp v0, v0, v0 quad_perm:[1,0,3,2] row_mask:0xf bank_mask:0xf
	s_waitcnt lgkmcnt(0)
	s_nop 1
	v_add_f32_dpp v0, v0, v0 quad_perm:[2,3,0,1] row_mask:0xf bank_mask:0xf
	s_waitcnt lgkmcnt(0)
	s_nop 1
	v_add_f32_dpp v0, v0, v0 row_ror:4 row_mask:0xf bank_mask:0xf
	s_waitcnt lgkmcnt(0)
	s_nop 1
	v_add_f32_dpp v0, v0, v0 row_ror:8 row_mask:0xf bank_mask:0xf
	v_fmamk_f32 v0, v0, 0x3c2aaaab, v148
	v_mul_f32_e32 v46, 0x4b800000, v0
	v_cmp_gt_f32_e64 s[0:1], s2, v0
	s_nop 1
	v_cndmask_b32_e64 v0, v0, v46, s[0:1]
	v_rsq_f32_e32 v0, v0
	s_nop 0
	v_mul_f32_e32 v46, 0x45800000, v0
	v_cndmask_b32_e64 v0, v0, v46, s[0:1]
	v_pk_mul_f32 v[46:47], v[72:73], v[0:1] op_sel_hi:[1,0]
	v_pk_mul_f32 v[48:49], v[74:75], v[0:1] op_sel_hi:[1,0]
	v_pk_mul_f32 v[52:53], v[76:77], v[0:1] op_sel_hi:[1,0]
	v_pk_mul_f32 v[58:59], v[78:79], v[0:1] op_sel_hi:[1,0]
	v_pk_mul_f32 v[46:47], v[50:51], v[46:47]
	v_pk_mul_f32 v[48:49], v[54:55], v[48:49]
	v_pk_mul_f32 v[50:51], v[56:57], v[52:53]
	v_pk_mul_f32 v[52:53], v[60:61], v[58:59]
	ds_bpermute_b32 v60, v81, v46
	ds_bpermute_b32 v61, v81, v47
	ds_bpermute_b32 v58, v81, v48
	ds_bpermute_b32 v59, v81, v49
	ds_bpermute_b32 v56, v81, v50
	ds_bpermute_b32 v57, v81, v51
	ds_bpermute_b32 v54, v81, v52
	ds_bpermute_b32 v55, v81, v53
	v_or_b32_e32 v0, 16, v83
	s_and_saveexec_b64 s[0:1], s[40:41]
	s_cbranch_execz .LBB0_563
	v_add_u32_e32 v64, 0xffffff00, v67
	v_lshlrev_b32_e32 v65, 6, v0
	v_cndmask_b32_e64 v64, v65, v64, s[46:47]
	v_add_u32_e32 v64, 0, v64
	ds_read_b128 v[102:105], v64
	ds_read_b128 v[106:109], v64 offset:16
	ds_read_b128 v[110:113], v64 offset:32
	ds_read_b128 v[114:117], v64 offset:48
	s_waitcnt lgkmcnt(3)
	v_mov_b32_e32 v64, v103
	v_mov_b32_e32 v65, v105
	v_pk_mul_f32 v[60:61], v[64:65], v[60:61]
	v_mov_b32_e32 v103, v104
	v_cndmask_b32_e64 v61, v61, -v61, s[44:45]
	v_cndmask_b32_e64 v60, v60, -v60, s[44:45]
	v_pk_fma_f32 v[46:47], v[46:47], v[102:103], v[60:61]
	s_waitcnt lgkmcnt(2)
	v_mov_b32_e32 v60, v107
	v_mov_b32_e32 v61, v109
	v_pk_mul_f32 v[58:59], v[60:61], v[58:59]
	v_mov_b32_e32 v107, v108
	v_cndmask_b32_e64 v59, v59, -v59, s[44:45]
	v_cndmask_b32_e64 v58, v58, -v58, s[44:45]
	v_pk_fma_f32 v[48:49], v[48:49], v[106:107], v[58:59]
	s_waitcnt lgkmcnt(1)
	v_mov_b32_e32 v58, v111
	v_mov_b32_e32 v59, v113
	v_pk_mul_f32 v[56:57], v[58:59], v[56:57]
	v_mov_b32_e32 v111, v112
	v_cndmask_b32_e64 v57, v57, -v57, s[44:45]
	v_cndmask_b32_e64 v56, v56, -v56, s[44:45]
	v_pk_fma_f32 v[50:51], v[50:51], v[110:111], v[56:57]
	s_waitcnt lgkmcnt(0)
	v_mov_b32_e32 v56, v115
	v_mov_b32_e32 v57, v117
	v_pk_mul_f32 v[54:55], v[56:57], v[54:55]
	v_mov_b32_e32 v115, v116
	v_cndmask_b32_e64 v55, v55, -v55, s[44:45]
	v_cndmask_b32_e64 v54, v54, -v54, s[44:45]
	v_pk_fma_f32 v[52:53], v[52:53], v[114:115], v[54:55]

; template <int NCH, bool ROPE>
; DI void norm_rows16(int lane, size_t row0, bool is_ctx, int t0, const bf16_t* srcA, size_t ldA, int nA, const bf16_t* srcB, size_t ldB,
;                     const float* st, int st_idx, const float* gain, float inv_n, bf16_t* dst, size_t ldd, const float* tab) {
;     ...
;   for (int it = 0; it < 16; ++it) {
;     const int tk = it * 4 + tq;
;     const size_t row = row0 + tk;
;     const u32x4 u = ua[it];
;     const float pre = prea[it];
;     float f[8];
;     unpack8(u, f);
;     float ss = 0.f;
; #pragma unroll
;     for (int j = 0; j < 8; ++j) { f[j] *= pre; ss += f[j] * f[j]; }
;     ss += __shfl_xor(ss, 1); ss += __shfl_xor(ss, 2); ss += __shfl_xor(ss, 4); ss += __shfl_xor(ss, 8);
;     const float rs = rsqrtf(ss * inv_n + EPS);
; #pragma unroll
;     for (int j = 0; j < 8; ++j) f[j] *= rs * gv[j];
;     if (ROPE) {
;       float pf[8];
; #pragma unroll
;       for (int j = 0; j < 8; ++j) pf[j] = __shfl_xor(f[j], 1);
;       if (!is_ctx && sub >= 8 && sub < 12) {
;         const int pos = t0 + tk - CTXL;
;         const float* tr = (const float*)smem + ((sub < 10) ? (pos >> 6) : (pos & 63)) * 16;
; #pragma unroll
;         for (int j = 0; j < 8; ++j) {
;           const float c = tr[2 * j], sn = tr[2 * j + 1];
;           f[j] = (sub & 1) ? (pf[j] * sn + f[j] * c) : (f[j] * c - pf[j] * sn);
;         }
;       }
.LBB0_565:
	s_or_b64 exec, exec, s[0:1]
	s_nop 0
	v_lshlrev_b32_e32 v46, 16, v42
	v_and_b32_e32 v47, 0xffff0000, v42
	v_pk_mul_f32 v[46:47], v[100:101], v[46:47] op_sel_hi:[0,1]
	v_lshlrev_b32_e32 v42, 16, v43
	v_and_b32_e32 v43, 0xffff0000, v43
	v_pk_mul_f32 v[48:49], v[46:47], v[46:47]
	v_pk_mul_f32 v[50:51], v[100:101], v[42:43] op_sel_hi:[0,1]
	v_pk_mul_f32 v[42:43], v[50:51], v[50:51]
	v_lshlrev_b32_e32 v52, 16, v44
	v_and_b32_e32 v53, 0xffff0000, v44
	v_add_f32_e32 v0, v48, v49
	v_pk_mul_f32 v[52:53], v[100:101], v[52:53] op_sel_hi:[0,1]
	v_add_f32_e32 v0, v42, v0
	s_waitcnt lgkmcnt(0)
	v_pk_mul_f32 v[54:55], v[52:53], v[52:53]
	v_lshlrev_b32_e32 v44, 16, v45
	v_and_b32_e32 v45, 0xffff0000, v45
	v_add_f32_e32 v0, v43, v0
	v_pk_mul_f32 v[56:57], v[100:101], v[44:45] op_sel_hi:[0,1]
	v_add_f32_e32 v0, v54, v0
	v_pk_mul_f32 v[44:45], v[56:57], v[56:57]
	v_add_f32_e32 v0, v55, v0
	v_add_f32_e32 v0, v44, v0
	v_add_f32_e32 v0, v45, v0
	s_waitcnt lgkmcnt(0)
	s_nop 1
	v_add_f32_dpp v0, v0, v0 quad_perm:[1,0,3,2] row_mask:0xf bank_mask:0xf
	s_waitcnt lgkmcnt(0)
	s_nop 1
	v_add_f32_dpp v0, v0, v0 quad_perm:[2,3,0,1] row_mask:0xf bank_mask:0xf
	s_waitcnt lgkmcnt(0)
	s_nop 1
	v_add_f32_dpp v0, v0, v0 row_ror:4 row_mask:0xf bank_mask:0xf
	s_waitcnt lgkmcnt(0)
	s_nop 1
	v_add_f32_dpp v0, v0, v0 row_ror:8 row_mask:0xf bank_mask:0xf
	v_fmamk_f32 v0, v0, 0x3c2aaaab, v148
	v_mul_f32_e32 v42, 0x4b800000, v0
	v_cmp_gt_f32_e64 s[0:1], s2, v0
	s_nop 1
	v_cndmask_b32_e64 v0, v0, v42, s[0:1]
	v_rsq_f32_e32 v0, v0
	s_nop 0
	v_mul_f32_e32 v42, 0x45800000, v0
	v_cndmask_b32_e64 v0, v0, v42, s[0:1]
	v_pk_mul_f32 v[42:43], v[72:73], v[0:1] op_sel_hi:[1,0]
	v_pk_mul_f32 v[44:45], v[74:75], v[0:1] op_sel_hi:[1,0]
	v_pk_mul_f32 v[48:49], v[76:77], v[0:1] op_sel_hi:[1,0]
	v_pk_mul_f32 v[54:55], v[78:79], v[0:1] op_sel_hi:[1,0]
	v_pk_mul_f32 v[42:43], v[46:47], v[42:43]
	v_pk_mul_f32 v[44:45], v[50:51], v[44:45]
	v_pk_mul_f32 v[46:47], v[52:53], v[48:49]
	v_pk_mul_f32 v[48:49], v[56:57], v[54:55]
	ds_bpermute_b32 v56, v81, v42
	ds_bpermute_b32 v57, v81, v43
	ds_bpermute_b32 v54, v81, v44
	ds_bpermute_b32 v55, v81, v45
	ds_bpermute_b32 v52, v81, v46
	ds_bpermute_b32 v53, v81, v47
	ds_bpermute_b32 v50, v81, v48
	ds_bpermute_b32 v51, v81, v49
	v_or_b32_e32 v0, 20, v83
	s_and_saveexec_b64 s[0:1], s[40:41]
	s_cbranch_execz .LBB0_567
	v_add_u32_e32 v58, 0xffffff00, v67
	v_lshlrev_b32_e32 v59, 6, v0
	v_cndmask_b32_e64 v58, v59, v58, s[46:47]
	v_add_u32_e32 v64, 0, v58
	ds_read_b128 v[58:61], v64
	ds_read_b128 v[100:103], v64 offset:16
	ds_read_b128 v[104:107], v64 offset:32
	ds_read_b128 v[108:111], v64 offset:48
	s_waitcnt lgkmcnt(3)
	v_mov_b32_e32 v64, v59
	v_mov_b32_e32 v65, v61
	v_pk_mul_f32 v[56:57], v[64:65], v[56:57]
	v_mov_b32_e32 v59, v60
	v_cndmask_b32_e64 v57, v57, -v57, s[44:45]
	v_cndmask_b32_e64 v56, v56, -v56, s[44:45]
	v_pk_fma_f32 v[42:43], v[42:43], v[58:59], v[56:57]
	s_waitcnt lgkmcnt(2)
	v_mov_b32_e32 v56, v101
	v_mov_b32_e32 v57, v103
	v_pk_mul_f32 v[54:55], v[56:57], v[54:55]
	v_mov_b32_e32 v101, v102
	v_cndmask_b32_e64 v55, v55, -v55, s[44:45]
	v_cndmask_b32_e64 v54, v54, -v54, s[44:45]
	v_pk_fma_f32 v[44:45], v[44:45], v[100:101], v[54:55]
	s_waitcnt lgkmcnt(1)
	v_mov_b32_e32 v54, v105
	v_mov_b32_e32 v55, v107
	v_pk_mul_f32 v[52:53], v[54:55], v[52:53]
	v_mov_b32_e32 v105, v106
	v_cndmask_b32_e64 v53, v53, -v53, s[44:45]
	v_cndmask_b32_e64 v52, v52, -v52, s[44:45]
	v_pk_fma_f32 v[46:47], v[46:47], v[104:105], v[52:53]
	s_waitcnt lgkmcnt(0)
	v_mov_b32_e32 v52, v109
	v_mov_b32_e32 v53, v111
	v_pk_mul_f32 v[50:51], v[52:53], v[50:51]
	v_mov_b32_e32 v109, v110
	v_cndmask_b32_e64 v51, v51, -v51, s[44:45]
	v_cndmask_b32_e64 v50, v50, -v50, s[44:45]
	v_pk_fma_f32 v[48:49], v[48:49], v[108:109], v[50:51]

; template <int NCH, bool ROPE>
; DI void norm_rows16(int lane, size_t row0, bool is_ctx, int t0, const bf16_t* srcA, size_t ldA, int nA, const bf16_t* srcB, size_t ldB,
;                     const float* st, int st_idx, const float* gain, float inv_n, bf16_t* dst, size_t ldd, const float* tab) {
;     ...
;   for (int it = 0; it < 16; ++it) {
;     const int tk = it * 4 + tq;
;     const size_t row = row0 + tk;
;     const u32x4 u = ua[it];
;     const float pre = prea[it];
;     float f[8];
;     unpack8(u, f);
;     float ss = 0.f;
; #pragma unroll
;     for (int j = 0; j < 8; ++j) { f[j] *= pre; ss += f[j] * f[j]; }
;     ss += __shfl_xor(ss, 1); ss += __shfl_xor(ss, 2); ss += __shfl_xor(ss, 4); ss += __shfl_xor(ss, 8);
;     const float rs = rsqrtf(ss * inv_n + EPS);
; #pragma unroll
;     for (int j = 0; j < 8; ++j) f[j] *= rs * gv[j];
;     if (ROPE) {
;       float pf[8];
; #pragma unroll
;       for (int j = 0; j < 8; ++j) pf[j] = __shfl_xor(f[j], 1);
;       if (!is_ctx && sub >= 8 && sub < 12) {
;         const int pos = t0 + tk - CTXL;
;         const float* tr = (const float*)smem + ((sub < 10) ? (pos >> 6) : (pos & 63)) * 16;
; #pragma unroll
;         for (int j = 0; j < 8; ++j) {
;           const float c = tr[2 * j], sn = tr[2 * j + 1];
;           f[j] = (sub & 1) ? (pf[j] * sn + f[j] * c) : (f[j] * c - pf[j] * sn);
;         }
;       }
.LBB0_569:
	s_or_b64 exec, exec, s[0:1]
	s_nop 0
	v_lshlrev_b32_e32 v42, 16, v38
	v_and_b32_e32 v43, 0xffff0000, v38
	v_pk_mul_f32 v[42:43], v[98:99], v[42:43] op_sel_hi:[0,1]
	v_lshlrev_b32_e32 v38, 16, v39
	v_and_b32_e32 v39, 0xffff0000, v39
	v_pk_mul_f32 v[44:45], v[42:43], v[42:43]
	v_pk_mul_f32 v[46:47], v[98:99], v[38:39] op_sel_hi:[0,1]
	v_pk_mul_f32 v[38:39], v[46:47], v[46:47]
	v_lshlrev_b32_e32 v48, 16, v40
	v_and_b32_e32 v49, 0xffff0000, v40
	v_add_f32_e32 v0, v44, v45
	v_pk_mul_f32 v[48:49], v[98:99], v[48:49] op_sel_hi:[0,1]
	v_add_f32_e32 v0, v38, v0
	s_waitcnt lgkmcnt(0)
	v_pk_mul_f32 v[50:51], v[48:49], v[48:49]
	v_lshlrev_b32_e32 v40, 16, v41
	v_and_b32_e32 v41, 0xffff0000, v41
	v_add_f32_e32 v0, v39, v0
	v_pk_mul_f32 v[52:53], v[98:99], v[40:41] op_sel_hi:[0,1]
	v_add_f32_e32 v0, v50, v0
	v_pk_mul_f32 v[40:41], v[52:53], v[52:53]
	v_add_f32_e32 v0, v51, v0
	v_add_f32_e32 v0, v40, v0
	v_add_f32_e32 v0, v41, v0
	s_waitcnt lgkmcnt(0)
	s_nop 1
	v_add_f32_dpp v0, v0, v0 quad_perm:[1,0,3,2] row_mask:0xf bank_mask:0xf
	s_waitcnt lgkmcnt(0)
	s_nop 1
	v_add_f32_dpp v0, v0, v0 quad_perm:[2,3,0,1] row_mask:0xf bank_mask:0xf
	s_waitcnt lgkmcnt(0)
	s_nop 1
	v_add_f32_dpp v0, v0, v0 row_ror:4 row_mask:0xf bank_mask:0xf
	s_waitcnt lgkmcnt(0)
	s_nop 1
	v_add_f32_dpp v0, v0, v0 row_ror:8 row_mask:0xf bank_mask:0xf
	v_fmamk_f32 v0, v0, 0x3c2aaaab, v148
	v_mul_f32_e32 v38, 0x4b800000, v0
	v_cmp_gt_f32_e64 s[0:1], s2, v0
	s_nop 1
	v_cndmask_b32_e64 v0, v0, v38, s[0:1]
	v_rsq_f32_e32 v0, v0
	s_nop 0
	v_mul_f32_e32 v38, 0x45800000, v0
	v_cndmask_b32_e64 v0, v0, v38, s[0:1]
	v_pk_mul_f32 v[38:39], v[72:73], v[0:1] op_sel_hi:[1,0]
	v_pk_mul_f32 v[40:41], v[74:75], v[0:1] op_sel_hi:[1,0]
	v_pk_mul_f32 v[44:45], v[76:77], v[0:1] op_sel_hi:[1,0]
	v_pk_mul_f32 v[50:51], v[78:79], v[0:1] op_sel_hi:[1,0]
	v_pk_mul_f32 v[38:39], v[42:43], v[38:39]
	v_pk_mul_f32 v[40:41], v[46:47], v[40:41]
	v_pk_mul_f32 v[42:43], v[48:49], v[44:45]
	v_pk_mul_f32 v[44:45], v[52:53], v[50:51]
	ds_bpermute_b32 v52, v81, v38
	ds_bpermute_b32 v53, v81, v39
	ds_bpermute_b32 v50, v81, v40
	ds_bpermute_b32 v51, v81, v41
	ds_bpermute_b32 v48, v81, v42
	ds_bpermute_b32 v49, v81, v43
	ds_bpermute_b32 v46, v81, v44
	ds_bpermute_b32 v47, v81, v45
	v_or_b32_e32 v0, 24, v83
	s_and_saveexec_b64 s[0:1], s[40:41]
	s_cbranch_execz .LBB0_571
	v_add_u32_e32 v54, 0xffffff00, v67
	v_lshlrev_b32_e32 v55, 6, v0
	v_cndmask_b32_e64 v54, v55, v54, s[46:47]
	v_add_u32_e32 v64, 0, v54
	ds_read_b128 v[54:57], v64
	ds_read_b128 v[58:61], v64 offset:16
	ds_read_b128 v[98:101], v64 offset:32
	ds_read_b128 v[102:105], v64 offset:48
	s_waitcnt lgkmcnt(3)
	v_mov_b32_e32 v64, v55
	v_mov_b32_e32 v65, v57
	v_pk_mul_f32 v[52:53], v[64:65], v[52:53]
	v_mov_b32_e32 v55, v56
	v_cndmask_b32_e64 v53, v53, -v53, s[44:45]
	v_cndmask_b32_e64 v52, v52, -v52, s[44:45]
	v_pk_fma_f32 v[38:39], v[38:39], v[54:55], v[52:53]
	s_waitcnt lgkmcnt(2)
	v_mov_b32_e32 v52, v59
	v_mov_b32_e32 v53, v61
	v_pk_mul_f32 v[50:51], v[52:53], v[50:51]
	v_mov_b32_e32 v59, v60
	v_cndmask_b32_e64 v51, v51, -v51, s[44:45]
	v_cndmask_b32_e64 v50, v50, -v50, s[44:45]
	v_pk_fma_f32 v[40:41], v[40:41], v[58:59], v[50:51]
	s_waitcnt lgkmcnt(1)
	v_mov_b32_e32 v50, v99
	v_mov_b32_e32 v51, v101
	v_pk_mul_f32 v[48:49], v[50:51], v[48:49]
	v_mov_b32_e32 v99, v100
	v_cndmask_b32_e64 v49, v49, -v49, s[44:45]
	v_cndmask_b32_e64 v48, v48, -v48, s[44:45]
	v_pk_fma_f32 v[42:43], v[42:43], v[98:99], v[48:49]
	s_waitcnt lgkmcnt(0)
	v_mov_b32_e32 v48, v103
	v_mov_b32_e32 v49, v105
	v_pk_mul_f32 v[46:47], v[48:49], v[46:47]
	v_mov_b32_e32 v103, v104
	v_cndmask_b32_e64 v47, v47, -v47, s[44:45]
	v_cndmask_b32_e64 v46, v46, -v46, s[44:45]
	v_pk_fma_f32 v[44:45], v[44:45], v[102:103], v[46:47]

; template <int NCH, bool ROPE>
; DI void norm_rows16(int lane, size_t row0, bool is_ctx, int t0, const bf16_t* srcA, size_t ldA, int nA, const bf16_t* srcB, size_t ldB,
;                     const float* st, int st_idx, const float* gain, float inv_n, bf16_t* dst, size_t ldd, const float* tab) {
;     ...
;   for (int it = 0; it < 16; ++it) {
;     const int tk = it * 4 + tq;
;     const size_t row = row0 + tk;
;     const u32x4 u = ua[it];
;     const float pre = prea[it];
;     float f[8];
;     unpack8(u, f);
;     float ss = 0.f;
; #pragma unroll
;     for (int j = 0; j < 8; ++j) { f[j] *= pre; ss += f[j] * f[j]; }
;     ss += __shfl_xor(ss, 1); ss += __shfl_xor(ss, 2); ss += __shfl_xor(ss, 4); ss += __shfl_xor(ss, 8);
;     const float rs = rsqrtf(ss * inv_n + EPS);
; #pragma unroll
;     for (int j = 0; j < 8; ++j) f[j] *= rs * gv[j];
;     if (ROPE) {
;       float pf[8];
; #pragma unroll
;       for (int j = 0; j < 8; ++j) pf[j] = __shfl_xor(f[j], 1);
;       if (!is_ctx && sub >= 8 && sub < 12) {
;         const int pos = t0 + tk - CTXL;
;         const float* tr = (const float*)smem + ((sub < 10) ? (pos >> 6) : (pos & 63)) * 16;
; #pragma unroll
;         for (int j = 0; j < 8; ++j) {
;           const float c = tr[2 * j], sn = tr[2 * j + 1];
;           f[j] = (sub & 1) ? (pf[j] * sn + f[j] * c) : (f[j] * c - pf[j] * sn);
;         }
;       }
.LBB0_573:
	s_or_b64 exec, exec, s[0:1]
	s_nop 0
	v_lshlrev_b32_e32 v38, 16, v34
	v_and_b32_e32 v39, 0xffff0000, v34
	v_pk_mul_f32 v[38:39], v[96:97], v[38:39] op_sel_hi:[0,1]
	v_lshlrev_b32_e32 v34, 16, v35
	v_and_b32_e32 v35, 0xffff0000, v35
	v_pk_mul_f32 v[40:41], v[38:39], v[38:39]
	v_pk_mul_f32 v[42:43], v[96:97], v[34:35] op_sel_hi:[0,1]
	v_pk_mul_f32 v[34:35], v[42:43], v[42:43]
	v_lshlrev_b32_e32 v44, 16, v36
	v_and_b32_e32 v45, 0xffff0000, v36
	v_add_f32_e32 v0, v40, v41
	v_pk_mul_f32 v[44:45], v[96:97], v[44:45] op_sel_hi:[0,1]
	v_add_f32_e32 v0, v34, v0
	s_waitcnt lgkmcnt(0)
	v_pk_mul_f32 v[46:47], v[44:45], v[44:45]
	v_lshlrev_b32_e32 v36, 16, v37
	v_and_b32_e32 v37, 0xffff0000, v37
	v_add_f32_e32 v0, v35, v0
	v_pk_mul_f32 v[48:49], v[96:97], v[36:37] op_sel_hi:[0,1]
	v_add_f32_e32 v0, v46, v0
	v_pk_mul_f32 v[36:37], v[48:49], v[48:49]
	v_add_f32_e32 v0, v47, v0
	v_add_f32_e32 v0, v36, v0
	v_add_f32_e32 v0, v37, v0
	s_waitcnt lgkmcnt(0)
	s_nop 1
	v_add_f32_dpp v0, v0, v0 quad_perm:[1,0,3,2] row_mask:0xf bank_mask:0xf
	s_waitcnt lgkmcnt(0)
	s_nop 1
	v_add_f32_dpp v0, v0, v0 quad_perm:[2,3,0,1] row_mask:0xf bank_mask:0xf
	s_waitcnt lgkmcnt(0)
	s_nop 1
	v_add_f32_dpp v0, v0, v0 row_ror:4 row_mask:0xf bank_mask:0xf
	s_waitcnt lgkmcnt(0)
	s_nop 1
	v_add_f32_dpp v0, v0, v0 row_ror:8 row_mask:0xf bank_mask:0xf
	v_fmamk_f32 v0, v0, 0x3c2aaaab, v148
	v_mul_f32_e32 v34, 0x4b800000, v0
	v_cmp_gt_f32_e64 s[0:1], s2, v0
	s_nop 1
	v_cndmask_b32_e64 v0, v0, v34, s[0:1]
	v_rsq_f32_e32 v0, v0
	s_nop 0
	v_mul_f32_e32 v34, 0x45800000, v0
	v_cndmask_b32_e64 v0, v0, v34, s[0:1]
	v_pk_mul_f32 v[34:35], v[72:73], v[0:1] op_sel_hi:[1,0]
	v_pk_mul_f32 v[36:37], v[74:75], v[0:1] op_sel_hi:[1,0]
	v_pk_mul_f32 v[40:41], v[76:77], v[0:1] op_sel_hi:[1,0]
	v_pk_mul_f32 v[46:47], v[78:79], v[0:1] op_sel_hi:[1,0]
	v_pk_mul_f32 v[34:35], v[38:39], v[34:35]
	v_pk_mul_f32 v[36:37], v[42:43], v[36:37]
	v_pk_mul_f32 v[38:39], v[44:45], v[40:41]
	v_pk_mul_f32 v[40:41], v[48:49], v[46:47]
	ds_bpermute_b32 v48, v81, v34
	ds_bpermute_b32 v49, v81, v35
	ds_bpermute_b32 v46, v81, v36
	ds_bpermute_b32 v47, v81, v37
	ds_bpermute_b32 v44, v81, v38
	ds_bpermute_b32 v45, v81, v39
	ds_bpermute_b32 v42, v81, v40
	ds_bpermute_b32 v43, v81, v41
	v_or_b32_e32 v0, 28, v83
	s_and_saveexec_b64 s[0:1], s[40:41]
	s_cbranch_execz .LBB0_575
	v_add_u32_e32 v50, 0xffffff00, v67
	v_lshlrev_b32_e32 v51, 6, v0
	v_cndmask_b32_e64 v50, v51, v50, s[46:47]
	v_add_u32_e32 v64, 0, v50
	ds_read_b128 v[50:53], v64
	ds_read_b128 v[54:57], v64 offset:16
	ds_read_b128 v[58:61], v64 offset:32
	ds_read_b128 v[96:99], v64 offset:48
	s_waitcnt lgkmcnt(3)
	v_mov_b32_e32 v64, v51
	v_mov_b32_e32 v65, v53
	v_pk_mul_f32 v[48:49], v[64:65], v[48:49]
	v_mov_b32_e32 v51, v52
	v_cndmask_b32_e64 v49, v49, -v49, s[44:45]
	v_cndmask_b32_e64 v48, v48, -v48, s[44:45]
	v_pk_fma_f32 v[34:35], v[34:35], v[50:51], v[48:49]
	s_waitcnt lgkmcnt(2)
	v_mov_b32_e32 v48, v55
	v_mov_b32_e32 v49, v57
	v_pk_mul_f32 v[46:47], v[48:49], v[46:47]
	v_mov_b32_e32 v55, v56
	v_cndmask_b32_e64 v47, v47, -v47, s[44:45]
	v_cndmask_b32_e64 v46, v46, -v46, s[44:45]
	v_pk_fma_f32 v[36:37], v[36:37], v[54:55], v[46:47]
	s_waitcnt lgkmcnt(1)
	v_mov_b32_e32 v46, v59
	v_mov_b32_e32 v47, v61
	v_pk_mul_f32 v[44:45], v[46:47], v[44:45]
	v_mov_b32_e32 v59, v60
	v_cndmask_b32_e64 v45, v45, -v45, s[44:45]
	v_cndmask_b32_e64 v44, v44, -v44, s[44:45]
	v_pk_fma_f32 v[38:39], v[38:39], v[58:59], v[44:45]
	s_waitcnt lgkmcnt(0)
	v_mov_b32_e32 v44, v97
	v_mov_b32_e32 v45, v99
	v_pk_mul_f32 v[42:43], v[44:45], v[42:43]
	v_mov_b32_e32 v97, v98
	v_cndmask_b32_e64 v43, v43, -v43, s[44:45]
	v_cndmask_b32_e64 v42, v42, -v42, s[44:45]
	v_pk_fma_f32 v[40:41], v[40:41], v[96:97], v[42:43]

; template <int NCH, bool ROPE>
; DI void norm_rows16(int lane, size_t row0, bool is_ctx, int t0, const bf16_t* srcA, size_t ldA, int nA, const bf16_t* srcB, size_t ldB,
;                     const float* st, int st_idx, const float* gain, float inv_n, bf16_t* dst, size_t ldd, const float* tab) {
;     ...
;   for (int it = 0; it < 16; ++it) {
;     const int tk = it * 4 + tq;
;     const size_t row = row0 + tk;
;     const u32x4 u = ua[it];
;     const float pre = prea[it];
;     float f[8];
;     unpack8(u, f);
;     float ss = 0.f;
; #pragma unroll
;     for (int j = 0; j < 8; ++j) { f[j] *= pre; ss += f[j] * f[j]; }
;     ss += __shfl_xor(ss, 1); ss += __shfl_xor(ss, 2); ss += __shfl_xor(ss, 4); ss += __shfl_xor(ss, 8);
;     const float rs = rsqrtf(ss * inv_n + EPS);
; #pragma unroll
;     for (int j = 0; j < 8; ++j) f[j] *= rs * gv[j];
;     if (ROPE) {
;       float pf[8];
; #pragma unroll
;       for (int j = 0; j < 8; ++j) pf[j] = __shfl_xor(f[j], 1);
;       if (!is_ctx && sub >= 8 && sub < 12) {
;         const int pos = t0 + tk - CTXL;
;         const float* tr = (const float*)smem + ((sub < 10) ? (pos >> 6) : (pos & 63)) * 16;
; #pragma unroll
;         for (int j = 0; j < 8; ++j) {
;           const float c = tr[2 * j], sn = tr[2 * j + 1];
;           f[j] = (sub & 1) ? (pf[j] * sn + f[j] * c) : (f[j] * c - pf[j] * sn);
;         }
;       }
.LBB0_577:
	s_or_b64 exec, exec, s[0:1]
	s_nop 0
	v_lshlrev_b32_e32 v34, 16, v30
	v_and_b32_e32 v35, 0xffff0000, v30
	v_pk_mul_f32 v[34:35], v[94:95], v[34:35] op_sel_hi:[0,1]
	v_lshlrev_b32_e32 v30, 16, v31
	v_and_b32_e32 v31, 0xffff0000, v31
	v_pk_mul_f32 v[36:37], v[34:35], v[34:35]
	v_pk_mul_f32 v[38:39], v[94:95], v[30:31] op_sel_hi:[0,1]
	v_pk_mul_f32 v[30:31], v[38:39], v[38:39]
	v_lshlrev_b32_e32 v40, 16, v32
	v_and_b32_e32 v41, 0xffff0000, v32
	v_add_f32_e32 v0, v36, v37
	v_pk_mul_f32 v[40:41], v[94:95], v[40:41] op_sel_hi:[0,1]
	v_add_f32_e32 v0, v30, v0
	s_waitcnt lgkmcnt(0)
	v_pk_mul_f32 v[42:43], v[40:41], v[40:41]
	v_lshlrev_b32_e32 v32, 16, v33
	v_and_b32_e32 v33, 0xffff0000, v33
	v_add_f32_e32 v0, v31, v0
	v_pk_mul_f32 v[44:45], v[94:95], v[32:33] op_sel_hi:[0,1]
	v_add_f32_e32 v0, v42, v0
	v_pk_mul_f32 v[32:33], v[44:45], v[44:45]
	v_add_f32_e32 v0, v43, v0
	v_add_f32_e32 v0, v32, v0
	v_add_f32_e32 v0, v33, v0
	s_waitcnt lgkmcnt(0)
	s_nop 1
	v_add_f32_dpp v0, v0, v0 quad_perm:[1,0,3,2] row_mask:0xf bank_mask:0xf
	s_waitcnt lgkmcnt(0)
	s_nop 1
	v_add_f32_dpp v0, v0, v0 quad_perm:[2,3,0,1] row_mask:0xf bank_mask:0xf
	s_waitcnt lgkmcnt(0)
	s_nop 1
	v_add_f32_dpp v0, v0, v0 row_ror:4 row_mask:0xf bank_mask:0xf
	s_waitcnt lgkmcnt(0)
	s_nop 1
	v_add_f32_dpp v0, v0, v0 row_ror:8 row_mask:0xf bank_mask:0xf
	v_fmamk_f32 v0, v0, 0x3c2aaaab, v148
	v_mul_f32_e32 v30, 0x4b800000, v0
	v_cmp_gt_f32_e64 s[0:1], s2, v0
	s_nop 1
	v_cndmask_b32_e64 v0, v0, v30, s[0:1]
	v_rsq_f32_e32 v0, v0
	s_nop 0
	v_mul_f32_e32 v30, 0x45800000, v0
	v_cndmask_b32_e64 v0, v0, v30, s[0:1]
	v_pk_mul_f32 v[30:31], v[72:73], v[0:1] op_sel_hi:[1,0]
	v_pk_mul_f32 v[32:33], v[74:75], v[0:1] op_sel_hi:[1,0]
	v_pk_mul_f32 v[36:37], v[76:77], v[0:1] op_sel_hi:[1,0]
	v_pk_mul_f32 v[42:43], v[78:79], v[0:1] op_sel_hi:[1,0]
	v_pk_mul_f32 v[30:31], v[34:35], v[30:31]
	v_pk_mul_f32 v[32:33], v[38:39], v[32:33]
	v_pk_mul_f32 v[34:35], v[40:41], v[36:37]
	v_pk_mul_f32 v[36:37], v[44:45], v[42:43]
	ds_bpermute_b32 v44, v81, v30
	ds_bpermute_b32 v45, v81, v31
	ds_bpermute_b32 v42, v81, v32
	ds_bpermute_b32 v43, v81, v33
	ds_bpermute_b32 v40, v81, v34
	ds_bpermute_b32 v41, v81, v35
	ds_bpermute_b32 v38, v81, v36
	ds_bpermute_b32 v39, v81, v37
	v_or_b32_e32 v0, 32, v83
	s_and_saveexec_b64 s[0:1], s[40:41]
	s_cbranch_execz .LBB0_579
	v_add_u32_e32 v46, 0xffffff00, v67
	v_lshlrev_b32_e32 v47, 6, v0
	v_cndmask_b32_e64 v46, v47, v46, s[46:47]
	v_add_u32_e32 v58, 0, v46
	ds_read_b128 v[46:49], v58
	ds_read_b128 v[50:53], v58 offset:16
	ds_read_b128 v[54:57], v58 offset:32
	ds_read_b128 v[58:61], v58 offset:48
	s_waitcnt lgkmcnt(3)
	v_mov_b32_e32 v64, v47
	v_mov_b32_e32 v65, v49
	v_pk_mul_f32 v[44:45], v[64:65], v[44:45]
	v_mov_b32_e32 v47, v48
	v_cndmask_b32_e64 v45, v45, -v45, s[44:45]
	v_cndmask_b32_e64 v44, v44, -v44, s[44:45]
	v_pk_fma_f32 v[30:31], v[30:31], v[46:47], v[44:45]
	s_waitcnt lgkmcnt(2)
	v_mov_b32_e32 v44, v51
	v_mov_b32_e32 v45, v53
	v_pk_mul_f32 v[42:43], v[44:45], v[42:43]
	v_mov_b32_e32 v51, v52
	v_cndmask_b32_e64 v43, v43, -v43, s[44:45]
	v_cndmask_b32_e64 v42, v42, -v42, s[44:45]
	v_pk_fma_f32 v[32:33], v[32:33], v[50:51], v[42:43]
	s_waitcnt lgkmcnt(1)
	v_mov_b32_e32 v42, v55
	v_mov_b32_e32 v43, v57
	v_pk_mul_f32 v[40:41], v[42:43], v[40:41]
	v_mov_b32_e32 v55, v56
	v_cndmask_b32_e64 v41, v41, -v41, s[44:45]
	v_cndmask_b32_e64 v40, v40, -v40, s[44:45]
	v_pk_fma_f32 v[34:35], v[34:35], v[54:55], v[40:41]
	s_waitcnt lgkmcnt(0)
	v_mov_b32_e32 v40, v59
	v_mov_b32_e32 v41, v61
	v_pk_mul_f32 v[38:39], v[40:41], v[38:39]
	v_mov_b32_e32 v59, v60
	v_cndmask_b32_e64 v39, v39, -v39, s[44:45]
	v_cndmask_b32_e64 v38, v38, -v38, s[44:45]
	v_pk_fma_f32 v[36:37], v[36:37], v[58:59], v[38:39]

; template <int NCH, bool ROPE>
; DI void norm_rows16(int lane, size_t row0, bool is_ctx, int t0, const bf16_t* srcA, size_t ldA, int nA, const bf16_t* srcB, size_t ldB,
;                     const float* st, int st_idx, const float* gain, float inv_n, bf16_t* dst, size_t ldd, const float* tab) {
;     ...
;   for (int it = 0; it < 16; ++it) {
;     const int tk = it * 4 + tq;
;     const size_t row = row0 + tk;
;     const u32x4 u = ua[it];
;     const float pre = prea[it];
;     float f[8];
;     unpack8(u, f);
;     float ss = 0.f;
; #pragma unroll
;     for (int j = 0; j < 8; ++j) { f[j] *= pre; ss += f[j] * f[j]; }
;     ss += __shfl_xor(ss, 1); ss += __shfl_xor(ss, 2); ss += __shfl_xor(ss, 4); ss += __shfl_xor(ss, 8);
;     const float rs = rsqrtf(ss * inv_n + EPS);
; #pragma unroll
;     for (int j = 0; j < 8; ++j) f[j] *= rs * gv[j];
;     if (ROPE) {
;       float pf[8];
; #pragma unroll
;       for (int j = 0; j < 8; ++j) pf[j] = __shfl_xor(f[j], 1);
;       if (!is_ctx && sub >= 8 && sub < 12) {
;         const int pos = t0 + tk - CTXL;
;         const float* tr = (const float*)smem + ((sub < 10) ? (pos >> 6) : (pos & 63)) * 16;
; #pragma unroll
;         for (int j = 0; j < 8; ++j) {
;           const float c = tr[2 * j], sn = tr[2 * j + 1];
;           f[j] = (sub & 1) ? (pf[j] * sn + f[j] * c) : (f[j] * c - pf[j] * sn);
;         }
;       }
.LBB0_581:
	s_or_b64 exec, exec, s[0:1]
	s_nop 0
	v_lshlrev_b32_e32 v30, 16, v26
	v_and_b32_e32 v31, 0xffff0000, v26
	v_pk_mul_f32 v[30:31], v[92:93], v[30:31] op_sel_hi:[0,1]
	v_lshlrev_b32_e32 v26, 16, v27
	v_and_b32_e32 v27, 0xffff0000, v27
	v_pk_mul_f32 v[32:33], v[30:31], v[30:31]
	v_pk_mul_f32 v[34:35], v[92:93], v[26:27] op_sel_hi:[0,1]
	v_pk_mul_f32 v[26:27], v[34:35], v[34:35]
	v_lshlrev_b32_e32 v36, 16, v28
	v_and_b32_e32 v37, 0xffff0000, v28
	v_add_f32_e32 v0, v32, v33
	v_pk_mul_f32 v[36:37], v[92:93], v[36:37] op_sel_hi:[0,1]
	v_add_f32_e32 v0, v26, v0
	s_waitcnt lgkmcnt(0)
	v_pk_mul_f32 v[38:39], v[36:37], v[36:37]
	v_lshlrev_b32_e32 v28, 16, v29
	v_and_b32_e32 v29, 0xffff0000, v29
	v_add_f32_e32 v0, v27, v0
	v_pk_mul_f32 v[40:41], v[92:93], v[28:29] op_sel_hi:[0,1]
	v_add_f32_e32 v0, v38, v0
	v_pk_mul_f32 v[28:29], v[40:41], v[40:41]
	v_add_f32_e32 v0, v39, v0
	v_add_f32_e32 v0, v28, v0
	v_add_f32_e32 v0, v29, v0
	s_waitcnt lgkmcnt(0)
	s_nop 1
	v_add_f32_dpp v0, v0, v0 quad_perm:[1,0,3,2] row_mask:0xf bank_mask:0xf
	s_waitcnt lgkmcnt(0)
	s_nop 1
	v_add_f32_dpp v0, v0, v0 quad_perm:[2,3,0,1] row_mask:0xf bank_mask:0xf
	s_waitcnt lgkmcnt(0)
	s_nop 1
	v_add_f32_dpp v0, v0, v0 row_ror:4 row_mask:0xf bank_mask:0xf
	s_waitcnt lgkmcnt(0)
	s_nop 1
	v_add_f32_dpp v0, v0, v0 row_ror:8 row_mask:0xf bank_mask:0xf
	v_fmamk_f32 v0, v0, 0x3c2aaaab, v148
	v_mul_f32_e32 v26, 0x4b800000, v0
	v_cmp_gt_f32_e64 s[0:1], s2, v0
	s_nop 1
	v_cndmask_b32_e64 v0, v0, v26, s[0:1]
	v_rsq_f32_e32 v0, v0
	s_nop 0
	v_mul_f32_e32 v26, 0x45800000, v0
	v_cndmask_b32_e64 v0, v0, v26, s[0:1]
	v_pk_mul_f32 v[26:27], v[72:73], v[0:1] op_sel_hi:[1,0]
	v_pk_mul_f32 v[28:29], v[74:75], v[0:1] op_sel_hi:[1,0]
	v_pk_mul_f32 v[32:33], v[76:77], v[0:1] op_sel_hi:[1,0]
	v_pk_mul_f32 v[38:39], v[78:79], v[0:1] op_sel_hi:[1,0]
	v_pk_mul_f32 v[26:27], v[30:31], v[26:27]
	v_pk_mul_f32 v[28:29], v[34:35], v[28:29]
	v_pk_mul_f32 v[30:31], v[36:37], v[32:33]
	v_pk_mul_f32 v[32:33], v[40:41], v[38:39]
	ds_bpermute_b32 v40, v81, v26
	ds_bpermute_b32 v41, v81, v27
	ds_bpermute_b32 v38, v81, v28
	ds_bpermute_b32 v39, v81, v29
	ds_bpermute_b32 v36, v81, v30
	ds_bpermute_b32 v37, v81, v31
	ds_bpermute_b32 v34, v81, v32
	ds_bpermute_b32 v35, v81, v33
	v_or_b32_e32 v0, 36, v83
	s_and_saveexec_b64 s[0:1], s[40:41]
	s_cbranch_execz .LBB0_583
	v_add_u32_e32 v42, 0xffffff00, v67
	v_lshlrev_b32_e32 v43, 6, v0
	v_cndmask_b32_e64 v42, v43, v42, s[46:47]
	v_add_u32_e32 v54, 0, v42
	ds_read_b128 v[42:45], v54
	ds_read_b128 v[46:49], v54 offset:16
	ds_read_b128 v[50:53], v54 offset:32
	ds_read_b128 v[54:57], v54 offset:48
	s_waitcnt lgkmcnt(3)
	v_mov_b32_e32 v58, v43
	v_mov_b32_e32 v59, v45
	v_pk_mul_f32 v[40:41], v[58:59], v[40:41]
	v_mov_b32_e32 v43, v44
	v_cndmask_b32_e64 v41, v41, -v41, s[44:45]
	v_cndmask_b32_e64 v40, v40, -v40, s[44:45]
	v_pk_fma_f32 v[26:27], v[26:27], v[42:43], v[40:41]
	s_waitcnt lgkmcnt(2)
	v_mov_b32_e32 v40, v47
	v_mov_b32_e32 v41, v49
	v_pk_mul_f32 v[38:39], v[40:41], v[38:39]
	v_mov_b32_e32 v47, v48
	v_cndmask_b32_e64 v39, v39, -v39, s[44:45]
	v_cndmask_b32_e64 v38, v38, -v38, s[44:45]
	v_pk_fma_f32 v[28:29], v[28:29], v[46:47], v[38:39]
	s_waitcnt lgkmcnt(1)
	v_mov_b32_e32 v38, v51
	v_mov_b32_e32 v39, v53
	v_pk_mul_f32 v[36:37], v[38:39], v[36:37]
	v_mov_b32_e32 v51, v52
	v_cndmask_b32_e64 v37, v37, -v37, s[44:45]
	v_cndmask_b32_e64 v36, v36, -v36, s[44:45]
	v_pk_fma_f32 v[30:31], v[30:31], v[50:51], v[36:37]
	s_waitcnt lgkmcnt(0)
	v_mov_b32_e32 v36, v55
	v_mov_b32_e32 v37, v57
	v_pk_mul_f32 v[34:35], v[36:37], v[34:35]
	v_mov_b32_e32 v55, v56
	v_cndmask_b32_e64 v35, v35, -v35, s[44:45]
	v_cndmask_b32_e64 v34, v34, -v34, s[44:45]
	v_pk_fma_f32 v[32:33], v[32:33], v[54:55], v[34:35]

; template <int NCH, bool ROPE>
; DI void norm_rows16(int lane, size_t row0, bool is_ctx, int t0, const bf16_t* srcA, size_t ldA, int nA, const bf16_t* srcB, size_t ldB,
;                     const float* st, int st_idx, const float* gain, float inv_n, bf16_t* dst, size_t ldd, const float* tab) {
;     ...
;   for (int it = 0; it < 16; ++it) {
;     const int tk = it * 4 + tq;
;     const size_t row = row0 + tk;
;     const u32x4 u = ua[it];
;     const float pre = prea[it];
;     float f[8];
;     unpack8(u, f);
;     float ss = 0.f;
; #pragma unroll
;     for (int j = 0; j < 8; ++j) { f[j] *= pre; ss += f[j] * f[j]; }
;     ss += __shfl_xor(ss, 1); ss += __shfl_xor(ss, 2); ss += __shfl_xor(ss, 4); ss += __shfl_xor(ss, 8);
;     const float rs = rsqrtf(ss * inv_n + EPS);
; #pragma unroll
;     for (int j = 0; j < 8; ++j) f[j] *= rs * gv[j];
;     if (ROPE) {
;       float pf[8];
; #pragma unroll
;       for (int j = 0; j < 8; ++j) pf[j] = __shfl_xor(f[j], 1);
;       if (!is_ctx && sub >= 8 && sub < 12) {
;         const int pos = t0 + tk - CTXL;
;         const float* tr = (const float*)smem + ((sub < 10) ? (pos >> 6) : (pos & 63)) * 16;
; #pragma unroll
;         for (int j = 0; j < 8; ++j) {
;           const float c = tr[2 * j], sn = tr[2 * j + 1];
;           f[j] = (sub & 1) ? (pf[j] * sn + f[j] * c) : (f[j] * c - pf[j] * sn);
;         }
;       }
.LBB0_585:
	s_or_b64 exec, exec, s[0:1]
	s_nop 0
	v_lshlrev_b32_e32 v26, 16, v22
	v_and_b32_e32 v27, 0xffff0000, v22
	v_pk_mul_f32 v[26:27], v[90:91], v[26:27] op_sel_hi:[0,1]
	v_lshlrev_b32_e32 v22, 16, v23
	v_and_b32_e32 v23, 0xffff0000, v23
	v_pk_mul_f32 v[28:29], v[26:27], v[26:27]
	v_pk_mul_f32 v[30:31], v[90:91], v[22:23] op_sel_hi:[0,1]
	v_pk_mul_f32 v[22:23], v[30:31], v[30:31]
	v_lshlrev_b32_e32 v32, 16, v24
	v_and_b32_e32 v33, 0xffff0000, v24
	v_add_f32_e32 v0, v28, v29
	v_pk_mul_f32 v[32:33], v[90:91], v[32:33] op_sel_hi:[0,1]
	v_add_f32_e32 v0, v22, v0
	s_waitcnt lgkmcnt(0)
	v_pk_mul_f32 v[34:35], v[32:33], v[32:33]
	v_lshlrev_b32_e32 v24, 16, v25
	v_and_b32_e32 v25, 0xffff0000, v25
	v_add_f32_e32 v0, v23, v0
	v_pk_mul_f32 v[36:37], v[90:91], v[24:25] op_sel_hi:[0,1]
	v_add_f32_e32 v0, v34, v0
	v_pk_mul_f32 v[24:25], v[36:37], v[36:37]
	v_add_f32_e32 v0, v35, v0
	v_add_f32_e32 v0, v24, v0
	v_add_f32_e32 v0, v25, v0
	s_waitcnt lgkmcnt(0)
	s_nop 1
	v_add_f32_dpp v0, v0, v0 quad_perm:[1,0,3,2] row_mask:0xf bank_mask:0xf
	s_waitcnt lgkmcnt(0)
	s_nop 1
	v_add_f32_dpp v0, v0, v0 quad_perm:[2,3,0,1] row_mask:0xf bank_mask:0xf
	s_waitcnt lgkmcnt(0)
	s_nop 1
	v_add_f32_dpp v0, v0, v0 row_ror:4 row_mask:0xf bank_mask:0xf
	s_waitcnt lgkmcnt(0)
	s_nop 1
	v_add_f32_dpp v0, v0, v0 row_ror:8 row_mask:0xf bank_mask:0xf
	v_fmamk_f32 v0, v0, 0x3c2aaaab, v148
	v_mul_f32_e32 v22, 0x4b800000, v0
	v_cmp_gt_f32_e64 s[0:1], s2, v0
	s_nop 1
	v_cndmask_b32_e64 v0, v0, v22, s[0:1]
	v_rsq_f32_e32 v0, v0
	s_nop 0
	v_mul_f32_e32 v22, 0x45800000, v0
	v_cndmask_b32_e64 v0, v0, v22, s[0:1]
	v_pk_mul_f32 v[22:23], v[72:73], v[0:1] op_sel_hi:[1,0]
	v_pk_mul_f32 v[24:25], v[74:75], v[0:1] op_sel_hi:[1,0]
	v_pk_mul_f32 v[28:29], v[76:77], v[0:1] op_sel_hi:[1,0]
	v_pk_mul_f32 v[34:35], v[78:79], v[0:1] op_sel_hi:[1,0]
	v_pk_mul_f32 v[22:23], v[26:27], v[22:23]
	v_pk_mul_f32 v[24:25], v[30:31], v[24:25]
	v_pk_mul_f32 v[26:27], v[32:33], v[28:29]
	v_pk_mul_f32 v[28:29], v[36:37], v[34:35]
	ds_bpermute_b32 v36, v81, v22
	ds_bpermute_b32 v37, v81, v23
	ds_bpermute_b32 v34, v81, v24
	ds_bpermute_b32 v35, v81, v25
	ds_bpermute_b32 v32, v81, v26
	ds_bpermute_b32 v33, v81, v27
	ds_bpermute_b32 v30, v81, v28
	ds_bpermute_b32 v31, v81, v29
	v_or_b32_e32 v0, 40, v83
	s_and_saveexec_b64 s[0:1], s[40:41]
	s_cbranch_execz .LBB0_587
	v_add_u32_e32 v38, 0xffffff00, v67
	v_lshlrev_b32_e32 v39, 6, v0
	v_cndmask_b32_e64 v38, v39, v38, s[46:47]
	v_add_u32_e32 v50, 0, v38
	ds_read_b128 v[38:41], v50
	ds_read_b128 v[42:45], v50 offset:16
	ds_read_b128 v[46:49], v50 offset:32
	ds_read_b128 v[50:53], v50 offset:48
	s_waitcnt lgkmcnt(3)
	v_mov_b32_e32 v54, v39
	v_mov_b32_e32 v55, v41
	v_pk_mul_f32 v[36:37], v[54:55], v[36:37]
	v_mov_b32_e32 v39, v40
	v_cndmask_b32_e64 v37, v37, -v37, s[44:45]
	v_cndmask_b32_e64 v36, v36, -v36, s[44:45]
	v_pk_fma_f32 v[22:23], v[22:23], v[38:39], v[36:37]
	s_waitcnt lgkmcnt(2)
	v_mov_b32_e32 v36, v43
	v_mov_b32_e32 v37, v45
	v_pk_mul_f32 v[34:35], v[36:37], v[34:35]
	v_mov_b32_e32 v43, v44
	v_cndmask_b32_e64 v35, v35, -v35, s[44:45]
	v_cndmask_b32_e64 v34, v34, -v34, s[44:45]
	v_pk_fma_f32 v[24:25], v[24:25], v[42:43], v[34:35]
	s_waitcnt lgkmcnt(1)
	v_mov_b32_e32 v34, v47
	v_mov_b32_e32 v35, v49
	v_pk_mul_f32 v[32:33], v[34:35], v[32:33]
	v_mov_b32_e32 v47, v48
	v_cndmask_b32_e64 v33, v33, -v33, s[44:45]
	v_cndmask_b32_e64 v32, v32, -v32, s[44:45]
	v_pk_fma_f32 v[26:27], v[26:27], v[46:47], v[32:33]
	s_waitcnt lgkmcnt(0)
	v_mov_b32_e32 v32, v51
	v_mov_b32_e32 v33, v53
	v_pk_mul_f32 v[30:31], v[32:33], v[30:31]
	v_mov_b32_e32 v51, v52
	v_cndmask_b32_e64 v31, v31, -v31, s[44:45]
	v_cndmask_b32_e64 v30, v30, -v30, s[44:45]
	v_pk_fma_f32 v[28:29], v[28:29], v[50:51], v[30:31]

; template <int NCH, bool ROPE>
; DI void norm_rows16(int lane, size_t row0, bool is_ctx, int t0, const bf16_t* srcA, size_t ldA, int nA, const bf16_t* srcB, size_t ldB,
;                     const float* st, int st_idx, const float* gain, float inv_n, bf16_t* dst, size_t ldd, const float* tab) {
;     ...
;   for (int it = 0; it < 16; ++it) {
;     const int tk = it * 4 + tq;
;     const size_t row = row0 + tk;
;     const u32x4 u = ua[it];
;     const float pre = prea[it];
;     float f[8];
;     unpack8(u, f);
;     float ss = 0.f;
; #pragma unroll
;     for (int j = 0; j < 8; ++j) { f[j] *= pre; ss += f[j] * f[j]; }
;     ss += __shfl_xor(ss, 1); ss += __shfl_xor(ss, 2); ss += __shfl_xor(ss, 4); ss += __shfl_xor(ss, 8);
;     const float rs = rsqrtf(ss * inv_n + EPS);
; #pragma unroll
;     for (int j = 0; j < 8; ++j) f[j] *= rs * gv[j];
;     if (ROPE) {
;       float pf[8];
; #pragma unroll
;       for (int j = 0; j < 8; ++j) pf[j] = __shfl_xor(f[j], 1);
;       if (!is_ctx && sub >= 8 && sub < 12) {
;         const int pos = t0 + tk - CTXL;
;         const float* tr = (const float*)smem + ((sub < 10) ? (pos >> 6) : (pos & 63)) * 16;
; #pragma unroll
;         for (int j = 0; j < 8; ++j) {
;           const float c = tr[2 * j], sn = tr[2 * j + 1];
;           f[j] = (sub & 1) ? (pf[j] * sn + f[j] * c) : (f[j] * c - pf[j] * sn);
;         }
;       }
.LBB0_589:
	s_or_b64 exec, exec, s[0:1]
	s_nop 0
	v_lshlrev_b32_e32 v22, 16, v18
	v_and_b32_e32 v23, 0xffff0000, v18
	v_pk_mul_f32 v[22:23], v[88:89], v[22:23] op_sel_hi:[0,1]
	v_lshlrev_b32_e32 v18, 16, v19
	v_and_b32_e32 v19, 0xffff0000, v19
	v_pk_mul_f32 v[24:25], v[22:23], v[22:23]
	v_pk_mul_f32 v[26:27], v[88:89], v[18:19] op_sel_hi:[0,1]
	v_pk_mul_f32 v[18:19], v[26:27], v[26:27]
	v_lshlrev_b32_e32 v28, 16, v20
	v_and_b32_e32 v29, 0xffff0000, v20
	v_add_f32_e32 v0, v24, v25
	v_pk_mul_f32 v[28:29], v[88:89], v[28:29] op_sel_hi:[0,1]
	v_add_f32_e32 v0, v18, v0
	s_waitcnt lgkmcnt(0)
	v_pk_mul_f32 v[30:31], v[28:29], v[28:29]
	v_lshlrev_b32_e32 v20, 16, v21
	v_and_b32_e32 v21, 0xffff0000, v21
	v_add_f32_e32 v0, v19, v0
	v_pk_mul_f32 v[32:33], v[88:89], v[20:21] op_sel_hi:[0,1]
	v_add_f32_e32 v0, v30, v0
	v_pk_mul_f32 v[20:21], v[32:33], v[32:33]
	v_add_f32_e32 v0, v31, v0
	v_add_f32_e32 v0, v20, v0
	v_add_f32_e32 v0, v21, v0
	s_waitcnt lgkmcnt(0)
	s_nop 1
	v_add_f32_dpp v0, v0, v0 quad_perm:[1,0,3,2] row_mask:0xf bank_mask:0xf
	s_waitcnt lgkmcnt(0)
	s_nop 1
	v_add_f32_dpp v0, v0, v0 quad_perm:[2,3,0,1] row_mask:0xf bank_mask:0xf
	s_waitcnt lgkmcnt(0)
	s_nop 1
	v_add_f32_dpp v0, v0, v0 row_ror:4 row_mask:0xf bank_mask:0xf
	s_waitcnt lgkmcnt(0)
	s_nop 1
	v_add_f32_dpp v0, v0, v0 row_ror:8 row_mask:0xf bank_mask:0xf
	v_fmamk_f32 v0, v0, 0x3c2aaaab, v148
	v_mul_f32_e32 v18, 0x4b800000, v0
	v_cmp_gt_f32_e64 s[0:1], s2, v0
	s_nop 1
	v_cndmask_b32_e64 v0, v0, v18, s[0:1]
	v_rsq_f32_e32 v0, v0
	s_nop 0
	v_mul_f32_e32 v18, 0x45800000, v0
	v_cndmask_b32_e64 v0, v0, v18, s[0:1]
	v_pk_mul_f32 v[18:19], v[72:73], v[0:1] op_sel_hi:[1,0]
	v_pk_mul_f32 v[20:21], v[74:75], v[0:1] op_sel_hi:[1,0]
	v_pk_mul_f32 v[24:25], v[76:77], v[0:1] op_sel_hi:[1,0]
	v_pk_mul_f32 v[30:31], v[78:79], v[0:1] op_sel_hi:[1,0]
	v_pk_mul_f32 v[18:19], v[22:23], v[18:19]
	v_pk_mul_f32 v[20:21], v[26:27], v[20:21]
	v_pk_mul_f32 v[22:23], v[28:29], v[24:25]
	v_pk_mul_f32 v[24:25], v[32:33], v[30:31]
	ds_bpermute_b32 v32, v81, v18
	ds_bpermute_b32 v33, v81, v19
	ds_bpermute_b32 v30, v81, v20
	ds_bpermute_b32 v31, v81, v21
	ds_bpermute_b32 v28, v81, v22
	ds_bpermute_b32 v29, v81, v23
	ds_bpermute_b32 v26, v81, v24
	ds_bpermute_b32 v27, v81, v25
	v_or_b32_e32 v0, 44, v83
	s_and_saveexec_b64 s[0:1], s[40:41]
	s_cbranch_execz .LBB0_591
	v_add_u32_e32 v34, 0xffffff00, v67
	v_lshlrev_b32_e32 v35, 6, v0
	v_cndmask_b32_e64 v34, v35, v34, s[46:47]
	v_add_u32_e32 v46, 0, v34
	ds_read_b128 v[34:37], v46
	ds_read_b128 v[38:41], v46 offset:16
	ds_read_b128 v[42:45], v46 offset:32
	ds_read_b128 v[46:49], v46 offset:48
	s_waitcnt lgkmcnt(3)
	v_mov_b32_e32 v50, v35
	v_mov_b32_e32 v51, v37
	v_pk_mul_f32 v[32:33], v[50:51], v[32:33]
	v_mov_b32_e32 v35, v36
	v_cndmask_b32_e64 v33, v33, -v33, s[44:45]
	v_cndmask_b32_e64 v32, v32, -v32, s[44:45]
	v_pk_fma_f32 v[18:19], v[18:19], v[34:35], v[32:33]
	s_waitcnt lgkmcnt(2)
	v_mov_b32_e32 v32, v39
	v_mov_b32_e32 v33, v41
	v_pk_mul_f32 v[30:31], v[32:33], v[30:31]
	v_mov_b32_e32 v39, v40
	v_cndmask_b32_e64 v31, v31, -v31, s[44:45]
	v_cndmask_b32_e64 v30, v30, -v30, s[44:45]
	v_pk_fma_f32 v[20:21], v[20:21], v[38:39], v[30:31]
	s_waitcnt lgkmcnt(1)
	v_mov_b32_e32 v30, v43
	v_mov_b32_e32 v31, v45
	v_pk_mul_f32 v[28:29], v[30:31], v[28:29]
	v_mov_b32_e32 v43, v44
	v_cndmask_b32_e64 v29, v29, -v29, s[44:45]
	v_cndmask_b32_e64 v28, v28, -v28, s[44:45]
	v_pk_fma_f32 v[22:23], v[22:23], v[42:43], v[28:29]
	s_waitcnt lgkmcnt(0)
	v_mov_b32_e32 v28, v47
	v_mov_b32_e32 v29, v49
	v_pk_mul_f32 v[26:27], v[28:29], v[26:27]
	v_mov_b32_e32 v47, v48
	v_cndmask_b32_e64 v27, v27, -v27, s[44:45]
	v_cndmask_b32_e64 v26, v26, -v26, s[44:45]
	v_pk_fma_f32 v[24:25], v[24:25], v[46:47], v[26:27]

; template <int NCH, bool ROPE>
; DI void norm_rows16(int lane, size_t row0, bool is_ctx, int t0, const bf16_t* srcA, size_t ldA, int nA, const bf16_t* srcB, size_t ldB,
;                     const float* st, int st_idx, const float* gain, float inv_n, bf16_t* dst, size_t ldd, const float* tab) {
;     ...
;   for (int it = 0; it < 16; ++it) {
;     const int tk = it * 4 + tq;
;     const size_t row = row0 + tk;
;     const u32x4 u = ua[it];
;     const float pre = prea[it];
;     float f[8];
;     unpack8(u, f);
;     float ss = 0.f;
; #pragma unroll
;     for (int j = 0; j < 8; ++j) { f[j] *= pre; ss += f[j] * f[j]; }
;     ss += __shfl_xor(ss, 1); ss += __shfl_xor(ss, 2); ss += __shfl_xor(ss, 4); ss += __shfl_xor(ss, 8);
;     const float rs = rsqrtf(ss * inv_n + EPS);
; #pragma unroll
;     for (int j = 0; j < 8; ++j) f[j] *= rs * gv[j];
;     if (ROPE) {
;       float pf[8];
; #pragma unroll
;       for (int j = 0; j < 8; ++j) pf[j] = __shfl_xor(f[j], 1);
;       if (!is_ctx && sub >= 8 && sub < 12) {
;         const int pos = t0 + tk - CTXL;
;         const float* tr = (const float*)smem + ((sub < 10) ? (pos >> 6) : (pos & 63)) * 16;
; #pragma unroll
;         for (int j = 0; j < 8; ++j) {
;           const float c = tr[2 * j], sn = tr[2 * j + 1];
;           f[j] = (sub & 1) ? (pf[j] * sn + f[j] * c) : (f[j] * c - pf[j] * sn);
;         }
;       }
.LBB0_593:
	s_or_b64 exec, exec, s[0:1]
	s_nop 0
	v_lshlrev_b32_e32 v18, 16, v14
	v_and_b32_e32 v19, 0xffff0000, v14
	v_pk_mul_f32 v[18:19], v[86:87], v[18:19] op_sel_hi:[0,1]
	v_lshlrev_b32_e32 v14, 16, v15
	v_and_b32_e32 v15, 0xffff0000, v15
	v_pk_mul_f32 v[20:21], v[18:19], v[18:19]
	v_pk_mul_f32 v[22:23], v[86:87], v[14:15] op_sel_hi:[0,1]
	v_pk_mul_f32 v[14:15], v[22:23], v[22:23]
	v_lshlrev_b32_e32 v24, 16, v16
	v_and_b32_e32 v25, 0xffff0000, v16
	v_add_f32_e32 v0, v20, v21
	v_pk_mul_f32 v[24:25], v[86:87], v[24:25] op_sel_hi:[0,1]
	v_add_f32_e32 v0, v14, v0
	s_waitcnt lgkmcnt(0)
	v_pk_mul_f32 v[26:27], v[24:25], v[24:25]
	v_lshlrev_b32_e32 v16, 16, v17
	v_and_b32_e32 v17, 0xffff0000, v17
	v_add_f32_e32 v0, v15, v0
	v_pk_mul_f32 v[28:29], v[86:87], v[16:17] op_sel_hi:[0,1]
	v_add_f32_e32 v0, v26, v0
	v_pk_mul_f32 v[16:17], v[28:29], v[28:29]
	v_add_f32_e32 v0, v27, v0
	v_add_f32_e32 v0, v16, v0
	v_add_f32_e32 v0, v17, v0
	s_waitcnt lgkmcnt(0)
	s_nop 1
	v_add_f32_dpp v0, v0, v0 quad_perm:[1,0,3,2] row_mask:0xf bank_mask:0xf
	s_waitcnt lgkmcnt(0)
	s_nop 1
	v_add_f32_dpp v0, v0, v0 quad_perm:[2,3,0,1] row_mask:0xf bank_mask:0xf
	s_waitcnt lgkmcnt(0)
	s_nop 1
	v_add_f32_dpp v0, v0, v0 row_ror:4 row_mask:0xf bank_mask:0xf
	s_waitcnt lgkmcnt(0)
	s_nop 1
	v_add_f32_dpp v0, v0, v0 row_ror:8 row_mask:0xf bank_mask:0xf
	v_fmamk_f32 v0, v0, 0x3c2aaaab, v148
	v_mul_f32_e32 v14, 0x4b800000, v0
	v_cmp_gt_f32_e64 s[0:1], s2, v0
	s_nop 1
	v_cndmask_b32_e64 v0, v0, v14, s[0:1]
	v_rsq_f32_e32 v0, v0
	s_nop 0
	v_mul_f32_e32 v14, 0x45800000, v0
	v_cndmask_b32_e64 v0, v0, v14, s[0:1]
	v_pk_mul_f32 v[14:15], v[72:73], v[0:1] op_sel_hi:[1,0]
	v_pk_mul_f32 v[16:17], v[74:75], v[0:1] op_sel_hi:[1,0]
	v_pk_mul_f32 v[20:21], v[76:77], v[0:1] op_sel_hi:[1,0]
	v_pk_mul_f32 v[26:27], v[78:79], v[0:1] op_sel_hi:[1,0]
	v_pk_mul_f32 v[14:15], v[18:19], v[14:15]
	v_pk_mul_f32 v[16:17], v[22:23], v[16:17]
	v_pk_mul_f32 v[18:19], v[24:25], v[20:21]
	v_pk_mul_f32 v[20:21], v[28:29], v[26:27]
	ds_bpermute_b32 v28, v81, v14
	ds_bpermute_b32 v29, v81, v15
	ds_bpermute_b32 v26, v81, v16
	ds_bpermute_b32 v27, v81, v17
	ds_bpermute_b32 v24, v81, v18
	ds_bpermute_b32 v25, v81, v19
	ds_bpermute_b32 v22, v81, v20
	ds_bpermute_b32 v23, v81, v21
	v_or_b32_e32 v0, 48, v83
	s_and_saveexec_b64 s[0:1], s[40:41]
	s_cbranch_execz .LBB0_595
	v_add_u32_e32 v30, 0xffffff00, v67
	v_lshlrev_b32_e32 v31, 6, v0
	v_cndmask_b32_e64 v30, v31, v30, s[46:47]
	v_add_u32_e32 v42, 0, v30
	ds_read_b128 v[30:33], v42
	ds_read_b128 v[34:37], v42 offset:16
	ds_read_b128 v[38:41], v42 offset:32
	ds_read_b128 v[42:45], v42 offset:48
	s_waitcnt lgkmcnt(3)
	v_mov_b32_e32 v46, v31
	v_mov_b32_e32 v47, v33
	v_pk_mul_f32 v[28:29], v[46:47], v[28:29]
	v_mov_b32_e32 v31, v32
	v_cndmask_b32_e64 v29, v29, -v29, s[44:45]
	v_cndmask_b32_e64 v28, v28, -v28, s[44:45]
	v_pk_fma_f32 v[14:15], v[14:15], v[30:31], v[28:29]
	s_waitcnt lgkmcnt(2)
	v_mov_b32_e32 v28, v35
	v_mov_b32_e32 v29, v37
	v_pk_mul_f32 v[26:27], v[28:29], v[26:27]
	v_mov_b32_e32 v35, v36
	v_cndmask_b32_e64 v27, v27, -v27, s[44:45]
	v_cndmask_b32_e64 v26, v26, -v26, s[44:45]
	v_pk_fma_f32 v[16:17], v[16:17], v[34:35], v[26:27]
	s_waitcnt lgkmcnt(1)
	v_mov_b32_e32 v26, v39
	v_mov_b32_e32 v27, v41
	v_pk_mul_f32 v[24:25], v[26:27], v[24:25]
	v_mov_b32_e32 v39, v40
	v_cndmask_b32_e64 v25, v25, -v25, s[44:45]
	v_cndmask_b32_e64 v24, v24, -v24, s[44:45]
	v_pk_fma_f32 v[18:19], v[18:19], v[38:39], v[24:25]
	s_waitcnt lgkmcnt(0)
	v_mov_b32_e32 v24, v43
	v_mov_b32_e32 v25, v45
	v_pk_mul_f32 v[22:23], v[24:25], v[22:23]
	v_mov_b32_e32 v43, v44
	v_cndmask_b32_e64 v23, v23, -v23, s[44:45]
	v_cndmask_b32_e64 v22, v22, -v22, s[44:45]
	v_pk_fma_f32 v[20:21], v[20:21], v[42:43], v[22:23]

; template <int NCH, bool ROPE>
; DI void norm_rows16(int lane, size_t row0, bool is_ctx, int t0, const bf16_t* srcA, size_t ldA, int nA, const bf16_t* srcB, size_t ldB,
;                     const float* st, int st_idx, const float* gain, float inv_n, bf16_t* dst, size_t ldd, const float* tab) {
;     ...
;   for (int it = 0; it < 16; ++it) {
;     const int tk = it * 4 + tq;
;     const size_t row = row0 + tk;
;     const u32x4 u = ua[it];
;     const float pre = prea[it];
;     float f[8];
;     unpack8(u, f);
;     float ss = 0.f;
; #pragma unroll
;     for (int j = 0; j < 8; ++j) { f[j] *= pre; ss += f[j] * f[j]; }
;     ss += __shfl_xor(ss, 1); ss += __shfl_xor(ss, 2); ss += __shfl_xor(ss, 4); ss += __shfl_xor(ss, 8);
;     const float rs = rsqrtf(ss * inv_n + EPS);
; #pragma unroll
;     for (int j = 0; j < 8; ++j) f[j] *= rs * gv[j];
;     if (ROPE) {
;       float pf[8];
; #pragma unroll
;       for (int j = 0; j < 8; ++j) pf[j] = __shfl_xor(f[j], 1);
;       if (!is_ctx && sub >= 8 && sub < 12) {
;         const int pos = t0 + tk - CTXL;
;         const float* tr = (const float*)smem + ((sub < 10) ? (pos >> 6) : (pos & 63)) * 16;
; #pragma unroll
;         for (int j = 0; j < 8; ++j) {
;           const float c = tr[2 * j], sn = tr[2 * j + 1];
;           f[j] = (sub & 1) ? (pf[j] * sn + f[j] * c) : (f[j] * c - pf[j] * sn);
;         }
;       }
.LBB0_597:
	s_or_b64 exec, exec, s[0:1]
	s_nop 0
	v_lshlrev_b32_e32 v14, 16, v10
	v_and_b32_e32 v15, 0xffff0000, v10
	v_pk_mul_f32 v[14:15], v[84:85], v[14:15] op_sel_hi:[0,1]
	v_lshlrev_b32_e32 v10, 16, v11
	v_and_b32_e32 v11, 0xffff0000, v11
	v_pk_mul_f32 v[16:17], v[14:15], v[14:15]
	v_pk_mul_f32 v[18:19], v[84:85], v[10:11] op_sel_hi:[0,1]
	v_pk_mul_f32 v[10:11], v[18:19], v[18:19]
	v_lshlrev_b32_e32 v20, 16, v12
	v_and_b32_e32 v21, 0xffff0000, v12
	v_add_f32_e32 v0, v16, v17
	v_pk_mul_f32 v[20:21], v[84:85], v[20:21] op_sel_hi:[0,1]
	v_add_f32_e32 v0, v10, v0
	s_waitcnt lgkmcnt(0)
	v_pk_mul_f32 v[22:23], v[20:21], v[20:21]
	v_lshlrev_b32_e32 v12, 16, v13
	v_and_b32_e32 v13, 0xffff0000, v13
	v_add_f32_e32 v0, v11, v0
	v_pk_mul_f32 v[24:25], v[84:85], v[12:13] op_sel_hi:[0,1]
	v_add_f32_e32 v0, v22, v0
	v_pk_mul_f32 v[12:13], v[24:25], v[24:25]
	v_add_f32_e32 v0, v23, v0
	v_add_f32_e32 v0, v12, v0
	v_add_f32_e32 v0, v13, v0
	s_waitcnt lgkmcnt(0)
	s_nop 1
	v_add_f32_dpp v0, v0, v0 quad_perm:[1,0,3,2] row_mask:0xf bank_mask:0xf
	s_waitcnt lgkmcnt(0)
	s_nop 1
	v_add_f32_dpp v0, v0, v0 quad_perm:[2,3,0,1] row_mask:0xf bank_mask:0xf
	s_waitcnt lgkmcnt(0)
	s_nop 1
	v_add_f32_dpp v0, v0, v0 row_ror:4 row_mask:0xf bank_mask:0xf
	s_waitcnt lgkmcnt(0)
	s_nop 1
	v_add_f32_dpp v0, v0, v0 row_ror:8 row_mask:0xf bank_mask:0xf
	v_fmamk_f32 v0, v0, 0x3c2aaaab, v148
	v_mul_f32_e32 v10, 0x4b800000, v0
	v_cmp_gt_f32_e64 s[0:1], s2, v0
	s_nop 1
	v_cndmask_b32_e64 v0, v0, v10, s[0:1]
	v_rsq_f32_e32 v0, v0
	s_nop 0
	v_mul_f32_e32 v10, 0x45800000, v0
	v_cndmask_b32_e64 v0, v0, v10, s[0:1]
	v_pk_mul_f32 v[10:11], v[72:73], v[0:1] op_sel_hi:[1,0]
	v_pk_mul_f32 v[12:13], v[74:75], v[0:1] op_sel_hi:[1,0]
	v_pk_mul_f32 v[16:17], v[76:77], v[0:1] op_sel_hi:[1,0]
	v_pk_mul_f32 v[22:23], v[78:79], v[0:1] op_sel_hi:[1,0]
	v_pk_mul_f32 v[10:11], v[14:15], v[10:11]
	v_pk_mul_f32 v[12:13], v[18:19], v[12:13]
	v_pk_mul_f32 v[14:15], v[20:21], v[16:17]
	v_pk_mul_f32 v[16:17], v[24:25], v[22:23]
	ds_bpermute_b32 v24, v81, v10
	ds_bpermute_b32 v25, v81, v11
	ds_bpermute_b32 v22, v81, v12
	ds_bpermute_b32 v23, v81, v13
	ds_bpermute_b32 v20, v81, v14
	ds_bpermute_b32 v21, v81, v15
	ds_bpermute_b32 v18, v81, v16
	ds_bpermute_b32 v19, v81, v17
	v_or_b32_e32 v0, 52, v83
	s_and_saveexec_b64 s[0:1], s[40:41]
	s_cbranch_execz .LBB0_599
	v_add_u32_e32 v26, 0xffffff00, v67
	v_lshlrev_b32_e32 v27, 6, v0
	v_cndmask_b32_e64 v26, v27, v26, s[46:47]
	v_add_u32_e32 v38, 0, v26
	ds_read_b128 v[26:29], v38
	ds_read_b128 v[30:33], v38 offset:16
	ds_read_b128 v[34:37], v38 offset:32
	ds_read_b128 v[38:41], v38 offset:48
	s_waitcnt lgkmcnt(3)
	v_mov_b32_e32 v42, v27
	v_mov_b32_e32 v43, v29
	v_pk_mul_f32 v[24:25], v[42:43], v[24:25]
	v_mov_b32_e32 v27, v28
	v_cndmask_b32_e64 v25, v25, -v25, s[44:45]
	v_cndmask_b32_e64 v24, v24, -v24, s[44:45]
	v_pk_fma_f32 v[10:11], v[10:11], v[26:27], v[24:25]
	s_waitcnt lgkmcnt(2)
	v_mov_b32_e32 v24, v31
	v_mov_b32_e32 v25, v33
	v_pk_mul_f32 v[22:23], v[24:25], v[22:23]
	v_mov_b32_e32 v31, v32
	v_cndmask_b32_e64 v23, v23, -v23, s[44:45]
	v_cndmask_b32_e64 v22, v22, -v22, s[44:45]
	v_pk_fma_f32 v[12:13], v[12:13], v[30:31], v[22:23]
	s_waitcnt lgkmcnt(1)
	v_mov_b32_e32 v22, v35
	v_mov_b32_e32 v23, v37
	v_pk_mul_f32 v[20:21], v[22:23], v[20:21]
	v_mov_b32_e32 v35, v36
	v_cndmask_b32_e64 v21, v21, -v21, s[44:45]
	v_cndmask_b32_e64 v20, v20, -v20, s[44:45]
	v_pk_fma_f32 v[14:15], v[14:15], v[34:35], v[20:21]
	s_waitcnt lgkmcnt(0)
	v_mov_b32_e32 v20, v39
	v_mov_b32_e32 v21, v41
	v_pk_mul_f32 v[18:19], v[20:21], v[18:19]
	v_mov_b32_e32 v39, v40
	v_cndmask_b32_e64 v19, v19, -v19, s[44:45]
	v_cndmask_b32_e64 v18, v18, -v18, s[44:45]
	v_pk_fma_f32 v[16:17], v[16:17], v[38:39], v[18:19]

; template <int NCH, bool ROPE>
; DI void norm_rows16(int lane, size_t row0, bool is_ctx, int t0, const bf16_t* srcA, size_t ldA, int nA, const bf16_t* srcB, size_t ldB,
;                     const float* st, int st_idx, const float* gain, float inv_n, bf16_t* dst, size_t ldd, const float* tab) {
;     ...
;   for (int it = 0; it < 16; ++it) {
;     const int tk = it * 4 + tq;
;     const size_t row = row0 + tk;
;     const u32x4 u = ua[it];
;     const float pre = prea[it];
;     float f[8];
;     unpack8(u, f);
;     float ss = 0.f;
; #pragma unroll
;     for (int j = 0; j < 8; ++j) { f[j] *= pre; ss += f[j] * f[j]; }
;     ss += __shfl_xor(ss, 1); ss += __shfl_xor(ss, 2); ss += __shfl_xor(ss, 4); ss += __shfl_xor(ss, 8);
;     const float rs = rsqrtf(ss * inv_n + EPS);
; #pragma unroll
;     for (int j = 0; j < 8; ++j) f[j] *= rs * gv[j];
;     if (ROPE) {
;       float pf[8];
; #pragma unroll
;       for (int j = 0; j < 8; ++j) pf[j] = __shfl_xor(f[j], 1);
;       if (!is_ctx && sub >= 8 && sub < 12) {
;         const int pos = t0 + tk - CTXL;
;         const float* tr = (const float*)smem + ((sub < 10) ? (pos >> 6) : (pos & 63)) * 16;
; #pragma unroll
;         for (int j = 0; j < 8; ++j) {
;           const float c = tr[2 * j], sn = tr[2 * j + 1];
;           f[j] = (sub & 1) ? (pf[j] * sn + f[j] * c) : (f[j] * c - pf[j] * sn);
;         }
;       }
.LBB0_601:
	s_or_b64 exec, exec, s[0:1]
	s_nop 0
	v_lshlrev_b32_e32 v10, 16, v6
	v_and_b32_e32 v11, 0xffff0000, v6
	v_pk_mul_f32 v[10:11], v[82:83], v[10:11] op_sel_hi:[0,1]
	v_lshlrev_b32_e32 v6, 16, v7
	v_and_b32_e32 v7, 0xffff0000, v7
	v_pk_mul_f32 v[12:13], v[10:11], v[10:11]
	v_pk_mul_f32 v[14:15], v[82:83], v[6:7] op_sel_hi:[0,1]
	v_pk_mul_f32 v[6:7], v[14:15], v[14:15]
	v_lshlrev_b32_e32 v16, 16, v8
	v_and_b32_e32 v17, 0xffff0000, v8
	v_add_f32_e32 v0, v12, v13
	v_pk_mul_f32 v[16:17], v[82:83], v[16:17] op_sel_hi:[0,1]
	v_add_f32_e32 v0, v6, v0
	s_waitcnt lgkmcnt(0)
	v_pk_mul_f32 v[18:19], v[16:17], v[16:17]
	v_lshlrev_b32_e32 v8, 16, v9
	v_and_b32_e32 v9, 0xffff0000, v9
	v_add_f32_e32 v0, v7, v0
	v_pk_mul_f32 v[20:21], v[82:83], v[8:9] op_sel_hi:[0,1]
	v_add_f32_e32 v0, v18, v0
	v_pk_mul_f32 v[8:9], v[20:21], v[20:21]
	v_add_f32_e32 v0, v19, v0
	v_add_f32_e32 v0, v8, v0
	v_add_f32_e32 v0, v9, v0
	s_waitcnt lgkmcnt(0)
	s_nop 1
	v_add_f32_dpp v0, v0, v0 quad_perm:[1,0,3,2] row_mask:0xf bank_mask:0xf
	s_waitcnt lgkmcnt(0)
	s_nop 1
	v_add_f32_dpp v0, v0, v0 quad_perm:[2,3,0,1] row_mask:0xf bank_mask:0xf
	s_waitcnt lgkmcnt(0)
	s_nop 1
	v_add_f32_dpp v0, v0, v0 row_ror:4 row_mask:0xf bank_mask:0xf
	s_waitcnt lgkmcnt(0)
	s_nop 1
	v_add_f32_dpp v0, v0, v0 row_ror:8 row_mask:0xf bank_mask:0xf
	v_fmamk_f32 v0, v0, 0x3c2aaaab, v148
	v_mul_f32_e32 v6, 0x4b800000, v0
	v_cmp_gt_f32_e64 s[0:1], s2, v0
	s_nop 1
	v_cndmask_b32_e64 v0, v0, v6, s[0:1]
	v_rsq_f32_e32 v0, v0
	s_nop 0
	v_mul_f32_e32 v6, 0x45800000, v0
	v_cndmask_b32_e64 v0, v0, v6, s[0:1]
	v_pk_mul_f32 v[6:7], v[72:73], v[0:1] op_sel_hi:[1,0]
	v_pk_mul_f32 v[8:9], v[74:75], v[0:1] op_sel_hi:[1,0]
	v_pk_mul_f32 v[12:13], v[76:77], v[0:1] op_sel_hi:[1,0]
	v_pk_mul_f32 v[18:19], v[78:79], v[0:1] op_sel_hi:[1,0]
	v_pk_mul_f32 v[6:7], v[10:11], v[6:7]
	v_pk_mul_f32 v[8:9], v[14:15], v[8:9]
	v_pk_mul_f32 v[10:11], v[16:17], v[12:13]
	v_pk_mul_f32 v[12:13], v[20:21], v[18:19]
	ds_bpermute_b32 v20, v81, v6
	ds_bpermute_b32 v21, v81, v7
	ds_bpermute_b32 v18, v81, v8
	ds_bpermute_b32 v19, v81, v9
	ds_bpermute_b32 v16, v81, v10
	ds_bpermute_b32 v17, v81, v11
	ds_bpermute_b32 v14, v81, v12
	ds_bpermute_b32 v15, v81, v13
	v_or_b32_e32 v0, 56, v83
	s_and_saveexec_b64 s[0:1], s[40:41]
	s_cbranch_execz .LBB0_603
	v_add_u32_e32 v22, 0xffffff00, v67
	v_lshlrev_b32_e32 v23, 6, v0
	v_cndmask_b32_e64 v22, v23, v22, s[46:47]
	v_add_u32_e32 v34, 0, v22
	ds_read_b128 v[22:25], v34
	ds_read_b128 v[26:29], v34 offset:16
	ds_read_b128 v[30:33], v34 offset:32
	ds_read_b128 v[34:37], v34 offset:48
	s_waitcnt lgkmcnt(3)
	v_mov_b32_e32 v38, v23
	v_mov_b32_e32 v39, v25
	v_pk_mul_f32 v[20:21], v[38:39], v[20:21]
	v_mov_b32_e32 v23, v24
	v_cndmask_b32_e64 v21, v21, -v21, s[44:45]
	v_cndmask_b32_e64 v20, v20, -v20, s[44:45]
	v_pk_fma_f32 v[6:7], v[6:7], v[22:23], v[20:21]
	s_waitcnt lgkmcnt(2)
	v_mov_b32_e32 v20, v27
	v_mov_b32_e32 v21, v29
	v_pk_mul_f32 v[18:19], v[20:21], v[18:19]
	v_mov_b32_e32 v27, v28
	v_cndmask_b32_e64 v19, v19, -v19, s[44:45]
	v_cndmask_b32_e64 v18, v18, -v18, s[44:45]
	v_pk_fma_f32 v[8:9], v[8:9], v[26:27], v[18:19]
	s_waitcnt lgkmcnt(1)
	v_mov_b32_e32 v18, v31
	v_mov_b32_e32 v19, v33
	v_pk_mul_f32 v[16:17], v[18:19], v[16:17]
	v_mov_b32_e32 v31, v32
	v_cndmask_b32_e64 v17, v17, -v17, s[44:45]
	v_cndmask_b32_e64 v16, v16, -v16, s[44:45]
	v_pk_fma_f32 v[10:11], v[10:11], v[30:31], v[16:17]
	s_waitcnt lgkmcnt(0)
	v_mov_b32_e32 v16, v35
	v_mov_b32_e32 v17, v37
	v_pk_mul_f32 v[14:15], v[16:17], v[14:15]
	v_mov_b32_e32 v35, v36
	v_cndmask_b32_e64 v15, v15, -v15, s[44:45]
	v_cndmask_b32_e64 v14, v14, -v14, s[44:45]
	v_pk_fma_f32 v[12:13], v[12:13], v[34:35], v[14:15]

; template <int NCH, bool ROPE>
; DI void norm_rows16(int lane, size_t row0, bool is_ctx, int t0, const bf16_t* srcA, size_t ldA, int nA, const bf16_t* srcB, size_t ldB,
;                     const float* st, int st_idx, const float* gain, float inv_n, bf16_t* dst, size_t ldd, const float* tab) {
;     ...
;   for (int it = 0; it < 16; ++it) {
;     const int tk = it * 4 + tq;
;     const size_t row = row0 + tk;
;     const u32x4 u = ua[it];
;     const float pre = prea[it];
;     float f[8];
;     unpack8(u, f);
;     float ss = 0.f;
; #pragma unroll
;     for (int j = 0; j < 8; ++j) { f[j] *= pre; ss += f[j] * f[j]; }
;     ss += __shfl_xor(ss, 1); ss += __shfl_xor(ss, 2); ss += __shfl_xor(ss, 4); ss += __shfl_xor(ss, 8);
;     const float rs = rsqrtf(ss * inv_n + EPS);
; #pragma unroll
;     for (int j = 0; j < 8; ++j) f[j] *= rs * gv[j];
;     if (ROPE) {
;       float pf[8];
; #pragma unroll
;       for (int j = 0; j < 8; ++j) pf[j] = __shfl_xor(f[j], 1);
;       if (!is_ctx && sub >= 8 && sub < 12) {
;         const int pos = t0 + tk - CTXL;
;         const float* tr = (const float*)smem + ((sub < 10) ? (pos >> 6) : (pos & 63)) * 16;
; #pragma unroll
;         for (int j = 0; j < 8; ++j) {
;           const float c = tr[2 * j], sn = tr[2 * j + 1];
;           f[j] = (sub & 1) ? (pf[j] * sn + f[j] * c) : (f[j] * c - pf[j] * sn);
;         }
;       }
.LBB0_605:
	s_or_b64 exec, exec, s[0:1]
	s_nop 0
	v_lshlrev_b32_e32 v6, 16, v2
	v_and_b32_e32 v7, 0xffff0000, v2
	v_pk_mul_f32 v[6:7], v[80:81], v[6:7] op_sel_hi:[0,1]
	v_lshlrev_b32_e32 v2, 16, v3
	v_and_b32_e32 v3, 0xffff0000, v3
	v_pk_mul_f32 v[8:9], v[6:7], v[6:7]
	v_pk_mul_f32 v[10:11], v[80:81], v[2:3] op_sel_hi:[0,1]
	v_pk_mul_f32 v[2:3], v[10:11], v[10:11]
	v_lshlrev_b32_e32 v12, 16, v4
	v_and_b32_e32 v13, 0xffff0000, v4
	v_add_f32_e32 v0, v8, v9
	v_pk_mul_f32 v[12:13], v[80:81], v[12:13] op_sel_hi:[0,1]
	v_add_f32_e32 v0, v2, v0
	s_waitcnt lgkmcnt(0)
	v_pk_mul_f32 v[14:15], v[12:13], v[12:13]
	v_lshlrev_b32_e32 v4, 16, v5
	v_and_b32_e32 v5, 0xffff0000, v5
	v_add_f32_e32 v0, v3, v0
	v_pk_mul_f32 v[16:17], v[80:81], v[4:5] op_sel_hi:[0,1]
	v_add_f32_e32 v0, v14, v0
	v_pk_mul_f32 v[4:5], v[16:17], v[16:17]
	v_add_f32_e32 v0, v15, v0
	v_add_f32_e32 v0, v4, v0
	v_add_f32_e32 v0, v5, v0
	s_waitcnt lgkmcnt(0)
	s_nop 1
	v_add_f32_dpp v0, v0, v0 quad_perm:[1,0,3,2] row_mask:0xf bank_mask:0xf
	s_waitcnt lgkmcnt(0)
	s_nop 1
	v_add_f32_dpp v0, v0, v0 quad_perm:[2,3,0,1] row_mask:0xf bank_mask:0xf
	s_waitcnt lgkmcnt(0)
	s_nop 1
	v_add_f32_dpp v0, v0, v0 row_ror:4 row_mask:0xf bank_mask:0xf
	s_waitcnt lgkmcnt(0)
	s_nop 1
	v_add_f32_dpp v0, v0, v0 row_ror:8 row_mask:0xf bank_mask:0xf
	v_fmamk_f32 v0, v0, 0x3c2aaaab, v148
	v_mul_f32_e32 v2, 0x4b800000, v0
	v_cmp_gt_f32_e64 s[0:1], s2, v0
	s_nop 1
	v_cndmask_b32_e64 v0, v0, v2, s[0:1]
	v_rsq_f32_e32 v0, v0
	s_nop 0
	v_mul_f32_e32 v2, 0x45800000, v0
	v_cndmask_b32_e64 v0, v0, v2, s[0:1]
	v_pk_mul_f32 v[2:3], v[72:73], v[0:1] op_sel_hi:[1,0]
	v_pk_mul_f32 v[4:5], v[74:75], v[0:1] op_sel_hi:[1,0]
	v_pk_mul_f32 v[8:9], v[76:77], v[0:1] op_sel_hi:[1,0]
	v_pk_mul_f32 v[14:15], v[78:79], v[0:1] op_sel_hi:[1,0]
	v_pk_mul_f32 v[2:3], v[6:7], v[2:3]
	v_pk_mul_f32 v[4:5], v[10:11], v[4:5]
	v_pk_mul_f32 v[6:7], v[12:13], v[8:9]
	v_pk_mul_f32 v[8:9], v[16:17], v[14:15]
	ds_bpermute_b32 v16, v81, v2
	ds_bpermute_b32 v17, v81, v3
	ds_bpermute_b32 v14, v81, v4
	ds_bpermute_b32 v15, v81, v5
	ds_bpermute_b32 v12, v81, v6
	ds_bpermute_b32 v13, v81, v7
	ds_bpermute_b32 v10, v81, v8
	ds_bpermute_b32 v11, v81, v9
	v_or_b32_e32 v0, 60, v83
	s_and_saveexec_b64 s[0:1], s[40:41]
	s_cbranch_execz .LBB0_607
	v_add_u32_e32 v18, 0xffffff00, v67
	v_lshlrev_b32_e32 v19, 6, v0
	v_cndmask_b32_e64 v18, v19, v18, s[46:47]
	v_add_u32_e32 v30, 0, v18
	ds_read_b128 v[18:21], v30
	ds_read_b128 v[22:25], v30 offset:16
	ds_read_b128 v[26:29], v30 offset:32
	ds_read_b128 v[30:33], v30 offset:48
	s_waitcnt lgkmcnt(3)
	v_mov_b32_e32 v34, v19
	v_mov_b32_e32 v35, v21
	v_pk_mul_f32 v[16:17], v[34:35], v[16:17]
	v_mov_b32_e32 v19, v20
	v_cndmask_b32_e64 v17, v17, -v17, s[44:45]
	v_cndmask_b32_e64 v16, v16, -v16, s[44:45]
	v_pk_fma_f32 v[2:3], v[2:3], v[18:19], v[16:17]
	s_waitcnt lgkmcnt(2)
	v_mov_b32_e32 v16, v23
	v_mov_b32_e32 v17, v25
	v_pk_mul_f32 v[14:15], v[16:17], v[14:15]
	v_mov_b32_e32 v23, v24
	v_cndmask_b32_e64 v15, v15, -v15, s[44:45]
	v_cndmask_b32_e64 v14, v14, -v14, s[44:45]
	v_pk_fma_f32 v[4:5], v[4:5], v[22:23], v[14:15]
	s_waitcnt lgkmcnt(1)
	v_mov_b32_e32 v14, v27
	v_mov_b32_e32 v15, v29
	v_pk_mul_f32 v[12:13], v[14:15], v[12:13]
	v_mov_b32_e32 v27, v28
	v_cndmask_b32_e64 v13, v13, -v13, s[44:45]
	v_cndmask_b32_e64 v12, v12, -v12, s[44:45]
	v_pk_fma_f32 v[6:7], v[6:7], v[26:27], v[12:13]
	s_waitcnt lgkmcnt(0)
	v_mov_b32_e32 v12, v31
	v_mov_b32_e32 v13, v33
	v_pk_mul_f32 v[10:11], v[12:13], v[10:11]
	v_mov_b32_e32 v31, v32
	v_cndmask_b32_e64 v11, v11, -v11, s[44:45]
	v_cndmask_b32_e64 v10, v10, -v10, s[44:45]
	v_pk_fma_f32 v[8:9], v[8:9], v[30:31], v[10:11]

; template <int NCH, bool ROPE>
; DI void norm_rows16(int lane, size_t row0, bool is_ctx, int t0, const bf16_t* srcA, size_t ldA, int nA, const bf16_t* srcB, size_t ldB,
;                     const float* st, int st_idx, const float* gain, float inv_n, bf16_t* dst, size_t ldd, const float* tab) {
;     ...
;   for (int it = 0; it < 16; ++it) {
;     const int tk = it * 4 + tq;
;     const size_t row = row0 + tk;
;     const u32x4 u = ua[it];
;     const float pre = prea[it];
;     float f[8];
;     unpack8(u, f);
;     float ss = 0.f;
; #pragma unroll
;     for (int j = 0; j < 8; ++j) { f[j] *= pre; ss += f[j] * f[j]; }
;     ss += __shfl_xor(ss, 1); ss += __shfl_xor(ss, 2); ss += __shfl_xor(ss, 4); ss += __shfl_xor(ss, 8);
;     const float rs = rsqrtf(ss * inv_n + EPS);
; #pragma unroll
;     for (int j = 0; j < 8; ++j) f[j] *= rs * gv[j];
;     if (ROPE) {
;       float pf[8];
; #pragma unroll
;       for (int j = 0; j < 8; ++j) pf[j] = __shfl_xor(f[j], 1);
;       if (!is_ctx && sub >= 8 && sub < 12) {
;         const int pos = t0 + tk - CTXL;
;         const float* tr = (const float*)smem + ((sub < 10) ? (pos >> 6) : (pos & 63)) * 16;
; #pragma unroll
;         for (int j = 0; j < 8; ++j) {
;           const float c = tr[2 * j], sn = tr[2 * j + 1];
;           f[j] = (sub & 1) ? (pf[j] * sn + f[j] * c) : (f[j] * c - pf[j] * sn);
;         }
;       }
.LBB0_852:
	s_or_b64 exec, exec, s[0:1]
	v_and_b32_e32 v83, 64, v192
	v_xor_b32_e32 v71, 1, v192
	v_add_u32_e32 v87, 64, v83
	v_cmp_lt_i32_e64 s[0:1], v71, v87
	v_xor_b32_e32 v83, 2, v192
	v_xor_b32_e32 v85, 4, v192
	v_cndmask_b32_e64 v71, v192, v71, s[0:1]
	v_cmp_lt_i32_e64 s[0:1], v83, v87
	v_xor_b32_e32 v89, 8, v192
	s_waitcnt vmcnt(0)
	v_lshlrev_b32_e32 v114, 16, v62
	v_cndmask_b32_e64 v83, v192, v83, s[0:1]
	v_cmp_lt_i32_e64 s[0:1], v85, v87
	v_and_b32_e32 v115, 0xffff0000, v62
	v_pk_mul_f32 v[114:115], v[112:113], v[114:115] op_sel_hi:[0,1]
	v_cndmask_b32_e64 v85, v192, v85, s[0:1]
	v_cmp_lt_i32_e64 s[0:1], v89, v87
	v_lshlrev_b32_e32 v62, 16, v63
	v_and_b32_e32 v63, 0xffff0000, v63
	v_cndmask_b32_e64 v87, v192, v89, s[0:1]
	v_and_b32_e32 v89, 12, v124
	v_cmp_eq_u32_e64 s[0:1], 8, v89
	v_and_b32_e32 v89, 1, v124
	v_pk_mul_f32 v[116:117], v[114:115], v[114:115]
	v_pk_mul_f32 v[62:63], v[112:113], v[62:63] op_sel_hi:[0,1]
	s_xor_b64 s[18:19], s[42:43], -1
	v_cmp_gt_u32_e64 s[44:45], 10, v120
	v_cmp_eq_u32_e64 s[42:43], 0, v89
	v_pk_mul_f32 v[118:119], v[62:63], v[62:63]
	v_lshlrev_b32_e32 v120, 16, v64
	v_and_b32_e32 v121, 0xffff0000, v64
	v_add_f32_e32 v89, v116, v117
	v_pk_mul_f32 v[120:121], v[112:113], v[120:121] op_sel_hi:[0,1]
	v_add_f32_e32 v89, v118, v89
	v_pk_mul_f32 v[122:123], v[120:121], v[120:121]
	v_lshlrev_b32_e32 v64, 16, v65
	v_and_b32_e32 v65, 0xffff0000, v65
	v_add_f32_e32 v89, v119, v89
	v_pk_mul_f32 v[124:125], v[112:113], v[64:65] op_sel_hi:[0,1]
	v_add_f32_e32 v89, v122, v89
	v_pk_mul_f32 v[64:65], v[124:125], v[124:125]
	v_add_f32_e32 v89, v123, v89
	v_add_f32_e32 v64, v64, v89
	v_lshlrev_b32_e32 v71, 2, v71
	v_add_f32_e32 v64, v65, v64
	v_lshlrev_b32_e32 v83, 2, v83
	v_lshlrev_b32_e32 v85, 2, v85
	v_lshlrev_b32_e32 v87, 2, v87
	s_and_b64 s[26:27], s[18:19], s[0:1]
	s_waitcnt lgkmcnt(0)
	s_nop 1
	v_add_f32_dpp v64, v64, v64 quad_perm:[1,0,3,2] row_mask:0xf bank_mask:0xf
	v_add_u32_e32 v67, 0xffffff00, v67
	s_waitcnt lgkmcnt(0)
	s_nop 1
	v_add_f32_dpp v64, v64, v64 quad_perm:[2,3,0,1] row_mask:0xf bank_mask:0xf
	s_waitcnt lgkmcnt(0)
	s_nop 1
	v_add_f32_dpp v64, v64, v64 row_ror:4 row_mask:0xf bank_mask:0xf
	s_waitcnt lgkmcnt(0)
	s_nop 1
	v_add_f32_dpp v64, v64, v64 row_ror:8 row_mask:0xf bank_mask:0xf
	v_fmamk_f32 v64, v64, 0x3c2aaaab, v148
	v_cmp_gt_f32_e64 s[0:1], s2, v64
	v_mul_f32_e32 v65, 0x4b800000, v64
	s_nop 0
	v_cndmask_b32_e64 v64, v64, v65, s[0:1]
	v_rsq_f32_e32 v64, v64
	s_nop 0
	v_mul_f32_e32 v65, 0x45800000, v64
	v_cndmask_b32_e64 v116, v64, v65, s[0:1]
	v_pk_mul_f32 v[112:113], v[74:75], v[116:117] op_sel_hi:[1,0]
	v_pk_mul_f32 v[64:65], v[72:73], v[116:117] op_sel_hi:[1,0]
	v_pk_mul_f32 v[112:113], v[62:63], v[112:113]
	v_pk_mul_f32 v[62:63], v[76:77], v[116:117] op_sel_hi:[1,0]
	v_pk_mul_f32 v[64:65], v[114:115], v[64:65]
	v_pk_mul_f32 v[114:115], v[120:121], v[62:63]
	v_pk_mul_f32 v[62:63], v[78:79], v[116:117] op_sel_hi:[1,0]
	ds_bpermute_b32 v122, v71, v64
	v_pk_mul_f32 v[116:117], v[124:125], v[62:63]
	ds_bpermute_b32 v123, v71, v65
	ds_bpermute_b32 v120, v71, v112
	ds_bpermute_b32 v121, v71, v113
	ds_bpermute_b32 v118, v71, v114
	ds_bpermute_b32 v119, v71, v115
	ds_bpermute_b32 v62, v71, v116
	ds_bpermute_b32 v63, v71, v117
	s_and_saveexec_b64 s[0:1], s[26:27]
	s_cbranch_execz .LBB0_854
	v_lshlrev_b32_e32 v89, 6, v81
	v_cndmask_b32_e64 v89, v89, v67, s[44:45]
	v_add_u32_e32 v89, 0, v89
	ds_read_b128 v[124:127], v89
	ds_read_b128 v[128:131], v89 offset:16
	ds_read_b128 v[132:135], v89 offset:32
	ds_read_b128 v[136:139], v89 offset:48
	s_waitcnt lgkmcnt(3)
	v_mov_b32_e32 v140, v125
	v_mov_b32_e32 v141, v127
	v_pk_mul_f32 v[122:123], v[140:141], v[122:123]
	v_mov_b32_e32 v125, v126
	v_cndmask_b32_e64 v123, v123, -v123, s[42:43]
	v_cndmask_b32_e64 v122, v122, -v122, s[42:43]
	v_pk_fma_f32 v[64:65], v[64:65], v[124:125], v[122:123]
	s_waitcnt lgkmcnt(2)
	v_mov_b32_e32 v122, v129
	v_mov_b32_e32 v123, v131
	v_pk_mul_f32 v[120:121], v[122:123], v[120:121]
	v_mov_b32_e32 v129, v130
	v_cndmask_b32_e64 v121, v121, -v121, s[42:43]
	v_cndmask_b32_e64 v120, v120, -v120, s[42:43]
	v_pk_fma_f32 v[112:113], v[112:113], v[128:129], v[120:121]
	s_waitcnt lgkmcnt(1)
	v_mov_b32_e32 v120, v133
	v_mov_b32_e32 v121, v135
	v_pk_mul_f32 v[118:119], v[120:121], v[118:119]
	v_mov_b32_e32 v133, v134
	v_cndmask_b32_e64 v119, v119, -v119, s[42:43]
	v_cndmask_b32_e64 v118, v118, -v118, s[42:43]
	v_pk_fma_f32 v[114:115], v[114:115], v[132:133], v[118:119]
	s_waitcnt lgkmcnt(0)
	v_mov_b32_e32 v118, v137
	v_mov_b32_e32 v119, v139
	v_pk_mul_f32 v[62:63], v[118:119], v[62:63]
	v_mov_b32_e32 v137, v138
	v_cndmask_b32_e64 v63, v63, -v63, s[42:43]
	v_cndmask_b32_e64 v62, v62, -v62, s[42:43]
	v_pk_fma_f32 v[116:117], v[116:117], v[136:137], v[62:63]

; template <int NCH, bool ROPE>
; DI void norm_rows16(int lane, size_t row0, bool is_ctx, int t0, const bf16_t* srcA, size_t ldA, int nA, const bf16_t* srcB, size_t ldB,
;                     const float* st, int st_idx, const float* gain, float inv_n, bf16_t* dst, size_t ldd, const float* tab) {
;     ...
;   for (int it = 0; it < 16; ++it) {
;     const int tk = it * 4 + tq;
;     const size_t row = row0 + tk;
;     const u32x4 u = ua[it];
;     const float pre = prea[it];
;     float f[8];
;     unpack8(u, f);
;     float ss = 0.f;
; #pragma unroll
;     for (int j = 0; j < 8; ++j) { f[j] *= pre; ss += f[j] * f[j]; }
;     ss += __shfl_xor(ss, 1); ss += __shfl_xor(ss, 2); ss += __shfl_xor(ss, 4); ss += __shfl_xor(ss, 8);
;     const float rs = rsqrtf(ss * inv_n + EPS);
; #pragma unroll
;     for (int j = 0; j < 8; ++j) f[j] *= rs * gv[j];
;     if (ROPE) {
;       float pf[8];
; #pragma unroll
;       for (int j = 0; j < 8; ++j) pf[j] = __shfl_xor(f[j], 1);
;       if (!is_ctx && sub >= 8 && sub < 12) {
;         const int pos = t0 + tk - CTXL;
;         const float* tr = (const float*)smem + ((sub < 10) ? (pos >> 6) : (pos & 63)) * 16;
; #pragma unroll
;         for (int j = 0; j < 8; ++j) {
;           const float c = tr[2 * j], sn = tr[2 * j + 1];
;           f[j] = (sub & 1) ? (pf[j] * sn + f[j] * c) : (f[j] * c - pf[j] * sn);
;         }
;       }
.LBB0_856:
	s_or_b64 exec, exec, s[0:1]
	v_lshlrev_b32_e32 v64, 16, v58
	v_and_b32_e32 v65, 0xffff0000, v58
	v_pk_mul_f32 v[64:65], v[110:111], v[64:65] op_sel_hi:[0,1]
	v_lshlrev_b32_e32 v58, 16, v59
	v_and_b32_e32 v59, 0xffff0000, v59
	v_pk_mul_f32 v[106:107], v[64:65], v[64:65]
	v_pk_mul_f32 v[108:109], v[110:111], v[58:59] op_sel_hi:[0,1]
	v_pk_mul_f32 v[58:59], v[108:109], v[108:109]
	v_lshlrev_b32_e32 v112, 16, v60
	v_and_b32_e32 v113, 0xffff0000, v60
	v_add_f32_e32 v0, v106, v107
	v_pk_mul_f32 v[112:113], v[110:111], v[112:113] op_sel_hi:[0,1]
	v_add_f32_e32 v0, v58, v0
	v_pk_mul_f32 v[114:115], v[112:113], v[112:113]
	v_lshlrev_b32_e32 v60, 16, v61
	v_and_b32_e32 v61, 0xffff0000, v61
	v_add_f32_e32 v0, v59, v0
	v_pk_mul_f32 v[110:111], v[110:111], v[60:61] op_sel_hi:[0,1]
	v_add_f32_e32 v0, v114, v0
	v_pk_mul_f32 v[60:61], v[110:111], v[110:111]
	v_add_f32_e32 v0, v115, v0
	v_add_f32_e32 v0, v60, v0
	v_add_f32_e32 v0, v61, v0
	s_waitcnt lgkmcnt(0)
	s_nop 1
	v_add_f32_dpp v0, v0, v0 quad_perm:[1,0,3,2] row_mask:0xf bank_mask:0xf
	s_waitcnt lgkmcnt(0)
	s_nop 1
	v_add_f32_dpp v0, v0, v0 quad_perm:[2,3,0,1] row_mask:0xf bank_mask:0xf
	s_waitcnt lgkmcnt(0)
	s_nop 1
	v_add_f32_dpp v0, v0, v0 row_ror:4 row_mask:0xf bank_mask:0xf
	s_waitcnt lgkmcnt(0)
	s_nop 1
	v_add_f32_dpp v0, v0, v0 row_ror:8 row_mask:0xf bank_mask:0xf
	v_fmamk_f32 v0, v0, 0x3c2aaaab, v148
	v_mul_f32_e32 v58, 0x4b800000, v0
	v_cmp_gt_f32_e64 s[0:1], s2, v0
	s_nop 1
	v_cndmask_b32_e64 v0, v0, v58, s[0:1]
	v_rsq_f32_e32 v0, v0
	s_nop 0
	v_mul_f32_e32 v58, 0x45800000, v0
	v_cndmask_b32_e64 v0, v0, v58, s[0:1]
	v_pk_mul_f32 v[58:59], v[72:73], v[0:1] op_sel_hi:[1,0]
	v_pk_mul_f32 v[60:61], v[74:75], v[0:1] op_sel_hi:[1,0]
	v_pk_mul_f32 v[106:107], v[76:77], v[0:1] op_sel_hi:[1,0]
	v_pk_mul_f32 v[114:115], v[78:79], v[0:1] op_sel_hi:[1,0]
	v_pk_mul_f32 v[58:59], v[64:65], v[58:59]
	v_pk_mul_f32 v[60:61], v[108:109], v[60:61]
	v_pk_mul_f32 v[64:65], v[112:113], v[106:107]
	v_pk_mul_f32 v[106:107], v[110:111], v[114:115]
	ds_bpermute_b32 v114, v71, v58
	ds_bpermute_b32 v115, v71, v59
	ds_bpermute_b32 v112, v71, v60
	ds_bpermute_b32 v113, v71, v61
	ds_bpermute_b32 v110, v71, v64
	ds_bpermute_b32 v111, v71, v65
	ds_bpermute_b32 v108, v71, v106
	ds_bpermute_b32 v109, v71, v107
	v_or_b32_e32 v0, 4, v81
	s_and_saveexec_b64 s[0:1], s[26:27]
	s_cbranch_execz .LBB0_858
	v_lshlrev_b32_e32 v89, 6, v0
	v_cndmask_b32_e64 v89, v89, v67, s[44:45]
	v_add_u32_e32 v89, 0, v89
	ds_read_b128 v[116:119], v89
	ds_read_b128 v[120:123], v89 offset:16
	ds_read_b128 v[124:127], v89 offset:32
	ds_read_b128 v[128:131], v89 offset:48
	s_waitcnt lgkmcnt(3)
	v_mov_b32_e32 v132, v117
	v_mov_b32_e32 v133, v119
	v_pk_mul_f32 v[114:115], v[132:133], v[114:115]
	v_mov_b32_e32 v117, v118
	v_cndmask_b32_e64 v115, v115, -v115, s[42:43]
	v_cndmask_b32_e64 v114, v114, -v114, s[42:43]
	v_pk_fma_f32 v[58:59], v[58:59], v[116:117], v[114:115]
	s_waitcnt lgkmcnt(2)
	v_mov_b32_e32 v114, v121
	v_mov_b32_e32 v115, v123
	v_pk_mul_f32 v[112:113], v[114:115], v[112:113]
	v_mov_b32_e32 v121, v122
	v_cndmask_b32_e64 v113, v113, -v113, s[42:43]
	v_cndmask_b32_e64 v112, v112, -v112, s[42:43]
	v_pk_fma_f32 v[60:61], v[60:61], v[120:121], v[112:113]
	s_waitcnt lgkmcnt(1)
	v_mov_b32_e32 v112, v125
	v_mov_b32_e32 v113, v127
	v_pk_mul_f32 v[110:111], v[112:113], v[110:111]
	v_mov_b32_e32 v125, v126
	v_cndmask_b32_e64 v111, v111, -v111, s[42:43]
	v_cndmask_b32_e64 v110, v110, -v110, s[42:43]
	v_pk_fma_f32 v[64:65], v[64:65], v[124:125], v[110:111]
	s_waitcnt lgkmcnt(0)
	v_mov_b32_e32 v110, v129
	v_mov_b32_e32 v111, v131
	v_pk_mul_f32 v[108:109], v[110:111], v[108:109]
	v_mov_b32_e32 v129, v130
	v_cndmask_b32_e64 v109, v109, -v109, s[42:43]
	v_cndmask_b32_e64 v108, v108, -v108, s[42:43]
	v_pk_fma_f32 v[106:107], v[106:107], v[128:129], v[108:109]

; template <int NCH, bool ROPE>
; DI void norm_rows16(int lane, size_t row0, bool is_ctx, int t0, const bf16_t* srcA, size_t ldA, int nA, const bf16_t* srcB, size_t ldB,
;                     const float* st, int st_idx, const float* gain, float inv_n, bf16_t* dst, size_t ldd, const float* tab) {
;     ...
;   for (int it = 0; it < 16; ++it) {
;     const int tk = it * 4 + tq;
;     const size_t row = row0 + tk;
;     const u32x4 u = ua[it];
;     const float pre = prea[it];
;     float f[8];
;     unpack8(u, f);
;     float ss = 0.f;
; #pragma unroll
;     for (int j = 0; j < 8; ++j) { f[j] *= pre; ss += f[j] * f[j]; }
;     ss += __shfl_xor(ss, 1); ss += __shfl_xor(ss, 2); ss += __shfl_xor(ss, 4); ss += __shfl_xor(ss, 8);
;     const float rs = rsqrtf(ss * inv_n + EPS);
; #pragma unroll
;     for (int j = 0; j < 8; ++j) f[j] *= rs * gv[j];
;     if (ROPE) {
;       float pf[8];
; #pragma unroll
;       for (int j = 0; j < 8; ++j) pf[j] = __shfl_xor(f[j], 1);
;       if (!is_ctx && sub >= 8 && sub < 12) {
;         const int pos = t0 + tk - CTXL;
;         const float* tr = (const float*)smem + ((sub < 10) ? (pos >> 6) : (pos & 63)) * 16;
; #pragma unroll
;         for (int j = 0; j < 8; ++j) {
;           const float c = tr[2 * j], sn = tr[2 * j + 1];
;           f[j] = (sub & 1) ? (pf[j] * sn + f[j] * c) : (f[j] * c - pf[j] * sn);
;         }
;       }
.LBB0_860:
	s_or_b64 exec, exec, s[0:1]
	s_nop 0
	v_lshlrev_b32_e32 v58, 16, v54
	v_and_b32_e32 v59, 0xffff0000, v54
	v_pk_mul_f32 v[58:59], v[104:105], v[58:59] op_sel_hi:[0,1]
	v_lshlrev_b32_e32 v54, 16, v55
	v_and_b32_e32 v55, 0xffff0000, v55
	v_pk_mul_f32 v[60:61], v[58:59], v[58:59]
	v_pk_mul_f32 v[64:65], v[104:105], v[54:55] op_sel_hi:[0,1]
	v_pk_mul_f32 v[54:55], v[64:65], v[64:65]
	v_lshlrev_b32_e32 v106, 16, v56
	v_and_b32_e32 v107, 0xffff0000, v56
	v_add_f32_e32 v0, v60, v61
	v_pk_mul_f32 v[106:107], v[104:105], v[106:107] op_sel_hi:[0,1]
	v_add_f32_e32 v0, v54, v0
	s_waitcnt lgkmcnt(0)
	v_pk_mul_f32 v[108:109], v[106:107], v[106:107]
	v_lshlrev_b32_e32 v56, 16, v57
	v_and_b32_e32 v57, 0xffff0000, v57
	v_add_f32_e32 v0, v55, v0
	v_pk_mul_f32 v[104:105], v[104:105], v[56:57] op_sel_hi:[0,1]
	v_add_f32_e32 v0, v108, v0
	v_pk_mul_f32 v[56:57], v[104:105], v[104:105]
	v_add_f32_e32 v0, v109, v0
	v_add_f32_e32 v0, v56, v0
	v_add_f32_e32 v0, v57, v0
	s_waitcnt lgkmcnt(0)
	s_nop 1
	v_add_f32_dpp v0, v0, v0 quad_perm:[1,0,3,2] row_mask:0xf bank_mask:0xf
	s_waitcnt lgkmcnt(0)
	s_nop 1
	v_add_f32_dpp v0, v0, v0 quad_perm:[2,3,0,1] row_mask:0xf bank_mask:0xf
	s_waitcnt lgkmcnt(0)
	s_nop 1
	v_add_f32_dpp v0, v0, v0 row_ror:4 row_mask:0xf bank_mask:0xf
	s_waitcnt lgkmcnt(0)
	s_nop 1
	v_add_f32_dpp v0, v0, v0 row_ror:8 row_mask:0xf bank_mask:0xf
	v_fmamk_f32 v0, v0, 0x3c2aaaab, v148
	v_mul_f32_e32 v54, 0x4b800000, v0
	v_cmp_gt_f32_e64 s[0:1], s2, v0
	s_nop 1
	v_cndmask_b32_e64 v0, v0, v54, s[0:1]
	v_rsq_f32_e32 v0, v0
	s_nop 0
	v_mul_f32_e32 v54, 0x45800000, v0
	v_cndmask_b32_e64 v0, v0, v54, s[0:1]
	v_pk_mul_f32 v[54:55], v[72:73], v[0:1] op_sel_hi:[1,0]
	v_pk_mul_f32 v[56:57], v[74:75], v[0:1] op_sel_hi:[1,0]
	v_pk_mul_f32 v[60:61], v[76:77], v[0:1] op_sel_hi:[1,0]
	v_pk_mul_f32 v[108:109], v[78:79], v[0:1] op_sel_hi:[1,0]
	v_pk_mul_f32 v[54:55], v[58:59], v[54:55]
	v_pk_mul_f32 v[56:57], v[64:65], v[56:57]
	v_pk_mul_f32 v[58:59], v[106:107], v[60:61]
	v_pk_mul_f32 v[60:61], v[104:105], v[108:109]
	ds_bpermute_b32 v108, v71, v54
	ds_bpermute_b32 v109, v71, v55
	ds_bpermute_b32 v106, v71, v56
	ds_bpermute_b32 v107, v71, v57
	ds_bpermute_b32 v104, v71, v58
	ds_bpermute_b32 v105, v71, v59
	ds_bpermute_b32 v64, v71, v60
	ds_bpermute_b32 v65, v71, v61
	v_or_b32_e32 v0, 8, v81
	s_and_saveexec_b64 s[0:1], s[26:27]
	s_cbranch_execz .LBB0_862
	v_lshlrev_b32_e32 v89, 6, v0
	v_cndmask_b32_e64 v89, v89, v67, s[44:45]
	v_add_u32_e32 v89, 0, v89
	ds_read_b128 v[110:113], v89
	ds_read_b128 v[114:117], v89 offset:16
	ds_read_b128 v[118:121], v89 offset:32
	ds_read_b128 v[122:125], v89 offset:48
	s_waitcnt lgkmcnt(3)
	v_mov_b32_e32 v126, v111
	v_mov_b32_e32 v127, v113
	v_pk_mul_f32 v[108:109], v[126:127], v[108:109]
	v_mov_b32_e32 v111, v112
	v_cndmask_b32_e64 v109, v109, -v109, s[42:43]
	v_cndmask_b32_e64 v108, v108, -v108, s[42:43]
	v_pk_fma_f32 v[54:55], v[54:55], v[110:111], v[108:109]
	s_waitcnt lgkmcnt(2)
	v_mov_b32_e32 v108, v115
	v_mov_b32_e32 v109, v117
	v_pk_mul_f32 v[106:107], v[108:109], v[106:107]
	v_mov_b32_e32 v115, v116
	v_cndmask_b32_e64 v107, v107, -v107, s[42:43]
	v_cndmask_b32_e64 v106, v106, -v106, s[42:43]
	v_pk_fma_f32 v[56:57], v[56:57], v[114:115], v[106:107]
	s_waitcnt lgkmcnt(1)
	v_mov_b32_e32 v106, v119
	v_mov_b32_e32 v107, v121
	v_pk_mul_f32 v[104:105], v[106:107], v[104:105]
	v_mov_b32_e32 v119, v120
	v_cndmask_b32_e64 v105, v105, -v105, s[42:43]
	v_cndmask_b32_e64 v104, v104, -v104, s[42:43]
	v_pk_fma_f32 v[58:59], v[58:59], v[118:119], v[104:105]
	s_waitcnt lgkmcnt(0)
	v_mov_b32_e32 v104, v123
	v_mov_b32_e32 v105, v125
	v_pk_mul_f32 v[64:65], v[104:105], v[64:65]
	v_mov_b32_e32 v123, v124
	v_cndmask_b32_e64 v65, v65, -v65, s[42:43]
	v_cndmask_b32_e64 v64, v64, -v64, s[42:43]
	v_pk_fma_f32 v[60:61], v[60:61], v[122:123], v[64:65]

; template <int NCH, bool ROPE>
; DI void norm_rows16(int lane, size_t row0, bool is_ctx, int t0, const bf16_t* srcA, size_t ldA, int nA, const bf16_t* srcB, size_t ldB,
;                     const float* st, int st_idx, const float* gain, float inv_n, bf16_t* dst, size_t ldd, const float* tab) {
;     ...
;   for (int it = 0; it < 16; ++it) {
;     const int tk = it * 4 + tq;
;     const size_t row = row0 + tk;
;     const u32x4 u = ua[it];
;     const float pre = prea[it];
;     float f[8];
;     unpack8(u, f);
;     float ss = 0.f;
; #pragma unroll
;     for (int j = 0; j < 8; ++j) { f[j] *= pre; ss += f[j] * f[j]; }
;     ss += __shfl_xor(ss, 1); ss += __shfl_xor(ss, 2); ss += __shfl_xor(ss, 4); ss += __shfl_xor(ss, 8);
;     const float rs = rsqrtf(ss * inv_n + EPS);
; #pragma unroll
;     for (int j = 0; j < 8; ++j) f[j] *= rs * gv[j];
;     if (ROPE) {
;       float pf[8];
; #pragma unroll
;       for (int j = 0; j < 8; ++j) pf[j] = __shfl_xor(f[j], 1);
;       if (!is_ctx && sub >= 8 && sub < 12) {
;         const int pos = t0 + tk - CTXL;
;         const float* tr = (const float*)smem + ((sub < 10) ? (pos >> 6) : (pos & 63)) * 16;
; #pragma unroll
;         for (int j = 0; j < 8; ++j) {
;           const float c = tr[2 * j], sn = tr[2 * j + 1];
;           f[j] = (sub & 1) ? (pf[j] * sn + f[j] * c) : (f[j] * c - pf[j] * sn);
;         }
;       }
.LBB0_864:
	s_or_b64 exec, exec, s[0:1]
	s_nop 0
	v_lshlrev_b32_e32 v54, 16, v50
	v_and_b32_e32 v55, 0xffff0000, v50
	v_pk_mul_f32 v[54:55], v[102:103], v[54:55] op_sel_hi:[0,1]
	v_lshlrev_b32_e32 v50, 16, v51
	v_and_b32_e32 v51, 0xffff0000, v51
	v_pk_mul_f32 v[56:57], v[54:55], v[54:55]
	v_pk_mul_f32 v[58:59], v[102:103], v[50:51] op_sel_hi:[0,1]
	v_pk_mul_f32 v[50:51], v[58:59], v[58:59]
	v_lshlrev_b32_e32 v60, 16, v52
	v_and_b32_e32 v61, 0xffff0000, v52
	v_add_f32_e32 v0, v56, v57
	v_pk_mul_f32 v[60:61], v[102:103], v[60:61] op_sel_hi:[0,1]
	v_add_f32_e32 v0, v50, v0
	s_waitcnt lgkmcnt(0)
	v_pk_mul_f32 v[64:65], v[60:61], v[60:61]
	v_lshlrev_b32_e32 v52, 16, v53
	v_and_b32_e32 v53, 0xffff0000, v53
	v_add_f32_e32 v0, v51, v0
	v_pk_mul_f32 v[102:103], v[102:103], v[52:53] op_sel_hi:[0,1]
	v_add_f32_e32 v0, v64, v0
	v_pk_mul_f32 v[52:53], v[102:103], v[102:103]
	v_add_f32_e32 v0, v65, v0
	v_add_f32_e32 v0, v52, v0
	v_add_f32_e32 v0, v53, v0
	s_waitcnt lgkmcnt(0)
	s_nop 1
	v_add_f32_dpp v0, v0, v0 quad_perm:[1,0,3,2] row_mask:0xf bank_mask:0xf
	s_waitcnt lgkmcnt(0)
	s_nop 1
	v_add_f32_dpp v0, v0, v0 quad_perm:[2,3,0,1] row_mask:0xf bank_mask:0xf
	s_waitcnt lgkmcnt(0)
	s_nop 1
	v_add_f32_dpp v0, v0, v0 row_ror:4 row_mask:0xf bank_mask:0xf
	s_waitcnt lgkmcnt(0)
	s_nop 1
	v_add_f32_dpp v0, v0, v0 row_ror:8 row_mask:0xf bank_mask:0xf
	v_fmamk_f32 v0, v0, 0x3c2aaaab, v148
	v_mul_f32_e32 v50, 0x4b800000, v0
	v_cmp_gt_f32_e64 s[0:1], s2, v0
	s_nop 1
	v_cndmask_b32_e64 v0, v0, v50, s[0:1]
	v_rsq_f32_e32 v0, v0
	s_nop 0
	v_mul_f32_e32 v50, 0x45800000, v0
	v_cndmask_b32_e64 v0, v0, v50, s[0:1]
	v_pk_mul_f32 v[50:51], v[72:73], v[0:1] op_sel_hi:[1,0]
	v_pk_mul_f32 v[52:53], v[74:75], v[0:1] op_sel_hi:[1,0]
	v_pk_mul_f32 v[56:57], v[76:77], v[0:1] op_sel_hi:[1,0]
	v_pk_mul_f32 v[64:65], v[78:79], v[0:1] op_sel_hi:[1,0]
	v_pk_mul_f32 v[50:51], v[54:55], v[50:51]
	v_pk_mul_f32 v[52:53], v[58:59], v[52:53]
	v_pk_mul_f32 v[54:55], v[60:61], v[56:57]
	v_pk_mul_f32 v[56:57], v[102:103], v[64:65]
	ds_bpermute_b32 v102, v71, v50
	ds_bpermute_b32 v103, v71, v51
	ds_bpermute_b32 v64, v71, v52
	ds_bpermute_b32 v65, v71, v53
	ds_bpermute_b32 v60, v71, v54
	ds_bpermute_b32 v61, v71, v55
	ds_bpermute_b32 v58, v71, v56
	ds_bpermute_b32 v59, v71, v57
	v_or_b32_e32 v0, 12, v81
	s_and_saveexec_b64 s[0:1], s[26:27]
	s_cbranch_execz .LBB0_866
	v_lshlrev_b32_e32 v89, 6, v0
	v_cndmask_b32_e64 v89, v89, v67, s[44:45]
	v_add_u32_e32 v89, 0, v89
	ds_read_b128 v[104:107], v89
	ds_read_b128 v[108:111], v89 offset:16
	ds_read_b128 v[112:115], v89 offset:32
	ds_read_b128 v[116:119], v89 offset:48
	s_waitcnt lgkmcnt(3)
	v_mov_b32_e32 v120, v105
	v_mov_b32_e32 v121, v107
	v_pk_mul_f32 v[102:103], v[120:121], v[102:103]
	v_mov_b32_e32 v105, v106
	v_cndmask_b32_e64 v103, v103, -v103, s[42:43]
	v_cndmask_b32_e64 v102, v102, -v102, s[42:43]
	v_pk_fma_f32 v[50:51], v[50:51], v[104:105], v[102:103]
	s_waitcnt lgkmcnt(2)
	v_mov_b32_e32 v102, v109
	v_mov_b32_e32 v103, v111
	v_pk_mul_f32 v[64:65], v[102:103], v[64:65]
	v_mov_b32_e32 v109, v110
	v_cndmask_b32_e64 v65, v65, -v65, s[42:43]
	v_cndmask_b32_e64 v64, v64, -v64, s[42:43]
	v_pk_fma_f32 v[52:53], v[52:53], v[108:109], v[64:65]
	s_waitcnt lgkmcnt(1)
	v_mov_b32_e32 v64, v113
	v_mov_b32_e32 v65, v115
	v_pk_mul_f32 v[60:61], v[64:65], v[60:61]
	v_mov_b32_e32 v113, v114
	v_cndmask_b32_e64 v61, v61, -v61, s[42:43]
	v_cndmask_b32_e64 v60, v60, -v60, s[42:43]
	v_pk_fma_f32 v[54:55], v[54:55], v[112:113], v[60:61]
	s_waitcnt lgkmcnt(0)
	v_mov_b32_e32 v60, v117
	v_mov_b32_e32 v61, v119
	v_pk_mul_f32 v[58:59], v[60:61], v[58:59]
	v_mov_b32_e32 v117, v118
	v_cndmask_b32_e64 v59, v59, -v59, s[42:43]
	v_cndmask_b32_e64 v58, v58, -v58, s[42:43]
	v_pk_fma_f32 v[56:57], v[56:57], v[116:117], v[58:59]

; template <int NCH, bool ROPE>
; DI void norm_rows16(int lane, size_t row0, bool is_ctx, int t0, const bf16_t* srcA, size_t ldA, int nA, const bf16_t* srcB, size_t ldB,
;                     const float* st, int st_idx, const float* gain, float inv_n, bf16_t* dst, size_t ldd, const float* tab) {
;     ...
;   for (int it = 0; it < 16; ++it) {
;     const int tk = it * 4 + tq;
;     const size_t row = row0 + tk;
;     const u32x4 u = ua[it];
;     const float pre = prea[it];
;     float f[8];
;     unpack8(u, f);
;     float ss = 0.f;
; #pragma unroll
;     for (int j = 0; j < 8; ++j) { f[j] *= pre; ss += f[j] * f[j]; }
;     ss += __shfl_xor(ss, 1); ss += __shfl_xor(ss, 2); ss += __shfl_xor(ss, 4); ss += __shfl_xor(ss, 8);
;     const float rs = rsqrtf(ss * inv_n + EPS);
; #pragma unroll
;     for (int j = 0; j < 8; ++j) f[j] *= rs * gv[j];
;     if (ROPE) {
;       float pf[8];
; #pragma unroll
;       for (int j = 0; j < 8; ++j) pf[j] = __shfl_xor(f[j], 1);
;       if (!is_ctx && sub >= 8 && sub < 12) {
;         const int pos = t0 + tk - CTXL;
;         const float* tr = (const float*)smem + ((sub < 10) ? (pos >> 6) : (pos & 63)) * 16;
; #pragma unroll
;         for (int j = 0; j < 8; ++j) {
;           const float c = tr[2 * j], sn = tr[2 * j + 1];
;           f[j] = (sub & 1) ? (pf[j] * sn + f[j] * c) : (f[j] * c - pf[j] * sn);
;         }
;       }
.LBB0_868:
	s_or_b64 exec, exec, s[0:1]
	s_nop 0
	v_lshlrev_b32_e32 v50, 16, v46
	v_and_b32_e32 v51, 0xffff0000, v46
	v_pk_mul_f32 v[50:51], v[100:101], v[50:51] op_sel_hi:[0,1]
	v_lshlrev_b32_e32 v46, 16, v47
	v_and_b32_e32 v47, 0xffff0000, v47
	v_pk_mul_f32 v[52:53], v[50:51], v[50:51]
	v_pk_mul_f32 v[54:55], v[100:101], v[46:47] op_sel_hi:[0,1]
	v_pk_mul_f32 v[46:47], v[54:55], v[54:55]
	v_lshlrev_b32_e32 v56, 16, v48
	v_and_b32_e32 v57, 0xffff0000, v48
	v_add_f32_e32 v0, v52, v53
	v_pk_mul_f32 v[56:57], v[100:101], v[56:57] op_sel_hi:[0,1]
	v_add_f32_e32 v0, v46, v0
	s_waitcnt lgkmcnt(0)
	v_pk_mul_f32 v[58:59], v[56:57], v[56:57]
	v_lshlrev_b32_e32 v48, 16, v49
	v_and_b32_e32 v49, 0xffff0000, v49
	v_add_f32_e32 v0, v47, v0
	v_pk_mul_f32 v[60:61], v[100:101], v[48:49] op_sel_hi:[0,1]
	v_add_f32_e32 v0, v58, v0
	v_pk_mul_f32 v[48:49], v[60:61], v[60:61]
	v_add_f32_e32 v0, v59, v0
	v_add_f32_e32 v0, v48, v0
	v_add_f32_e32 v0, v49, v0
	s_waitcnt lgkmcnt(0)
	s_nop 1
	v_add_f32_dpp v0, v0, v0 quad_perm:[1,0,3,2] row_mask:0xf bank_mask:0xf
	s_waitcnt lgkmcnt(0)
	s_nop 1
	v_add_f32_dpp v0, v0, v0 quad_perm:[2,3,0,1] row_mask:0xf bank_mask:0xf
	s_waitcnt lgkmcnt(0)
	s_nop 1
	v_add_f32_dpp v0, v0, v0 row_ror:4 row_mask:0xf bank_mask:0xf
	s_waitcnt lgkmcnt(0)
	s_nop 1
	v_add_f32_dpp v0, v0, v0 row_ror:8 row_mask:0xf bank_mask:0xf
	v_fmamk_f32 v0, v0, 0x3c2aaaab, v148
	v_mul_f32_e32 v46, 0x4b800000, v0
	v_cmp_gt_f32_e64 s[0:1], s2, v0
	s_nop 1
	v_cndmask_b32_e64 v0, v0, v46, s[0:1]
	v_rsq_f32_e32 v0, v0
	s_nop 0
	v_mul_f32_e32 v46, 0x45800000, v0
	v_cndmask_b32_e64 v0, v0, v46, s[0:1]
	v_pk_mul_f32 v[46:47], v[72:73], v[0:1] op_sel_hi:[1,0]
	v_pk_mul_f32 v[48:49], v[74:75], v[0:1] op_sel_hi:[1,0]
	v_pk_mul_f32 v[52:53], v[76:77], v[0:1] op_sel_hi:[1,0]
	v_pk_mul_f32 v[58:59], v[78:79], v[0:1] op_sel_hi:[1,0]
	v_pk_mul_f32 v[46:47], v[50:51], v[46:47]
	v_pk_mul_f32 v[48:49], v[54:55], v[48:49]
	v_pk_mul_f32 v[50:51], v[56:57], v[52:53]
	v_pk_mul_f32 v[52:53], v[60:61], v[58:59]
	ds_bpermute_b32 v60, v71, v46
	ds_bpermute_b32 v61, v71, v47
	ds_bpermute_b32 v58, v71, v48
	ds_bpermute_b32 v59, v71, v49
	ds_bpermute_b32 v56, v71, v50
	ds_bpermute_b32 v57, v71, v51
	ds_bpermute_b32 v54, v71, v52
	ds_bpermute_b32 v55, v71, v53
	v_or_b32_e32 v0, 16, v81
	s_and_saveexec_b64 s[0:1], s[26:27]
	s_cbranch_execz .LBB0_870
	v_lshlrev_b32_e32 v64, 6, v0
	v_cndmask_b32_e64 v64, v64, v67, s[44:45]
	v_add_u32_e32 v64, 0, v64
	ds_read_b128 v[100:103], v64
	ds_read_b128 v[104:107], v64 offset:16
	ds_read_b128 v[108:111], v64 offset:32
	ds_read_b128 v[112:115], v64 offset:48
	s_waitcnt lgkmcnt(3)
	v_mov_b32_e32 v64, v101
	v_mov_b32_e32 v65, v103
	v_pk_mul_f32 v[60:61], v[64:65], v[60:61]
	v_mov_b32_e32 v101, v102
	v_cndmask_b32_e64 v61, v61, -v61, s[42:43]
	v_cndmask_b32_e64 v60, v60, -v60, s[42:43]
	v_pk_fma_f32 v[46:47], v[46:47], v[100:101], v[60:61]
	s_waitcnt lgkmcnt(2)
	v_mov_b32_e32 v60, v105
	v_mov_b32_e32 v61, v107
	v_pk_mul_f32 v[58:59], v[60:61], v[58:59]
	v_mov_b32_e32 v105, v106
	v_cndmask_b32_e64 v59, v59, -v59, s[42:43]
	v_cndmask_b32_e64 v58, v58, -v58, s[42:43]
	v_pk_fma_f32 v[48:49], v[48:49], v[104:105], v[58:59]
	s_waitcnt lgkmcnt(1)
	v_mov_b32_e32 v58, v109
	v_mov_b32_e32 v59, v111
	v_pk_mul_f32 v[56:57], v[58:59], v[56:57]
	v_mov_b32_e32 v109, v110
	v_cndmask_b32_e64 v57, v57, -v57, s[42:43]
	v_cndmask_b32_e64 v56, v56, -v56, s[42:43]
	v_pk_fma_f32 v[50:51], v[50:51], v[108:109], v[56:57]
	s_waitcnt lgkmcnt(0)
	v_mov_b32_e32 v56, v113
	v_mov_b32_e32 v57, v115
	v_pk_mul_f32 v[54:55], v[56:57], v[54:55]
	v_mov_b32_e32 v113, v114
	v_cndmask_b32_e64 v55, v55, -v55, s[42:43]
	v_cndmask_b32_e64 v54, v54, -v54, s[42:43]
	v_pk_fma_f32 v[52:53], v[52:53], v[112:113], v[54:55]

; template <int NCH, bool ROPE>
; DI void norm_rows16(int lane, size_t row0, bool is_ctx, int t0, const bf16_t* srcA, size_t ldA, int nA, const bf16_t* srcB, size_t ldB,
;                     const float* st, int st_idx, const float* gain, float inv_n, bf16_t* dst, size_t ldd, const float* tab) {
;     ...
;   for (int it = 0; it < 16; ++it) {
;     const int tk = it * 4 + tq;
;     const size_t row = row0 + tk;
;     const u32x4 u = ua[it];
;     const float pre = prea[it];
;     float f[8];
;     unpack8(u, f);
;     float ss = 0.f;
; #pragma unroll
;     for (int j = 0; j < 8; ++j) { f[j] *= pre; ss += f[j] * f[j]; }
;     ss += __shfl_xor(ss, 1); ss += __shfl_xor(ss, 2); ss += __shfl_xor(ss, 4); ss += __shfl_xor(ss, 8);
;     const float rs = rsqrtf(ss * inv_n + EPS);
; #pragma unroll
;     for (int j = 0; j < 8; ++j) f[j] *= rs * gv[j];
;     if (ROPE) {
;       float pf[8];
; #pragma unroll
;       for (int j = 0; j < 8; ++j) pf[j] = __shfl_xor(f[j], 1);
;       if (!is_ctx && sub >= 8 && sub < 12) {
;         const int pos = t0 + tk - CTXL;
;         const float* tr = (const float*)smem + ((sub < 10) ? (pos >> 6) : (pos & 63)) * 16;
; #pragma unroll
;         for (int j = 0; j < 8; ++j) {
;           const float c = tr[2 * j], sn = tr[2 * j + 1];
;           f[j] = (sub & 1) ? (pf[j] * sn + f[j] * c) : (f[j] * c - pf[j] * sn);
;         }
;       }
.LBB0_872:
	s_or_b64 exec, exec, s[0:1]
	s_nop 0
	v_lshlrev_b32_e32 v46, 16, v42
	v_and_b32_e32 v47, 0xffff0000, v42
	v_pk_mul_f32 v[46:47], v[98:99], v[46:47] op_sel_hi:[0,1]
	v_lshlrev_b32_e32 v42, 16, v43
	v_and_b32_e32 v43, 0xffff0000, v43
	v_pk_mul_f32 v[48:49], v[46:47], v[46:47]
	v_pk_mul_f32 v[50:51], v[98:99], v[42:43] op_sel_hi:[0,1]
	v_pk_mul_f32 v[42:43], v[50:51], v[50:51]
	v_lshlrev_b32_e32 v52, 16, v44
	v_and_b32_e32 v53, 0xffff0000, v44
	v_add_f32_e32 v0, v48, v49
	v_pk_mul_f32 v[52:53], v[98:99], v[52:53] op_sel_hi:[0,1]
	v_add_f32_e32 v0, v42, v0
	s_waitcnt lgkmcnt(0)
	v_pk_mul_f32 v[54:55], v[52:53], v[52:53]
	v_lshlrev_b32_e32 v44, 16, v45
	v_and_b32_e32 v45, 0xffff0000, v45
	v_add_f32_e32 v0, v43, v0
	v_pk_mul_f32 v[56:57], v[98:99], v[44:45] op_sel_hi:[0,1]
	v_add_f32_e32 v0, v54, v0
	v_pk_mul_f32 v[44:45], v[56:57], v[56:57]
	v_add_f32_e32 v0, v55, v0
	v_add_f32_e32 v0, v44, v0
	v_add_f32_e32 v0, v45, v0
	s_waitcnt lgkmcnt(0)
	s_nop 1
	v_add_f32_dpp v0, v0, v0 quad_perm:[1,0,3,2] row_mask:0xf bank_mask:0xf
	s_waitcnt lgkmcnt(0)
	s_nop 1
	v_add_f32_dpp v0, v0, v0 quad_perm:[2,3,0,1] row_mask:0xf bank_mask:0xf
	s_waitcnt lgkmcnt(0)
	s_nop 1
	v_add_f32_dpp v0, v0, v0 row_ror:4 row_mask:0xf bank_mask:0xf
	s_waitcnt lgkmcnt(0)
	s_nop 1
	v_add_f32_dpp v0, v0, v0 row_ror:8 row_mask:0xf bank_mask:0xf
	v_fmamk_f32 v0, v0, 0x3c2aaaab, v148
	v_mul_f32_e32 v42, 0x4b800000, v0
	v_cmp_gt_f32_e64 s[0:1], s2, v0
	s_nop 1
	v_cndmask_b32_e64 v0, v0, v42, s[0:1]
	v_rsq_f32_e32 v0, v0
	s_nop 0
	v_mul_f32_e32 v42, 0x45800000, v0
	v_cndmask_b32_e64 v0, v0, v42, s[0:1]
	v_pk_mul_f32 v[42:43], v[72:73], v[0:1] op_sel_hi:[1,0]
	v_pk_mul_f32 v[44:45], v[74:75], v[0:1] op_sel_hi:[1,0]
	v_pk_mul_f32 v[48:49], v[76:77], v[0:1] op_sel_hi:[1,0]
	v_pk_mul_f32 v[54:55], v[78:79], v[0:1] op_sel_hi:[1,0]
	v_pk_mul_f32 v[42:43], v[46:47], v[42:43]
	v_pk_mul_f32 v[44:45], v[50:51], v[44:45]
	v_pk_mul_f32 v[46:47], v[52:53], v[48:49]
	v_pk_mul_f32 v[48:49], v[56:57], v[54:55]
	ds_bpermute_b32 v56, v71, v42
	ds_bpermute_b32 v57, v71, v43
	ds_bpermute_b32 v54, v71, v44
	ds_bpermute_b32 v55, v71, v45
	ds_bpermute_b32 v52, v71, v46
	ds_bpermute_b32 v53, v71, v47
	ds_bpermute_b32 v50, v71, v48
	ds_bpermute_b32 v51, v71, v49
	v_or_b32_e32 v0, 20, v81
	s_and_saveexec_b64 s[0:1], s[26:27]
	s_cbranch_execz .LBB0_874
	v_lshlrev_b32_e32 v58, 6, v0
	v_cndmask_b32_e64 v58, v58, v67, s[44:45]
	v_add_u32_e32 v64, 0, v58
	ds_read_b128 v[58:61], v64
	ds_read_b128 v[98:101], v64 offset:16
	ds_read_b128 v[102:105], v64 offset:32
	ds_read_b128 v[106:109], v64 offset:48
	s_waitcnt lgkmcnt(3)
	v_mov_b32_e32 v64, v59
	v_mov_b32_e32 v65, v61
	v_pk_mul_f32 v[56:57], v[64:65], v[56:57]
	v_mov_b32_e32 v59, v60
	v_cndmask_b32_e64 v57, v57, -v57, s[42:43]
	v_cndmask_b32_e64 v56, v56, -v56, s[42:43]
	v_pk_fma_f32 v[42:43], v[42:43], v[58:59], v[56:57]
	s_waitcnt lgkmcnt(2)
	v_mov_b32_e32 v56, v99
	v_mov_b32_e32 v57, v101
	v_pk_mul_f32 v[54:55], v[56:57], v[54:55]
	v_mov_b32_e32 v99, v100
	v_cndmask_b32_e64 v55, v55, -v55, s[42:43]
	v_cndmask_b32_e64 v54, v54, -v54, s[42:43]
	v_pk_fma_f32 v[44:45], v[44:45], v[98:99], v[54:55]
	s_waitcnt lgkmcnt(1)
	v_mov_b32_e32 v54, v103
	v_mov_b32_e32 v55, v105
	v_pk_mul_f32 v[52:53], v[54:55], v[52:53]
	v_mov_b32_e32 v103, v104
	v_cndmask_b32_e64 v53, v53, -v53, s[42:43]
	v_cndmask_b32_e64 v52, v52, -v52, s[42:43]
	v_pk_fma_f32 v[46:47], v[46:47], v[102:103], v[52:53]
	s_waitcnt lgkmcnt(0)
	v_mov_b32_e32 v52, v107
	v_mov_b32_e32 v53, v109
	v_pk_mul_f32 v[50:51], v[52:53], v[50:51]
	v_mov_b32_e32 v107, v108
	v_cndmask_b32_e64 v51, v51, -v51, s[42:43]
	v_cndmask_b32_e64 v50, v50, -v50, s[42:43]
	v_pk_fma_f32 v[48:49], v[48:49], v[106:107], v[50:51]

; template <int NCH, bool ROPE>
; DI void norm_rows16(int lane, size_t row0, bool is_ctx, int t0, const bf16_t* srcA, size_t ldA, int nA, const bf16_t* srcB, size_t ldB,
;                     const float* st, int st_idx, const float* gain, float inv_n, bf16_t* dst, size_t ldd, const float* tab) {
;     ...
;   for (int it = 0; it < 16; ++it) {
;     const int tk = it * 4 + tq;
;     const size_t row = row0 + tk;
;     const u32x4 u = ua[it];
;     const float pre = prea[it];
;     float f[8];
;     unpack8(u, f);
;     float ss = 0.f;
; #pragma unroll
;     for (int j = 0; j < 8; ++j) { f[j] *= pre; ss += f[j] * f[j]; }
;     ss += __shfl_xor(ss, 1); ss += __shfl_xor(ss, 2); ss += __shfl_xor(ss, 4); ss += __shfl_xor(ss, 8);
;     const float rs = rsqrtf(ss * inv_n + EPS);
; #pragma unroll
;     for (int j = 0; j < 8; ++j) f[j] *= rs * gv[j];
;     if (ROPE) {
;       float pf[8];
; #pragma unroll
;       for (int j = 0; j < 8; ++j) pf[j] = __shfl_xor(f[j], 1);
;       if (!is_ctx && sub >= 8 && sub < 12) {
;         const int pos = t0 + tk - CTXL;
;         const float* tr = (const float*)smem + ((sub < 10) ? (pos >> 6) : (pos & 63)) * 16;
; #pragma unroll
;         for (int j = 0; j < 8; ++j) {
;           const float c = tr[2 * j], sn = tr[2 * j + 1];
;           f[j] = (sub & 1) ? (pf[j] * sn + f[j] * c) : (f[j] * c - pf[j] * sn);
;         }
;       }
.LBB0_876:
	s_or_b64 exec, exec, s[0:1]
	s_nop 0
	v_lshlrev_b32_e32 v42, 16, v38
	v_and_b32_e32 v43, 0xffff0000, v38
	v_pk_mul_f32 v[42:43], v[96:97], v[42:43] op_sel_hi:[0,1]
	v_lshlrev_b32_e32 v38, 16, v39
	v_and_b32_e32 v39, 0xffff0000, v39
	v_pk_mul_f32 v[44:45], v[42:43], v[42:43]
	v_pk_mul_f32 v[46:47], v[96:97], v[38:39] op_sel_hi:[0,1]
	v_pk_mul_f32 v[38:39], v[46:47], v[46:47]
	v_lshlrev_b32_e32 v48, 16, v40
	v_and_b32_e32 v49, 0xffff0000, v40
	v_add_f32_e32 v0, v44, v45
	v_pk_mul_f32 v[48:49], v[96:97], v[48:49] op_sel_hi:[0,1]
	v_add_f32_e32 v0, v38, v0
	s_waitcnt lgkmcnt(0)
	v_pk_mul_f32 v[50:51], v[48:49], v[48:49]
	v_lshlrev_b32_e32 v40, 16, v41
	v_and_b32_e32 v41, 0xffff0000, v41
	v_add_f32_e32 v0, v39, v0
	v_pk_mul_f32 v[52:53], v[96:97], v[40:41] op_sel_hi:[0,1]
	v_add_f32_e32 v0, v50, v0
	v_pk_mul_f32 v[40:41], v[52:53], v[52:53]
	v_add_f32_e32 v0, v51, v0
	v_add_f32_e32 v0, v40, v0
	v_add_f32_e32 v0, v41, v0
	s_waitcnt lgkmcnt(0)
	s_nop 1
	v_add_f32_dpp v0, v0, v0 quad_perm:[1,0,3,2] row_mask:0xf bank_mask:0xf
	s_waitcnt lgkmcnt(0)
	s_nop 1
	v_add_f32_dpp v0, v0, v0 quad_perm:[2,3,0,1] row_mask:0xf bank_mask:0xf
	s_waitcnt lgkmcnt(0)
	s_nop 1
	v_add_f32_dpp v0, v0, v0 row_ror:4 row_mask:0xf bank_mask:0xf
	s_waitcnt lgkmcnt(0)
	s_nop 1
	v_add_f32_dpp v0, v0, v0 row_ror:8 row_mask:0xf bank_mask:0xf
	v_fmamk_f32 v0, v0, 0x3c2aaaab, v148
	v_mul_f32_e32 v38, 0x4b800000, v0
	v_cmp_gt_f32_e64 s[0:1], s2, v0
	s_nop 1
	v_cndmask_b32_e64 v0, v0, v38, s[0:1]
	v_rsq_f32_e32 v0, v0
	s_nop 0
	v_mul_f32_e32 v38, 0x45800000, v0
	v_cndmask_b32_e64 v0, v0, v38, s[0:1]
	v_pk_mul_f32 v[38:39], v[72:73], v[0:1] op_sel_hi:[1,0]
	v_pk_mul_f32 v[40:41], v[74:75], v[0:1] op_sel_hi:[1,0]
	v_pk_mul_f32 v[44:45], v[76:77], v[0:1] op_sel_hi:[1,0]
	v_pk_mul_f32 v[50:51], v[78:79], v[0:1] op_sel_hi:[1,0]
	v_pk_mul_f32 v[38:39], v[42:43], v[38:39]
	v_pk_mul_f32 v[40:41], v[46:47], v[40:41]
	v_pk_mul_f32 v[42:43], v[48:49], v[44:45]
	v_pk_mul_f32 v[44:45], v[52:53], v[50:51]
	ds_bpermute_b32 v52, v71, v38
	ds_bpermute_b32 v53, v71, v39
	ds_bpermute_b32 v50, v71, v40
	ds_bpermute_b32 v51, v71, v41
	ds_bpermute_b32 v48, v71, v42
	ds_bpermute_b32 v49, v71, v43
	ds_bpermute_b32 v46, v71, v44
	ds_bpermute_b32 v47, v71, v45
	v_or_b32_e32 v0, 24, v81
	s_and_saveexec_b64 s[0:1], s[26:27]
	s_cbranch_execz .LBB0_878
	v_lshlrev_b32_e32 v54, 6, v0
	v_cndmask_b32_e64 v54, v54, v67, s[44:45]
	v_add_u32_e32 v64, 0, v54
	ds_read_b128 v[54:57], v64
	ds_read_b128 v[58:61], v64 offset:16
	ds_read_b128 v[96:99], v64 offset:32
	ds_read_b128 v[100:103], v64 offset:48
	s_waitcnt lgkmcnt(3)
	v_mov_b32_e32 v64, v55
	v_mov_b32_e32 v65, v57
	v_pk_mul_f32 v[52:53], v[64:65], v[52:53]
	v_mov_b32_e32 v55, v56
	v_cndmask_b32_e64 v53, v53, -v53, s[42:43]
	v_cndmask_b32_e64 v52, v52, -v52, s[42:43]
	v_pk_fma_f32 v[38:39], v[38:39], v[54:55], v[52:53]
	s_waitcnt lgkmcnt(2)
	v_mov_b32_e32 v52, v59
	v_mov_b32_e32 v53, v61
	v_pk_mul_f32 v[50:51], v[52:53], v[50:51]
	v_mov_b32_e32 v59, v60
	v_cndmask_b32_e64 v51, v51, -v51, s[42:43]
	v_cndmask_b32_e64 v50, v50, -v50, s[42:43]
	v_pk_fma_f32 v[40:41], v[40:41], v[58:59], v[50:51]
	s_waitcnt lgkmcnt(1)
	v_mov_b32_e32 v50, v97
	v_mov_b32_e32 v51, v99
	v_pk_mul_f32 v[48:49], v[50:51], v[48:49]
	v_mov_b32_e32 v97, v98
	v_cndmask_b32_e64 v49, v49, -v49, s[42:43]
	v_cndmask_b32_e64 v48, v48, -v48, s[42:43]
	v_pk_fma_f32 v[42:43], v[42:43], v[96:97], v[48:49]
	s_waitcnt lgkmcnt(0)
	v_mov_b32_e32 v48, v101
	v_mov_b32_e32 v49, v103
	v_pk_mul_f32 v[46:47], v[48:49], v[46:47]
	v_mov_b32_e32 v101, v102
	v_cndmask_b32_e64 v47, v47, -v47, s[42:43]
	v_cndmask_b32_e64 v46, v46, -v46, s[42:43]
	v_pk_fma_f32 v[44:45], v[44:45], v[100:101], v[46:47]

; template <int NCH, bool ROPE>
; DI void norm_rows16(int lane, size_t row0, bool is_ctx, int t0, const bf16_t* srcA, size_t ldA, int nA, const bf16_t* srcB, size_t ldB,
;                     const float* st, int st_idx, const float* gain, float inv_n, bf16_t* dst, size_t ldd, const float* tab) {
;     ...
;   for (int it = 0; it < 16; ++it) {
;     const int tk = it * 4 + tq;
;     const size_t row = row0 + tk;
;     const u32x4 u = ua[it];
;     const float pre = prea[it];
;     float f[8];
;     unpack8(u, f);
;     float ss = 0.f;
; #pragma unroll
;     for (int j = 0; j < 8; ++j) { f[j] *= pre; ss += f[j] * f[j]; }
;     ss += __shfl_xor(ss, 1); ss += __shfl_xor(ss, 2); ss += __shfl_xor(ss, 4); ss += __shfl_xor(ss, 8);
;     const float rs = rsqrtf(ss * inv_n + EPS);
; #pragma unroll
;     for (int j = 0; j < 8; ++j) f[j] *= rs * gv[j];
;     if (ROPE) {
;       float pf[8];
; #pragma unroll
;       for (int j = 0; j < 8; ++j) pf[j] = __shfl_xor(f[j], 1);
;       if (!is_ctx && sub >= 8 && sub < 12) {
;         const int pos = t0 + tk - CTXL;
;         const float* tr = (const float*)smem + ((sub < 10) ? (pos >> 6) : (pos & 63)) * 16;
; #pragma unroll
;         for (int j = 0; j < 8; ++j) {
;           const float c = tr[2 * j], sn = tr[2 * j + 1];
;           f[j] = (sub & 1) ? (pf[j] * sn + f[j] * c) : (f[j] * c - pf[j] * sn);
;         }
;       }
.LBB0_880:
	s_or_b64 exec, exec, s[0:1]
	s_nop 0
	v_lshlrev_b32_e32 v38, 16, v34
	v_and_b32_e32 v39, 0xffff0000, v34
	v_pk_mul_f32 v[38:39], v[94:95], v[38:39] op_sel_hi:[0,1]
	v_lshlrev_b32_e32 v34, 16, v35
	v_and_b32_e32 v35, 0xffff0000, v35
	v_pk_mul_f32 v[40:41], v[38:39], v[38:39]
	v_pk_mul_f32 v[42:43], v[94:95], v[34:35] op_sel_hi:[0,1]
	v_pk_mul_f32 v[34:35], v[42:43], v[42:43]
	v_lshlrev_b32_e32 v44, 16, v36
	v_and_b32_e32 v45, 0xffff0000, v36
	v_add_f32_e32 v0, v40, v41
	v_pk_mul_f32 v[44:45], v[94:95], v[44:45] op_sel_hi:[0,1]
	v_add_f32_e32 v0, v34, v0
	s_waitcnt lgkmcnt(0)
	v_pk_mul_f32 v[46:47], v[44:45], v[44:45]
	v_lshlrev_b32_e32 v36, 16, v37
	v_and_b32_e32 v37, 0xffff0000, v37
	v_add_f32_e32 v0, v35, v0
	v_pk_mul_f32 v[48:49], v[94:95], v[36:37] op_sel_hi:[0,1]
	v_add_f32_e32 v0, v46, v0
	v_pk_mul_f32 v[36:37], v[48:49], v[48:49]
	v_add_f32_e32 v0, v47, v0
	v_add_f32_e32 v0, v36, v0
	v_add_f32_e32 v0, v37, v0
	s_waitcnt lgkmcnt(0)
	s_nop 1
	v_add_f32_dpp v0, v0, v0 quad_perm:[1,0,3,2] row_mask:0xf bank_mask:0xf
	s_waitcnt lgkmcnt(0)
	s_nop 1
	v_add_f32_dpp v0, v0, v0 quad_perm:[2,3,0,1] row_mask:0xf bank_mask:0xf
	s_waitcnt lgkmcnt(0)
	s_nop 1
	v_add_f32_dpp v0, v0, v0 row_ror:4 row_mask:0xf bank_mask:0xf
	s_waitcnt lgkmcnt(0)
	s_nop 1
	v_add_f32_dpp v0, v0, v0 row_ror:8 row_mask:0xf bank_mask:0xf
	v_fmamk_f32 v0, v0, 0x3c2aaaab, v148
	v_mul_f32_e32 v34, 0x4b800000, v0
	v_cmp_gt_f32_e64 s[0:1], s2, v0
	s_nop 1
	v_cndmask_b32_e64 v0, v0, v34, s[0:1]
	v_rsq_f32_e32 v0, v0
	s_nop 0
	v_mul_f32_e32 v34, 0x45800000, v0
	v_cndmask_b32_e64 v0, v0, v34, s[0:1]
	v_pk_mul_f32 v[34:35], v[72:73], v[0:1] op_sel_hi:[1,0]
	v_pk_mul_f32 v[36:37], v[74:75], v[0:1] op_sel_hi:[1,0]
	v_pk_mul_f32 v[40:41], v[76:77], v[0:1] op_sel_hi:[1,0]
	v_pk_mul_f32 v[46:47], v[78:79], v[0:1] op_sel_hi:[1,0]
	v_pk_mul_f32 v[34:35], v[38:39], v[34:35]
	v_pk_mul_f32 v[36:37], v[42:43], v[36:37]
	v_pk_mul_f32 v[38:39], v[44:45], v[40:41]
	v_pk_mul_f32 v[40:41], v[48:49], v[46:47]
	ds_bpermute_b32 v48, v71, v34
	ds_bpermute_b32 v49, v71, v35
	ds_bpermute_b32 v46, v71, v36
	ds_bpermute_b32 v47, v71, v37
	ds_bpermute_b32 v44, v71, v38
	ds_bpermute_b32 v45, v71, v39
	ds_bpermute_b32 v42, v71, v40
	ds_bpermute_b32 v43, v71, v41
	v_or_b32_e32 v0, 28, v81
	s_and_saveexec_b64 s[0:1], s[26:27]
	s_cbranch_execz .LBB0_882
	v_lshlrev_b32_e32 v50, 6, v0
	v_cndmask_b32_e64 v50, v50, v67, s[44:45]
	v_add_u32_e32 v64, 0, v50
	ds_read_b128 v[50:53], v64
	ds_read_b128 v[54:57], v64 offset:16
	ds_read_b128 v[58:61], v64 offset:32
	ds_read_b128 v[94:97], v64 offset:48
	s_waitcnt lgkmcnt(3)
	v_mov_b32_e32 v64, v51
	v_mov_b32_e32 v65, v53
	v_pk_mul_f32 v[48:49], v[64:65], v[48:49]
	v_mov_b32_e32 v51, v52
	v_cndmask_b32_e64 v49, v49, -v49, s[42:43]
	v_cndmask_b32_e64 v48, v48, -v48, s[42:43]
	v_pk_fma_f32 v[34:35], v[34:35], v[50:51], v[48:49]
	s_waitcnt lgkmcnt(2)
	v_mov_b32_e32 v48, v55
	v_mov_b32_e32 v49, v57
	v_pk_mul_f32 v[46:47], v[48:49], v[46:47]
	v_mov_b32_e32 v55, v56
	v_cndmask_b32_e64 v47, v47, -v47, s[42:43]
	v_cndmask_b32_e64 v46, v46, -v46, s[42:43]
	v_pk_fma_f32 v[36:37], v[36:37], v[54:55], v[46:47]
	s_waitcnt lgkmcnt(1)
	v_mov_b32_e32 v46, v59
	v_mov_b32_e32 v47, v61
	v_pk_mul_f32 v[44:45], v[46:47], v[44:45]
	v_mov_b32_e32 v59, v60
	v_cndmask_b32_e64 v45, v45, -v45, s[42:43]
	v_cndmask_b32_e64 v44, v44, -v44, s[42:43]
	v_pk_fma_f32 v[38:39], v[38:39], v[58:59], v[44:45]
	s_waitcnt lgkmcnt(0)
	v_mov_b32_e32 v44, v95
	v_mov_b32_e32 v45, v97
	v_pk_mul_f32 v[42:43], v[44:45], v[42:43]
	v_mov_b32_e32 v95, v96
	v_cndmask_b32_e64 v43, v43, -v43, s[42:43]
	v_cndmask_b32_e64 v42, v42, -v42, s[42:43]
	v_pk_fma_f32 v[40:41], v[40:41], v[94:95], v[42:43]

; template <int NCH, bool ROPE>
; DI void norm_rows16(int lane, size_t row0, bool is_ctx, int t0, const bf16_t* srcA, size_t ldA, int nA, const bf16_t* srcB, size_t ldB,
;                     const float* st, int st_idx, const float* gain, float inv_n, bf16_t* dst, size_t ldd, const float* tab) {
;     ...
;   for (int it = 0; it < 16; ++it) {
;     const int tk = it * 4 + tq;
;     const size_t row = row0 + tk;
;     const u32x4 u = ua[it];
;     const float pre = prea[it];
;     float f[8];
;     unpack8(u, f);
;     float ss = 0.f;
; #pragma unroll
;     for (int j = 0; j < 8; ++j) { f[j] *= pre; ss += f[j] * f[j]; }
;     ss += __shfl_xor(ss, 1); ss += __shfl_xor(ss, 2); ss += __shfl_xor(ss, 4); ss += __shfl_xor(ss, 8);
;     const float rs = rsqrtf(ss * inv_n + EPS);
; #pragma unroll
;     for (int j = 0; j < 8; ++j) f[j] *= rs * gv[j];
;     if (ROPE) {
;       float pf[8];
; #pragma unroll
;       for (int j = 0; j < 8; ++j) pf[j] = __shfl_xor(f[j], 1);
;       if (!is_ctx && sub >= 8 && sub < 12) {
;         const int pos = t0 + tk - CTXL;
;         const float* tr = (const float*)smem + ((sub < 10) ? (pos >> 6) : (pos & 63)) * 16;
; #pragma unroll
;         for (int j = 0; j < 8; ++j) {
;           const float c = tr[2 * j], sn = tr[2 * j + 1];
;           f[j] = (sub & 1) ? (pf[j] * sn + f[j] * c) : (f[j] * c - pf[j] * sn);
;         }
;       }
.LBB0_884:
	s_or_b64 exec, exec, s[0:1]
	s_nop 0
	v_lshlrev_b32_e32 v34, 16, v30
	v_and_b32_e32 v35, 0xffff0000, v30
	v_pk_mul_f32 v[34:35], v[92:93], v[34:35] op_sel_hi:[0,1]
	v_lshlrev_b32_e32 v30, 16, v31
	v_and_b32_e32 v31, 0xffff0000, v31
	v_pk_mul_f32 v[36:37], v[34:35], v[34:35]
	v_pk_mul_f32 v[38:39], v[92:93], v[30:31] op_sel_hi:[0,1]
	v_pk_mul_f32 v[30:31], v[38:39], v[38:39]
	v_lshlrev_b32_e32 v40, 16, v32
	v_and_b32_e32 v41, 0xffff0000, v32
	v_add_f32_e32 v0, v36, v37
	v_pk_mul_f32 v[40:41], v[92:93], v[40:41] op_sel_hi:[0,1]
	v_add_f32_e32 v0, v30, v0
	s_waitcnt lgkmcnt(0)
	v_pk_mul_f32 v[42:43], v[40:41], v[40:41]
	v_lshlrev_b32_e32 v32, 16, v33
	v_and_b32_e32 v33, 0xffff0000, v33
	v_add_f32_e32 v0, v31, v0
	v_pk_mul_f32 v[44:45], v[92:93], v[32:33] op_sel_hi:[0,1]
	v_add_f32_e32 v0, v42, v0
	v_pk_mul_f32 v[32:33], v[44:45], v[44:45]
	v_add_f32_e32 v0, v43, v0
	v_add_f32_e32 v0, v32, v0
	v_add_f32_e32 v0, v33, v0
	s_waitcnt lgkmcnt(0)
	s_nop 1
	v_add_f32_dpp v0, v0, v0 quad_perm:[1,0,3,2] row_mask:0xf bank_mask:0xf
	s_waitcnt lgkmcnt(0)
	s_nop 1
	v_add_f32_dpp v0, v0, v0 quad_perm:[2,3,0,1] row_mask:0xf bank_mask:0xf
	s_waitcnt lgkmcnt(0)
	s_nop 1
	v_add_f32_dpp v0, v0, v0 row_ror:4 row_mask:0xf bank_mask:0xf
	s_waitcnt lgkmcnt(0)
	s_nop 1
	v_add_f32_dpp v0, v0, v0 row_ror:8 row_mask:0xf bank_mask:0xf
	v_fmamk_f32 v0, v0, 0x3c2aaaab, v148
	v_mul_f32_e32 v30, 0x4b800000, v0
	v_cmp_gt_f32_e64 s[0:1], s2, v0
	s_nop 1
	v_cndmask_b32_e64 v0, v0, v30, s[0:1]
	v_rsq_f32_e32 v0, v0
	s_nop 0
	v_mul_f32_e32 v30, 0x45800000, v0
	v_cndmask_b32_e64 v0, v0, v30, s[0:1]
	v_pk_mul_f32 v[30:31], v[72:73], v[0:1] op_sel_hi:[1,0]
	v_pk_mul_f32 v[32:33], v[74:75], v[0:1] op_sel_hi:[1,0]
	v_pk_mul_f32 v[36:37], v[76:77], v[0:1] op_sel_hi:[1,0]
	v_pk_mul_f32 v[42:43], v[78:79], v[0:1] op_sel_hi:[1,0]
	v_pk_mul_f32 v[30:31], v[34:35], v[30:31]
	v_pk_mul_f32 v[32:33], v[38:39], v[32:33]
	v_pk_mul_f32 v[34:35], v[40:41], v[36:37]
	v_pk_mul_f32 v[36:37], v[44:45], v[42:43]
	ds_bpermute_b32 v44, v71, v30
	ds_bpermute_b32 v45, v71, v31
	ds_bpermute_b32 v42, v71, v32
	ds_bpermute_b32 v43, v71, v33
	ds_bpermute_b32 v40, v71, v34
	ds_bpermute_b32 v41, v71, v35
	ds_bpermute_b32 v38, v71, v36
	ds_bpermute_b32 v39, v71, v37
	v_or_b32_e32 v0, 32, v81
	s_and_saveexec_b64 s[0:1], s[26:27]
	s_cbranch_execz .LBB0_886
	v_lshlrev_b32_e32 v46, 6, v0
	v_cndmask_b32_e64 v46, v46, v67, s[44:45]
	v_add_u32_e32 v58, 0, v46
	ds_read_b128 v[46:49], v58
	ds_read_b128 v[50:53], v58 offset:16
	ds_read_b128 v[54:57], v58 offset:32
	ds_read_b128 v[58:61], v58 offset:48
	s_waitcnt lgkmcnt(3)
	v_mov_b32_e32 v64, v47
	v_mov_b32_e32 v65, v49
	v_pk_mul_f32 v[44:45], v[64:65], v[44:45]
	v_mov_b32_e32 v47, v48
	v_cndmask_b32_e64 v45, v45, -v45, s[42:43]
	v_cndmask_b32_e64 v44, v44, -v44, s[42:43]
	v_pk_fma_f32 v[30:31], v[30:31], v[46:47], v[44:45]
	s_waitcnt lgkmcnt(2)
	v_mov_b32_e32 v44, v51
	v_mov_b32_e32 v45, v53
	v_pk_mul_f32 v[42:43], v[44:45], v[42:43]
	v_mov_b32_e32 v51, v52
	v_cndmask_b32_e64 v43, v43, -v43, s[42:43]
	v_cndmask_b32_e64 v42, v42, -v42, s[42:43]
	v_pk_fma_f32 v[32:33], v[32:33], v[50:51], v[42:43]
	s_waitcnt lgkmcnt(1)
	v_mov_b32_e32 v42, v55
	v_mov_b32_e32 v43, v57
	v_pk_mul_f32 v[40:41], v[42:43], v[40:41]
	v_mov_b32_e32 v55, v56
	v_cndmask_b32_e64 v41, v41, -v41, s[42:43]
	v_cndmask_b32_e64 v40, v40, -v40, s[42:43]
	v_pk_fma_f32 v[34:35], v[34:35], v[54:55], v[40:41]
	s_waitcnt lgkmcnt(0)
	v_mov_b32_e32 v40, v59
	v_mov_b32_e32 v41, v61
	v_pk_mul_f32 v[38:39], v[40:41], v[38:39]
	v_mov_b32_e32 v59, v60
	v_cndmask_b32_e64 v39, v39, -v39, s[42:43]
	v_cndmask_b32_e64 v38, v38, -v38, s[42:43]
	v_pk_fma_f32 v[36:37], v[36:37], v[58:59], v[38:39]

; template <int NCH, bool ROPE>
; DI void norm_rows16(int lane, size_t row0, bool is_ctx, int t0, const bf16_t* srcA, size_t ldA, int nA, const bf16_t* srcB, size_t ldB,
;                     const float* st, int st_idx, const float* gain, float inv_n, bf16_t* dst, size_t ldd, const float* tab) {
;     ...
;   for (int it = 0; it < 16; ++it) {
;     const int tk = it * 4 + tq;
;     const size_t row = row0 + tk;
;     const u32x4 u = ua[it];
;     const float pre = prea[it];
;     float f[8];
;     unpack8(u, f);
;     float ss = 0.f;
; #pragma unroll
;     for (int j = 0; j < 8; ++j) { f[j] *= pre; ss += f[j] * f[j]; }
;     ss += __shfl_xor(ss, 1); ss += __shfl_xor(ss, 2); ss += __shfl_xor(ss, 4); ss += __shfl_xor(ss, 8);
;     const float rs = rsqrtf(ss * inv_n + EPS);
; #pragma unroll
;     for (int j = 0; j < 8; ++j) f[j] *= rs * gv[j];
;     if (ROPE) {
;       float pf[8];
; #pragma unroll
;       for (int j = 0; j < 8; ++j) pf[j] = __shfl_xor(f[j], 1);
;       if (!is_ctx && sub >= 8 && sub < 12) {
;         const int pos = t0 + tk - CTXL;
;         const float* tr = (const float*)smem + ((sub < 10) ? (pos >> 6) : (pos & 63)) * 16;
; #pragma unroll
;         for (int j = 0; j < 8; ++j) {
;           const float c = tr[2 * j], sn = tr[2 * j + 1];
;           f[j] = (sub & 1) ? (pf[j] * sn + f[j] * c) : (f[j] * c - pf[j] * sn);
;         }
;       }
.LBB0_888:
	s_or_b64 exec, exec, s[0:1]
	s_nop 0
	v_lshlrev_b32_e32 v30, 16, v26
	v_and_b32_e32 v31, 0xffff0000, v26
	v_pk_mul_f32 v[30:31], v[90:91], v[30:31] op_sel_hi:[0,1]
	v_lshlrev_b32_e32 v26, 16, v27
	v_and_b32_e32 v27, 0xffff0000, v27
	v_pk_mul_f32 v[32:33], v[30:31], v[30:31]
	v_pk_mul_f32 v[34:35], v[90:91], v[26:27] op_sel_hi:[0,1]
	v_pk_mul_f32 v[26:27], v[34:35], v[34:35]
	v_lshlrev_b32_e32 v36, 16, v28
	v_and_b32_e32 v37, 0xffff0000, v28
	v_add_f32_e32 v0, v32, v33
	v_pk_mul_f32 v[36:37], v[90:91], v[36:37] op_sel_hi:[0,1]
	v_add_f32_e32 v0, v26, v0
	s_waitcnt lgkmcnt(0)
	v_pk_mul_f32 v[38:39], v[36:37], v[36:37]
	v_lshlrev_b32_e32 v28, 16, v29
	v_and_b32_e32 v29, 0xffff0000, v29
	v_add_f32_e32 v0, v27, v0
	v_pk_mul_f32 v[40:41], v[90:91], v[28:29] op_sel_hi:[0,1]
	v_add_f32_e32 v0, v38, v0
	v_pk_mul_f32 v[28:29], v[40:41], v[40:41]
	v_add_f32_e32 v0, v39, v0
	v_add_f32_e32 v0, v28, v0
	v_add_f32_e32 v0, v29, v0
	s_waitcnt lgkmcnt(0)
	s_nop 1
	v_add_f32_dpp v0, v0, v0 quad_perm:[1,0,3,2] row_mask:0xf bank_mask:0xf
	s_waitcnt lgkmcnt(0)
	s_nop 1
	v_add_f32_dpp v0, v0, v0 quad_perm:[2,3,0,1] row_mask:0xf bank_mask:0xf
	s_waitcnt lgkmcnt(0)
	s_nop 1
	v_add_f32_dpp v0, v0, v0 row_ror:4 row_mask:0xf bank_mask:0xf
	s_waitcnt lgkmcnt(0)
	s_nop 1
	v_add_f32_dpp v0, v0, v0 row_ror:8 row_mask:0xf bank_mask:0xf
	v_fmamk_f32 v0, v0, 0x3c2aaaab, v148
	v_mul_f32_e32 v26, 0x4b800000, v0
	v_cmp_gt_f32_e64 s[0:1], s2, v0
	s_nop 1
	v_cndmask_b32_e64 v0, v0, v26, s[0:1]
	v_rsq_f32_e32 v0, v0
	s_nop 0
	v_mul_f32_e32 v26, 0x45800000, v0
	v_cndmask_b32_e64 v0, v0, v26, s[0:1]
	v_pk_mul_f32 v[26:27], v[72:73], v[0:1] op_sel_hi:[1,0]
	v_pk_mul_f32 v[28:29], v[74:75], v[0:1] op_sel_hi:[1,0]
	v_pk_mul_f32 v[32:33], v[76:77], v[0:1] op_sel_hi:[1,0]
	v_pk_mul_f32 v[38:39], v[78:79], v[0:1] op_sel_hi:[1,0]
	v_pk_mul_f32 v[26:27], v[30:31], v[26:27]
	v_pk_mul_f32 v[28:29], v[34:35], v[28:29]
	v_pk_mul_f32 v[30:31], v[36:37], v[32:33]
	v_pk_mul_f32 v[32:33], v[40:41], v[38:39]
	ds_bpermute_b32 v40, v71, v26
	ds_bpermute_b32 v41, v71, v27
	ds_bpermute_b32 v38, v71, v28
	ds_bpermute_b32 v39, v71, v29
	ds_bpermute_b32 v36, v71, v30
	ds_bpermute_b32 v37, v71, v31
	ds_bpermute_b32 v34, v71, v32
	ds_bpermute_b32 v35, v71, v33
	v_or_b32_e32 v0, 36, v81
	s_and_saveexec_b64 s[0:1], s[26:27]
	s_cbranch_execz .LBB0_890
	v_lshlrev_b32_e32 v42, 6, v0
	v_cndmask_b32_e64 v42, v42, v67, s[44:45]
	v_add_u32_e32 v54, 0, v42
	ds_read_b128 v[42:45], v54
	ds_read_b128 v[46:49], v54 offset:16
	ds_read_b128 v[50:53], v54 offset:32
	ds_read_b128 v[54:57], v54 offset:48
	s_waitcnt lgkmcnt(3)
	v_mov_b32_e32 v58, v43
	v_mov_b32_e32 v59, v45
	v_pk_mul_f32 v[40:41], v[58:59], v[40:41]
	v_mov_b32_e32 v43, v44
	v_cndmask_b32_e64 v41, v41, -v41, s[42:43]
	v_cndmask_b32_e64 v40, v40, -v40, s[42:43]
	v_pk_fma_f32 v[26:27], v[26:27], v[42:43], v[40:41]
	s_waitcnt lgkmcnt(2)
	v_mov_b32_e32 v40, v47
	v_mov_b32_e32 v41, v49
	v_pk_mul_f32 v[38:39], v[40:41], v[38:39]
	v_mov_b32_e32 v47, v48
	v_cndmask_b32_e64 v39, v39, -v39, s[42:43]
	v_cndmask_b32_e64 v38, v38, -v38, s[42:43]
	v_pk_fma_f32 v[28:29], v[28:29], v[46:47], v[38:39]
	s_waitcnt lgkmcnt(1)
	v_mov_b32_e32 v38, v51
	v_mov_b32_e32 v39, v53
	v_pk_mul_f32 v[36:37], v[38:39], v[36:37]
	v_mov_b32_e32 v51, v52
	v_cndmask_b32_e64 v37, v37, -v37, s[42:43]
	v_cndmask_b32_e64 v36, v36, -v36, s[42:43]
	v_pk_fma_f32 v[30:31], v[30:31], v[50:51], v[36:37]
	s_waitcnt lgkmcnt(0)
	v_mov_b32_e32 v36, v55
	v_mov_b32_e32 v37, v57
	v_pk_mul_f32 v[34:35], v[36:37], v[34:35]
	v_mov_b32_e32 v55, v56
	v_cndmask_b32_e64 v35, v35, -v35, s[42:43]
	v_cndmask_b32_e64 v34, v34, -v34, s[42:43]
	v_pk_fma_f32 v[32:33], v[32:33], v[54:55], v[34:35]

; template <int NCH, bool ROPE>
; DI void norm_rows16(int lane, size_t row0, bool is_ctx, int t0, const bf16_t* srcA, size_t ldA, int nA, const bf16_t* srcB, size_t ldB,
;                     const float* st, int st_idx, const float* gain, float inv_n, bf16_t* dst, size_t ldd, const float* tab) {
;     ...
;   for (int it = 0; it < 16; ++it) {
;     const int tk = it * 4 + tq;
;     const size_t row = row0 + tk;
;     const u32x4 u = ua[it];
;     const float pre = prea[it];
;     float f[8];
;     unpack8(u, f);
;     float ss = 0.f;
; #pragma unroll
;     for (int j = 0; j < 8; ++j) { f[j] *= pre; ss += f[j] * f[j]; }
;     ss += __shfl_xor(ss, 1); ss += __shfl_xor(ss, 2); ss += __shfl_xor(ss, 4); ss += __shfl_xor(ss, 8);
;     const float rs = rsqrtf(ss * inv_n + EPS);
; #pragma unroll
;     for (int j = 0; j < 8; ++j) f[j] *= rs * gv[j];
;     if (ROPE) {
;       float pf[8];
; #pragma unroll
;       for (int j = 0; j < 8; ++j) pf[j] = __shfl_xor(f[j], 1);
;       if (!is_ctx && sub >= 8 && sub < 12) {
;         const int pos = t0 + tk - CTXL;
;         const float* tr = (const float*)smem + ((sub < 10) ? (pos >> 6) : (pos & 63)) * 16;
; #pragma unroll
;         for (int j = 0; j < 8; ++j) {
;           const float c = tr[2 * j], sn = tr[2 * j + 1];
;           f[j] = (sub & 1) ? (pf[j] * sn + f[j] * c) : (f[j] * c - pf[j] * sn);
;         }
;       }
.LBB0_892:
	s_or_b64 exec, exec, s[0:1]
	s_nop 0
	v_lshlrev_b32_e32 v26, 16, v22
	v_and_b32_e32 v27, 0xffff0000, v22
	v_pk_mul_f32 v[26:27], v[88:89], v[26:27] op_sel_hi:[0,1]
	v_lshlrev_b32_e32 v22, 16, v23
	v_and_b32_e32 v23, 0xffff0000, v23
	v_pk_mul_f32 v[28:29], v[26:27], v[26:27]
	v_pk_mul_f32 v[30:31], v[88:89], v[22:23] op_sel_hi:[0,1]
	v_pk_mul_f32 v[22:23], v[30:31], v[30:31]
	v_lshlrev_b32_e32 v32, 16, v24
	v_and_b32_e32 v33, 0xffff0000, v24
	v_add_f32_e32 v0, v28, v29
	v_pk_mul_f32 v[32:33], v[88:89], v[32:33] op_sel_hi:[0,1]
	v_add_f32_e32 v0, v22, v0
	s_waitcnt lgkmcnt(0)
	v_pk_mul_f32 v[34:35], v[32:33], v[32:33]
	v_lshlrev_b32_e32 v24, 16, v25
	v_and_b32_e32 v25, 0xffff0000, v25
	v_add_f32_e32 v0, v23, v0
	v_pk_mul_f32 v[36:37], v[88:89], v[24:25] op_sel_hi:[0,1]
	v_add_f32_e32 v0, v34, v0
	v_pk_mul_f32 v[24:25], v[36:37], v[36:37]
	v_add_f32_e32 v0, v35, v0
	v_add_f32_e32 v0, v24, v0
	v_add_f32_e32 v0, v25, v0
	s_waitcnt lgkmcnt(0)
	s_nop 1
	v_add_f32_dpp v0, v0, v0 quad_perm:[1,0,3,2] row_mask:0xf bank_mask:0xf
	s_waitcnt lgkmcnt(0)
	s_nop 1
	v_add_f32_dpp v0, v0, v0 quad_perm:[2,3,0,1] row_mask:0xf bank_mask:0xf
	s_waitcnt lgkmcnt(0)
	s_nop 1
	v_add_f32_dpp v0, v0, v0 row_ror:4 row_mask:0xf bank_mask:0xf
	s_waitcnt lgkmcnt(0)
	s_nop 1
	v_add_f32_dpp v0, v0, v0 row_ror:8 row_mask:0xf bank_mask:0xf
	v_fmamk_f32 v0, v0, 0x3c2aaaab, v148
	v_mul_f32_e32 v22, 0x4b800000, v0
	v_cmp_gt_f32_e64 s[0:1], s2, v0
	s_nop 1
	v_cndmask_b32_e64 v0, v0, v22, s[0:1]
	v_rsq_f32_e32 v0, v0
	s_nop 0
	v_mul_f32_e32 v22, 0x45800000, v0
	v_cndmask_b32_e64 v0, v0, v22, s[0:1]
	v_pk_mul_f32 v[22:23], v[72:73], v[0:1] op_sel_hi:[1,0]
	v_pk_mul_f32 v[24:25], v[74:75], v[0:1] op_sel_hi:[1,0]
	v_pk_mul_f32 v[28:29], v[76:77], v[0:1] op_sel_hi:[1,0]
	v_pk_mul_f32 v[34:35], v[78:79], v[0:1] op_sel_hi:[1,0]
	v_pk_mul_f32 v[22:23], v[26:27], v[22:23]
	v_pk_mul_f32 v[24:25], v[30:31], v[24:25]
	v_pk_mul_f32 v[26:27], v[32:33], v[28:29]
	v_pk_mul_f32 v[28:29], v[36:37], v[34:35]
	ds_bpermute_b32 v36, v71, v22
	ds_bpermute_b32 v37, v71, v23
	ds_bpermute_b32 v34, v71, v24
	ds_bpermute_b32 v35, v71, v25
	ds_bpermute_b32 v32, v71, v26
	ds_bpermute_b32 v33, v71, v27
	ds_bpermute_b32 v30, v71, v28
	ds_bpermute_b32 v31, v71, v29
	v_or_b32_e32 v0, 40, v81
	s_and_saveexec_b64 s[0:1], s[26:27]
	s_cbranch_execz .LBB0_894
	v_lshlrev_b32_e32 v38, 6, v0
	v_cndmask_b32_e64 v38, v38, v67, s[44:45]
	v_add_u32_e32 v50, 0, v38
	ds_read_b128 v[38:41], v50
	ds_read_b128 v[42:45], v50 offset:16
	ds_read_b128 v[46:49], v50 offset:32
	ds_read_b128 v[50:53], v50 offset:48
	s_waitcnt lgkmcnt(3)
	v_mov_b32_e32 v54, v39
	v_mov_b32_e32 v55, v41
	v_pk_mul_f32 v[36:37], v[54:55], v[36:37]
	v_mov_b32_e32 v39, v40
	v_cndmask_b32_e64 v37, v37, -v37, s[42:43]
	v_cndmask_b32_e64 v36, v36, -v36, s[42:43]
	v_pk_fma_f32 v[22:23], v[22:23], v[38:39], v[36:37]
	s_waitcnt lgkmcnt(2)
	v_mov_b32_e32 v36, v43
	v_mov_b32_e32 v37, v45
	v_pk_mul_f32 v[34:35], v[36:37], v[34:35]
	v_mov_b32_e32 v43, v44
	v_cndmask_b32_e64 v35, v35, -v35, s[42:43]
	v_cndmask_b32_e64 v34, v34, -v34, s[42:43]
	v_pk_fma_f32 v[24:25], v[24:25], v[42:43], v[34:35]
	s_waitcnt lgkmcnt(1)
	v_mov_b32_e32 v34, v47
	v_mov_b32_e32 v35, v49
	v_pk_mul_f32 v[32:33], v[34:35], v[32:33]
	v_mov_b32_e32 v47, v48
	v_cndmask_b32_e64 v33, v33, -v33, s[42:43]
	v_cndmask_b32_e64 v32, v32, -v32, s[42:43]
	v_pk_fma_f32 v[26:27], v[26:27], v[46:47], v[32:33]
	s_waitcnt lgkmcnt(0)
	v_mov_b32_e32 v32, v51
	v_mov_b32_e32 v33, v53
	v_pk_mul_f32 v[30:31], v[32:33], v[30:31]
	v_mov_b32_e32 v51, v52
	v_cndmask_b32_e64 v31, v31, -v31, s[42:43]
	v_cndmask_b32_e64 v30, v30, -v30, s[42:43]
	v_pk_fma_f32 v[28:29], v[28:29], v[50:51], v[30:31]

; template <int NCH, bool ROPE>
; DI void norm_rows16(int lane, size_t row0, bool is_ctx, int t0, const bf16_t* srcA, size_t ldA, int nA, const bf16_t* srcB, size_t ldB,
;                     const float* st, int st_idx, const float* gain, float inv_n, bf16_t* dst, size_t ldd, const float* tab) {
;     ...
;   for (int it = 0; it < 16; ++it) {
;     const int tk = it * 4 + tq;
;     const size_t row = row0 + tk;
;     const u32x4 u = ua[it];
;     const float pre = prea[it];
;     float f[8];
;     unpack8(u, f);
;     float ss = 0.f;
; #pragma unroll
;     for (int j = 0; j < 8; ++j) { f[j] *= pre; ss += f[j] * f[j]; }
;     ss += __shfl_xor(ss, 1); ss += __shfl_xor(ss, 2); ss += __shfl_xor(ss, 4); ss += __shfl_xor(ss, 8);
;     const float rs = rsqrtf(ss * inv_n + EPS);
; #pragma unroll
;     for (int j = 0; j < 8; ++j) f[j] *= rs * gv[j];
;     if (ROPE) {
;       float pf[8];
; #pragma unroll
;       for (int j = 0; j < 8; ++j) pf[j] = __shfl_xor(f[j], 1);
;       if (!is_ctx && sub >= 8 && sub < 12) {
;         const int pos = t0 + tk - CTXL;
;         const float* tr = (const float*)smem + ((sub < 10) ? (pos >> 6) : (pos & 63)) * 16;
; #pragma unroll
;         for (int j = 0; j < 8; ++j) {
;           const float c = tr[2 * j], sn = tr[2 * j + 1];
;           f[j] = (sub & 1) ? (pf[j] * sn + f[j] * c) : (f[j] * c - pf[j] * sn);
;         }
;       }
.LBB0_896:
	s_or_b64 exec, exec, s[0:1]
	s_nop 0
	v_lshlrev_b32_e32 v22, 16, v18
	v_and_b32_e32 v23, 0xffff0000, v18
	v_pk_mul_f32 v[22:23], v[86:87], v[22:23] op_sel_hi:[0,1]
	v_lshlrev_b32_e32 v18, 16, v19
	v_and_b32_e32 v19, 0xffff0000, v19
	v_pk_mul_f32 v[24:25], v[22:23], v[22:23]
	v_pk_mul_f32 v[26:27], v[86:87], v[18:19] op_sel_hi:[0,1]
	v_pk_mul_f32 v[18:19], v[26:27], v[26:27]
	v_lshlrev_b32_e32 v28, 16, v20
	v_and_b32_e32 v29, 0xffff0000, v20
	v_add_f32_e32 v0, v24, v25
	v_pk_mul_f32 v[28:29], v[86:87], v[28:29] op_sel_hi:[0,1]
	v_add_f32_e32 v0, v18, v0
	s_waitcnt lgkmcnt(0)
	v_pk_mul_f32 v[30:31], v[28:29], v[28:29]
	v_lshlrev_b32_e32 v20, 16, v21
	v_and_b32_e32 v21, 0xffff0000, v21
	v_add_f32_e32 v0, v19, v0
	v_pk_mul_f32 v[32:33], v[86:87], v[20:21] op_sel_hi:[0,1]
	v_add_f32_e32 v0, v30, v0
	v_pk_mul_f32 v[20:21], v[32:33], v[32:33]
	v_add_f32_e32 v0, v31, v0
	v_add_f32_e32 v0, v20, v0
	v_add_f32_e32 v0, v21, v0
	s_waitcnt lgkmcnt(0)
	s_nop 1
	v_add_f32_dpp v0, v0, v0 quad_perm:[1,0,3,2] row_mask:0xf bank_mask:0xf
	s_waitcnt lgkmcnt(0)
	s_nop 1
	v_add_f32_dpp v0, v0, v0 quad_perm:[2,3,0,1] row_mask:0xf bank_mask:0xf
	s_waitcnt lgkmcnt(0)
	s_nop 1
	v_add_f32_dpp v0, v0, v0 row_ror:4 row_mask:0xf bank_mask:0xf
	s_waitcnt lgkmcnt(0)
	s_nop 1
	v_add_f32_dpp v0, v0, v0 row_ror:8 row_mask:0xf bank_mask:0xf
	v_fmamk_f32 v0, v0, 0x3c2aaaab, v148
	v_mul_f32_e32 v18, 0x4b800000, v0
	v_cmp_gt_f32_e64 s[0:1], s2, v0
	s_nop 1
	v_cndmask_b32_e64 v0, v0, v18, s[0:1]
	v_rsq_f32_e32 v0, v0
	s_nop 0
	v_mul_f32_e32 v18, 0x45800000, v0
	v_cndmask_b32_e64 v0, v0, v18, s[0:1]
	v_pk_mul_f32 v[18:19], v[72:73], v[0:1] op_sel_hi:[1,0]
	v_pk_mul_f32 v[20:21], v[74:75], v[0:1] op_sel_hi:[1,0]
	v_pk_mul_f32 v[24:25], v[76:77], v[0:1] op_sel_hi:[1,0]
	v_pk_mul_f32 v[30:31], v[78:79], v[0:1] op_sel_hi:[1,0]
	v_pk_mul_f32 v[18:19], v[22:23], v[18:19]
	v_pk_mul_f32 v[20:21], v[26:27], v[20:21]
	v_pk_mul_f32 v[22:23], v[28:29], v[24:25]
	v_pk_mul_f32 v[24:25], v[32:33], v[30:31]
	ds_bpermute_b32 v32, v71, v18
	ds_bpermute_b32 v33, v71, v19
	ds_bpermute_b32 v30, v71, v20
	ds_bpermute_b32 v31, v71, v21
	ds_bpermute_b32 v28, v71, v22
	ds_bpermute_b32 v29, v71, v23
	ds_bpermute_b32 v26, v71, v24
	ds_bpermute_b32 v27, v71, v25
	v_or_b32_e32 v0, 44, v81
	s_and_saveexec_b64 s[0:1], s[26:27]
	s_cbranch_execz .LBB0_898
	v_lshlrev_b32_e32 v34, 6, v0
	v_cndmask_b32_e64 v34, v34, v67, s[44:45]
	v_add_u32_e32 v46, 0, v34
	ds_read_b128 v[34:37], v46
	ds_read_b128 v[38:41], v46 offset:16
	ds_read_b128 v[42:45], v46 offset:32
	ds_read_b128 v[46:49], v46 offset:48
	s_waitcnt lgkmcnt(3)
	v_mov_b32_e32 v50, v35
	v_mov_b32_e32 v51, v37
	v_pk_mul_f32 v[32:33], v[50:51], v[32:33]
	v_mov_b32_e32 v35, v36
	v_cndmask_b32_e64 v33, v33, -v33, s[42:43]
	v_cndmask_b32_e64 v32, v32, -v32, s[42:43]
	v_pk_fma_f32 v[18:19], v[18:19], v[34:35], v[32:33]
	s_waitcnt lgkmcnt(2)
	v_mov_b32_e32 v32, v39
	v_mov_b32_e32 v33, v41
	v_pk_mul_f32 v[30:31], v[32:33], v[30:31]
	v_mov_b32_e32 v39, v40
	v_cndmask_b32_e64 v31, v31, -v31, s[42:43]
	v_cndmask_b32_e64 v30, v30, -v30, s[42:43]
	v_pk_fma_f32 v[20:21], v[20:21], v[38:39], v[30:31]
	s_waitcnt lgkmcnt(1)
	v_mov_b32_e32 v30, v43
	v_mov_b32_e32 v31, v45
	v_pk_mul_f32 v[28:29], v[30:31], v[28:29]
	v_mov_b32_e32 v43, v44
	v_cndmask_b32_e64 v29, v29, -v29, s[42:43]
	v_cndmask_b32_e64 v28, v28, -v28, s[42:43]
	v_pk_fma_f32 v[22:23], v[22:23], v[42:43], v[28:29]
	s_waitcnt lgkmcnt(0)
	v_mov_b32_e32 v28, v47
	v_mov_b32_e32 v29, v49
	v_pk_mul_f32 v[26:27], v[28:29], v[26:27]
	v_mov_b32_e32 v47, v48
	v_cndmask_b32_e64 v27, v27, -v27, s[42:43]
	v_cndmask_b32_e64 v26, v26, -v26, s[42:43]
	v_pk_fma_f32 v[24:25], v[24:25], v[46:47], v[26:27]

; template <int NCH, bool ROPE>
; DI void norm_rows16(int lane, size_t row0, bool is_ctx, int t0, const bf16_t* srcA, size_t ldA, int nA, const bf16_t* srcB, size_t ldB,
;                     const float* st, int st_idx, const float* gain, float inv_n, bf16_t* dst, size_t ldd, const float* tab) {
;     ...
;   for (int it = 0; it < 16; ++it) {
;     const int tk = it * 4 + tq;
;     const size_t row = row0 + tk;
;     const u32x4 u = ua[it];
;     const float pre = prea[it];
;     float f[8];
;     unpack8(u, f);
;     float ss = 0.f;
; #pragma unroll
;     for (int j = 0; j < 8; ++j) { f[j] *= pre; ss += f[j] * f[j]; }
;     ss += __shfl_xor(ss, 1); ss += __shfl_xor(ss, 2); ss += __shfl_xor(ss, 4); ss += __shfl_xor(ss, 8);
;     const float rs = rsqrtf(ss * inv_n + EPS);
; #pragma unroll
;     for (int j = 0; j < 8; ++j) f[j] *= rs * gv[j];
;     if (ROPE) {
;       float pf[8];
; #pragma unroll
;       for (int j = 0; j < 8; ++j) pf[j] = __shfl_xor(f[j], 1);
;       if (!is_ctx && sub >= 8 && sub < 12) {
;         const int pos = t0 + tk - CTXL;
;         const float* tr = (const float*)smem + ((sub < 10) ? (pos >> 6) : (pos & 63)) * 16;
; #pragma unroll
;         for (int j = 0; j < 8; ++j) {
;           const float c = tr[2 * j], sn = tr[2 * j + 1];
;           f[j] = (sub & 1) ? (pf[j] * sn + f[j] * c) : (f[j] * c - pf[j] * sn);
;         }
;       }
.LBB0_900:
	s_or_b64 exec, exec, s[0:1]
	s_nop 0
	v_lshlrev_b32_e32 v18, 16, v14
	v_and_b32_e32 v19, 0xffff0000, v14
	v_pk_mul_f32 v[18:19], v[84:85], v[18:19] op_sel_hi:[0,1]
	v_lshlrev_b32_e32 v14, 16, v15
	v_and_b32_e32 v15, 0xffff0000, v15
	v_pk_mul_f32 v[20:21], v[18:19], v[18:19]
	v_pk_mul_f32 v[22:23], v[84:85], v[14:15] op_sel_hi:[0,1]
	v_pk_mul_f32 v[14:15], v[22:23], v[22:23]
	v_lshlrev_b32_e32 v24, 16, v16
	v_and_b32_e32 v25, 0xffff0000, v16
	v_add_f32_e32 v0, v20, v21
	v_pk_mul_f32 v[24:25], v[84:85], v[24:25] op_sel_hi:[0,1]
	v_add_f32_e32 v0, v14, v0
	s_waitcnt lgkmcnt(0)
	v_pk_mul_f32 v[26:27], v[24:25], v[24:25]
	v_lshlrev_b32_e32 v16, 16, v17
	v_and_b32_e32 v17, 0xffff0000, v17
	v_add_f32_e32 v0, v15, v0
	v_pk_mul_f32 v[28:29], v[84:85], v[16:17] op_sel_hi:[0,1]
	v_add_f32_e32 v0, v26, v0
	v_pk_mul_f32 v[16:17], v[28:29], v[28:29]
	v_add_f32_e32 v0, v27, v0
	v_add_f32_e32 v0, v16, v0
	v_add_f32_e32 v0, v17, v0
	s_waitcnt lgkmcnt(0)
	s_nop 1
	v_add_f32_dpp v0, v0, v0 quad_perm:[1,0,3,2] row_mask:0xf bank_mask:0xf
	s_waitcnt lgkmcnt(0)
	s_nop 1
	v_add_f32_dpp v0, v0, v0 quad_perm:[2,3,0,1] row_mask:0xf bank_mask:0xf
	s_waitcnt lgkmcnt(0)
	s_nop 1
	v_add_f32_dpp v0, v0, v0 row_ror:4 row_mask:0xf bank_mask:0xf
	s_waitcnt lgkmcnt(0)
	s_nop 1
	v_add_f32_dpp v0, v0, v0 row_ror:8 row_mask:0xf bank_mask:0xf
	v_fmamk_f32 v0, v0, 0x3c2aaaab, v148
	v_mul_f32_e32 v14, 0x4b800000, v0
	v_cmp_gt_f32_e64 s[0:1], s2, v0
	s_nop 1
	v_cndmask_b32_e64 v0, v0, v14, s[0:1]
	v_rsq_f32_e32 v0, v0
	s_nop 0
	v_mul_f32_e32 v14, 0x45800000, v0
	v_cndmask_b32_e64 v0, v0, v14, s[0:1]
	v_pk_mul_f32 v[14:15], v[72:73], v[0:1] op_sel_hi:[1,0]
	v_pk_mul_f32 v[16:17], v[74:75], v[0:1] op_sel_hi:[1,0]
	v_pk_mul_f32 v[20:21], v[76:77], v[0:1] op_sel_hi:[1,0]
	v_pk_mul_f32 v[26:27], v[78:79], v[0:1] op_sel_hi:[1,0]
	v_pk_mul_f32 v[14:15], v[18:19], v[14:15]
	v_pk_mul_f32 v[16:17], v[22:23], v[16:17]
	v_pk_mul_f32 v[18:19], v[24:25], v[20:21]
	v_pk_mul_f32 v[20:21], v[28:29], v[26:27]
	ds_bpermute_b32 v28, v71, v14
	ds_bpermute_b32 v29, v71, v15
	ds_bpermute_b32 v26, v71, v16
	ds_bpermute_b32 v27, v71, v17
	ds_bpermute_b32 v24, v71, v18
	ds_bpermute_b32 v25, v71, v19
	ds_bpermute_b32 v22, v71, v20
	ds_bpermute_b32 v23, v71, v21
	v_or_b32_e32 v0, 48, v81
	s_and_saveexec_b64 s[0:1], s[26:27]
	s_cbranch_execz .LBB0_902
	v_lshlrev_b32_e32 v30, 6, v0
	v_cndmask_b32_e64 v30, v30, v67, s[44:45]
	v_add_u32_e32 v42, 0, v30
	ds_read_b128 v[30:33], v42
	ds_read_b128 v[34:37], v42 offset:16
	ds_read_b128 v[38:41], v42 offset:32
	ds_read_b128 v[42:45], v42 offset:48
	s_waitcnt lgkmcnt(3)
	v_mov_b32_e32 v46, v31
	v_mov_b32_e32 v47, v33
	v_pk_mul_f32 v[28:29], v[46:47], v[28:29]
	v_mov_b32_e32 v31, v32
	v_cndmask_b32_e64 v29, v29, -v29, s[42:43]
	v_cndmask_b32_e64 v28, v28, -v28, s[42:43]
	v_pk_fma_f32 v[14:15], v[14:15], v[30:31], v[28:29]
	s_waitcnt lgkmcnt(2)
	v_mov_b32_e32 v28, v35
	v_mov_b32_e32 v29, v37
	v_pk_mul_f32 v[26:27], v[28:29], v[26:27]
	v_mov_b32_e32 v35, v36
	v_cndmask_b32_e64 v27, v27, -v27, s[42:43]
	v_cndmask_b32_e64 v26, v26, -v26, s[42:43]
	v_pk_fma_f32 v[16:17], v[16:17], v[34:35], v[26:27]
	s_waitcnt lgkmcnt(1)
	v_mov_b32_e32 v26, v39
	v_mov_b32_e32 v27, v41
	v_pk_mul_f32 v[24:25], v[26:27], v[24:25]
	v_mov_b32_e32 v39, v40
	v_cndmask_b32_e64 v25, v25, -v25, s[42:43]
	v_cndmask_b32_e64 v24, v24, -v24, s[42:43]
	v_pk_fma_f32 v[18:19], v[18:19], v[38:39], v[24:25]
	s_waitcnt lgkmcnt(0)
	v_mov_b32_e32 v24, v43
	v_mov_b32_e32 v25, v45
	v_pk_mul_f32 v[22:23], v[24:25], v[22:23]
	v_mov_b32_e32 v43, v44
	v_cndmask_b32_e64 v23, v23, -v23, s[42:43]
	v_cndmask_b32_e64 v22, v22, -v22, s[42:43]
	v_pk_fma_f32 v[20:21], v[20:21], v[42:43], v[22:23]

; template <int NCH, bool ROPE>
; DI void norm_rows16(int lane, size_t row0, bool is_ctx, int t0, const bf16_t* srcA, size_t ldA, int nA, const bf16_t* srcB, size_t ldB,
;                     const float* st, int st_idx, const float* gain, float inv_n, bf16_t* dst, size_t ldd, const float* tab) {
;     ...
;     unpack8(u, f);
;     float ss = 0.f;
; #pragma unroll
;     for (int j = 0; j < 8; ++j) { f[j] *= pre; ss += f[j] * f[j]; }
;     ss += __shfl_xor(ss, 1); ss += __shfl_xor(ss, 2); ss += __shfl_xor(ss, 4); ss += __shfl_xor(ss, 8);
;     const float rs = rsqrtf(ss * inv_n + EPS);
; #pragma unroll
;     for (int j = 0; j < 8; ++j) f[j] *= rs * gv[j];
;     if (ROPE) {
;       float pf[8];
; #pragma unroll
;       for (int j = 0; j < 8; ++j) pf[j] = __shfl_xor(f[j], 1);
;       if (!is_ctx && sub >= 8 && sub < 12) {
;         const int pos = t0 + tk - CTXL;
;         const float* tr = (const float*)smem + ((sub < 10) ? (pos >> 6) : (pos & 63)) * 16;
; #pragma unroll
;         for (int j = 0; j < 8; ++j) {
;           const float c = tr[2 * j], sn = tr[2 * j + 1];
;           f[j] = (sub & 1) ? (pf[j] * sn + f[j] * c) : (f[j] * c - pf[j] * sn);
.LBB0_904:
	s_or_b64 exec, exec, s[0:1]
	s_nop 0
	v_lshlrev_b32_e32 v14, 16, v10
	v_and_b32_e32 v15, 0xffff0000, v10
	v_pk_mul_f32 v[14:15], v[82:83], v[14:15] op_sel_hi:[0,1]
	v_lshlrev_b32_e32 v10, 16, v11
	v_and_b32_e32 v11, 0xffff0000, v11
	v_pk_mul_f32 v[16:17], v[14:15], v[14:15]
	v_pk_mul_f32 v[18:19], v[82:83], v[10:11] op_sel_hi:[0,1]
	v_pk_mul_f32 v[10:11], v[18:19], v[18:19]
	v_lshlrev_b32_e32 v20, 16, v12
	v_and_b32_e32 v21, 0xffff0000, v12
	v_add_f32_e32 v0, v16, v17
	v_pk_mul_f32 v[20:21], v[82:83], v[20:21] op_sel_hi:[0,1]
	v_add_f32_e32 v0, v10, v0
	s_waitcnt lgkmcnt(0)
	v_pk_mul_f32 v[22:23], v[20:21], v[20:21]
	v_lshlrev_b32_e32 v12, 16, v13
	v_and_b32_e32 v13, 0xffff0000, v13
	v_add_f32_e32 v0, v11, v0
	v_pk_mul_f32 v[24:25], v[82:83], v[12:13] op_sel_hi:[0,1]
	v_add_f32_e32 v0, v22, v0
	v_pk_mul_f32 v[12:13], v[24:25], v[24:25]
	v_add_f32_e32 v0, v23, v0
	v_add_f32_e32 v0, v12, v0
	v_add_f32_e32 v0, v13, v0
	s_waitcnt lgkmcnt(0)
	s_nop 1
	v_add_f32_dpp v0, v0, v0 quad_perm:[1,0,3,2] row_mask:0xf bank_mask:0xf
	s_waitcnt lgkmcnt(0)
	s_nop 1
	v_add_f32_dpp v0, v0, v0 quad_perm:[2,3,0,1] row_mask:0xf bank_mask:0xf
	s_waitcnt lgkmcnt(0)
	s_nop 1
	v_add_f32_dpp v0, v0, v0 row_ror:4 row_mask:0xf bank_mask:0xf
	s_waitcnt lgkmcnt(0)
	s_nop 1
	v_add_f32_dpp v0, v0, v0 row_ror:8 row_mask:0xf bank_mask:0xf
	v_fmamk_f32 v0, v0, 0x3c2aaaab, v148
	v_mul_f32_e32 v10, 0x4b800000, v0
	v_cmp_gt_f32_e64 s[0:1], s2, v0
	s_nop 1
	v_cndmask_b32_e64 v0, v0, v10, s[0:1]
	v_rsq_f32_e32 v0, v0
	s_nop 0
	v_mul_f32_e32 v10, 0x45800000, v0
	v_cndmask_b32_e64 v0, v0, v10, s[0:1]
	v_pk_mul_f32 v[10:11], v[72:73], v[0:1] op_sel_hi:[1,0]
	v_pk_mul_f32 v[12:13], v[74:75], v[0:1] op_sel_hi:[1,0]
	v_pk_mul_f32 v[16:17], v[76:77], v[0:1] op_sel_hi:[1,0]
	v_pk_mul_f32 v[22:23], v[78:79], v[0:1] op_sel_hi:[1,0]
	v_pk_mul_f32 v[10:11], v[14:15], v[10:11]
	v_pk_mul_f32 v[12:13], v[18:19], v[12:13]
	v_pk_mul_f32 v[14:15], v[20:21], v[16:17]
	v_pk_mul_f32 v[16:17], v[24:25], v[22:23]
	ds_bpermute_b32 v24, v71, v10
	ds_bpermute_b32 v25, v71, v11
	ds_bpermute_b32 v22, v71, v12
	ds_bpermute_b32 v23, v71, v13
	ds_bpermute_b32 v20, v71, v14
	ds_bpermute_b32 v21, v71, v15
	ds_bpermute_b32 v18, v71, v16
	ds_bpermute_b32 v19, v71, v17
	v_or_b32_e32 v0, 52, v81
	s_and_saveexec_b64 s[0:1], s[26:27]
	s_cbranch_execz .LBB0_906
	v_lshlrev_b32_e32 v26, 6, v0
	v_cndmask_b32_e64 v26, v26, v67, s[44:45]
	v_add_u32_e32 v38, 0, v26
	ds_read_b128 v[26:29], v38
	ds_read_b128 v[30:33], v38 offset:16
	ds_read_b128 v[34:37], v38 offset:32
	ds_read_b128 v[38:41], v38 offset:48
	s_waitcnt lgkmcnt(3)
	v_mov_b32_e32 v42, v27
	v_mov_b32_e32 v43, v29
	v_pk_mul_f32 v[24:25], v[42:43], v[24:25]
	v_mov_b32_e32 v27, v28
	v_cndmask_b32_e64 v25, v25, -v25, s[42:43]
	v_cndmask_b32_e64 v24, v24, -v24, s[42:43]
	v_pk_fma_f32 v[10:11], v[10:11], v[26:27], v[24:25]
	s_waitcnt lgkmcnt(2)
	v_mov_b32_e32 v24, v31
	v_mov_b32_e32 v25, v33
	v_pk_mul_f32 v[22:23], v[24:25], v[22:23]
	v_mov_b32_e32 v31, v32
	v_cndmask_b32_e64 v23, v23, -v23, s[42:43]
	v_cndmask_b32_e64 v22, v22, -v22, s[42:43]
	v_pk_fma_f32 v[12:13], v[12:13], v[30:31], v[22:23]
	s_waitcnt lgkmcnt(1)
	v_mov_b32_e32 v22, v35
	v_mov_b32_e32 v23, v37
	v_pk_mul_f32 v[20:21], v[22:23], v[20:21]
	v_mov_b32_e32 v35, v36
	v_cndmask_b32_e64 v21, v21, -v21, s[42:43]
	v_cndmask_b32_e64 v20, v20, -v20, s[42:43]
	v_pk_fma_f32 v[14:15], v[14:15], v[34:35], v[20:21]
	s_waitcnt lgkmcnt(0)
	v_mov_b32_e32 v20, v39
	v_mov_b32_e32 v21, v41
	v_pk_mul_f32 v[18:19], v[20:21], v[18:19]
	v_mov_b32_e32 v39, v40
	v_cndmask_b32_e64 v19, v19, -v19, s[42:43]
	v_cndmask_b32_e64 v18, v18, -v18, s[42:43]
	v_pk_fma_f32 v[16:17], v[16:17], v[38:39], v[18:19]

; template <int NCH, bool ROPE>
; DI void norm_rows16(int lane, size_t row0, bool is_ctx, int t0, const bf16_t* srcA, size_t ldA, int nA, const bf16_t* srcB, size_t ldB,
;                     const float* st, int st_idx, const float* gain, float inv_n, bf16_t* dst, size_t ldd, const float* tab) {
;     ...
;     unpack8(u, f);
;     float ss = 0.f;
; #pragma unroll
;     for (int j = 0; j < 8; ++j) { f[j] *= pre; ss += f[j] * f[j]; }
;     ss += __shfl_xor(ss, 1); ss += __shfl_xor(ss, 2); ss += __shfl_xor(ss, 4); ss += __shfl_xor(ss, 8);
;     const float rs = rsqrtf(ss * inv_n + EPS);
; #pragma unroll
;     for (int j = 0; j < 8; ++j) f[j] *= rs * gv[j];
;     if (ROPE) {
;       float pf[8];
; #pragma unroll
;       for (int j = 0; j < 8; ++j) pf[j] = __shfl_xor(f[j], 1);
;       if (!is_ctx && sub >= 8 && sub < 12) {
;         const int pos = t0 + tk - CTXL;
;         const float* tr = (const float*)smem + ((sub < 10) ? (pos >> 6) : (pos & 63)) * 16;
; #pragma unroll
;         for (int j = 0; j < 8; ++j) {
;           const float c = tr[2 * j], sn = tr[2 * j + 1];
;           f[j] = (sub & 1) ? (pf[j] * sn + f[j] * c) : (f[j] * c - pf[j] * sn);
.LBB0_908:
	s_or_b64 exec, exec, s[0:1]
	s_nop 0
	v_lshlrev_b32_e32 v10, 16, v6
	v_and_b32_e32 v11, 0xffff0000, v6
	v_pk_mul_f32 v[10:11], v[80:81], v[10:11] op_sel_hi:[0,1]
	v_lshlrev_b32_e32 v6, 16, v7
	v_and_b32_e32 v7, 0xffff0000, v7
	v_pk_mul_f32 v[12:13], v[10:11], v[10:11]
	v_pk_mul_f32 v[14:15], v[80:81], v[6:7] op_sel_hi:[0,1]
	v_pk_mul_f32 v[6:7], v[14:15], v[14:15]
	v_lshlrev_b32_e32 v16, 16, v8
	v_and_b32_e32 v17, 0xffff0000, v8
	v_add_f32_e32 v0, v12, v13
	v_pk_mul_f32 v[16:17], v[80:81], v[16:17] op_sel_hi:[0,1]
	v_add_f32_e32 v0, v6, v0
	s_waitcnt lgkmcnt(0)
	v_pk_mul_f32 v[18:19], v[16:17], v[16:17]
	v_lshlrev_b32_e32 v8, 16, v9
	v_and_b32_e32 v9, 0xffff0000, v9
	v_add_f32_e32 v0, v7, v0
	v_pk_mul_f32 v[20:21], v[80:81], v[8:9] op_sel_hi:[0,1]
	v_add_f32_e32 v0, v18, v0
	v_pk_mul_f32 v[8:9], v[20:21], v[20:21]
	v_add_f32_e32 v0, v19, v0
	v_add_f32_e32 v0, v8, v0
	v_add_f32_e32 v0, v9, v0
	s_waitcnt lgkmcnt(0)
	s_nop 1
	v_add_f32_dpp v0, v0, v0 quad_perm:[1,0,3,2] row_mask:0xf bank_mask:0xf
	s_waitcnt lgkmcnt(0)
	s_nop 1
	v_add_f32_dpp v0, v0, v0 quad_perm:[2,3,0,1] row_mask:0xf bank_mask:0xf
	s_waitcnt lgkmcnt(0)
	s_nop 1
	v_add_f32_dpp v0, v0, v0 row_ror:4 row_mask:0xf bank_mask:0xf
	s_waitcnt lgkmcnt(0)
	s_nop 1
	v_add_f32_dpp v0, v0, v0 row_ror:8 row_mask:0xf bank_mask:0xf
	v_fmamk_f32 v0, v0, 0x3c2aaaab, v148
	v_mul_f32_e32 v6, 0x4b800000, v0
	v_cmp_gt_f32_e64 s[0:1], s2, v0
	s_nop 1
	v_cndmask_b32_e64 v0, v0, v6, s[0:1]
	v_rsq_f32_e32 v0, v0
	s_nop 0
	v_mul_f32_e32 v6, 0x45800000, v0
	v_cndmask_b32_e64 v0, v0, v6, s[0:1]
	v_pk_mul_f32 v[6:7], v[72:73], v[0:1] op_sel_hi:[1,0]
	v_pk_mul_f32 v[8:9], v[74:75], v[0:1] op_sel_hi:[1,0]
	v_pk_mul_f32 v[12:13], v[76:77], v[0:1] op_sel_hi:[1,0]
	v_pk_mul_f32 v[18:19], v[78:79], v[0:1] op_sel_hi:[1,0]
	v_pk_mul_f32 v[6:7], v[10:11], v[6:7]
	v_pk_mul_f32 v[8:9], v[14:15], v[8:9]
	v_pk_mul_f32 v[10:11], v[16:17], v[12:13]
	v_pk_mul_f32 v[12:13], v[20:21], v[18:19]
	ds_bpermute_b32 v20, v71, v6
	ds_bpermute_b32 v21, v71, v7
	ds_bpermute_b32 v18, v71, v8
	ds_bpermute_b32 v19, v71, v9
	ds_bpermute_b32 v16, v71, v10
	ds_bpermute_b32 v17, v71, v11
	ds_bpermute_b32 v14, v71, v12
	ds_bpermute_b32 v15, v71, v13
	v_or_b32_e32 v0, 56, v81
	s_and_saveexec_b64 s[0:1], s[26:27]
	s_cbranch_execz .LBB0_910
	v_lshlrev_b32_e32 v22, 6, v0
	v_cndmask_b32_e64 v22, v22, v67, s[44:45]
	v_add_u32_e32 v34, 0, v22
	ds_read_b128 v[22:25], v34
	ds_read_b128 v[26:29], v34 offset:16
	ds_read_b128 v[30:33], v34 offset:32
	ds_read_b128 v[34:37], v34 offset:48
	s_waitcnt lgkmcnt(3)
	v_mov_b32_e32 v38, v23
	v_mov_b32_e32 v39, v25
	v_pk_mul_f32 v[20:21], v[38:39], v[20:21]
	v_mov_b32_e32 v23, v24
	v_cndmask_b32_e64 v21, v21, -v21, s[42:43]
	v_cndmask_b32_e64 v20, v20, -v20, s[42:43]
	v_pk_fma_f32 v[6:7], v[6:7], v[22:23], v[20:21]
	s_waitcnt lgkmcnt(2)
	v_mov_b32_e32 v20, v27
	v_mov_b32_e32 v21, v29
	v_pk_mul_f32 v[18:19], v[20:21], v[18:19]
	v_mov_b32_e32 v27, v28
	v_cndmask_b32_e64 v19, v19, -v19, s[42:43]
	v_cndmask_b32_e64 v18, v18, -v18, s[42:43]
	v_pk_fma_f32 v[8:9], v[8:9], v[26:27], v[18:19]
	s_waitcnt lgkmcnt(1)
	v_mov_b32_e32 v18, v31
	v_mov_b32_e32 v19, v33
	v_pk_mul_f32 v[16:17], v[18:19], v[16:17]
	v_mov_b32_e32 v31, v32
	v_cndmask_b32_e64 v17, v17, -v17, s[42:43]
	v_cndmask_b32_e64 v16, v16, -v16, s[42:43]
	v_pk_fma_f32 v[10:11], v[10:11], v[30:31], v[16:17]
	s_waitcnt lgkmcnt(0)
	v_mov_b32_e32 v16, v35
	v_mov_b32_e32 v17, v37
	v_pk_mul_f32 v[14:15], v[16:17], v[14:15]
	v_mov_b32_e32 v35, v36
	v_cndmask_b32_e64 v15, v15, -v15, s[42:43]
	v_cndmask_b32_e64 v14, v14, -v14, s[42:43]
	v_pk_fma_f32 v[12:13], v[12:13], v[34:35], v[14:15]

; template <int NCH, bool ROPE>
; DI void norm_rows16(int lane, size_t row0, bool is_ctx, int t0, const bf16_t* srcA, size_t ldA, int nA, const bf16_t* srcB, size_t ldB,
;                     const float* st, int st_idx, const float* gain, float inv_n, bf16_t* dst, size_t ldd, const float* tab) {
;     ...
;     unpack8(u, f);
;     float ss = 0.f;
; #pragma unroll
;     for (int j = 0; j < 8; ++j) { f[j] *= pre; ss += f[j] * f[j]; }
;     ss += __shfl_xor(ss, 1); ss += __shfl_xor(ss, 2); ss += __shfl_xor(ss, 4); ss += __shfl_xor(ss, 8);
;     const float rs = rsqrtf(ss * inv_n + EPS);
; #pragma unroll
;     for (int j = 0; j < 8; ++j) f[j] *= rs * gv[j];
;     if (ROPE) {
;       float pf[8];
; #pragma unroll
;       for (int j = 0; j < 8; ++j) pf[j] = __shfl_xor(f[j], 1);
;       if (!is_ctx && sub >= 8 && sub < 12) {
;         const int pos = t0 + tk - CTXL;
;         const float* tr = (const float*)smem + ((sub < 10) ? (pos >> 6) : (pos & 63)) * 16;
; #pragma unroll
;         for (int j = 0; j < 8; ++j) {
;           const float c = tr[2 * j], sn = tr[2 * j + 1];
;           f[j] = (sub & 1) ? (pf[j] * sn + f[j] * c) : (f[j] * c - pf[j] * sn);
.LBB0_912:
	s_or_b64 exec, exec, s[0:1]
	s_nop 0
	v_lshlrev_b32_e32 v6, 16, v2
	v_and_b32_e32 v7, 0xffff0000, v2
	v_pk_mul_f32 v[6:7], v[70:71], v[6:7] op_sel_hi:[0,1]
	v_lshlrev_b32_e32 v2, 16, v3
	v_and_b32_e32 v3, 0xffff0000, v3
	v_pk_mul_f32 v[8:9], v[6:7], v[6:7]
	v_pk_mul_f32 v[10:11], v[70:71], v[2:3] op_sel_hi:[0,1]
	v_pk_mul_f32 v[2:3], v[10:11], v[10:11]
	v_lshlrev_b32_e32 v12, 16, v4
	v_and_b32_e32 v13, 0xffff0000, v4
	v_add_f32_e32 v0, v8, v9
	v_pk_mul_f32 v[12:13], v[70:71], v[12:13] op_sel_hi:[0,1]
	v_add_f32_e32 v0, v2, v0
	s_waitcnt lgkmcnt(0)
	v_pk_mul_f32 v[14:15], v[12:13], v[12:13]
	v_lshlrev_b32_e32 v4, 16, v5
	v_and_b32_e32 v5, 0xffff0000, v5
	v_add_f32_e32 v0, v3, v0
	v_pk_mul_f32 v[16:17], v[70:71], v[4:5] op_sel_hi:[0,1]
	v_add_f32_e32 v0, v14, v0
	v_pk_mul_f32 v[4:5], v[16:17], v[16:17]
	v_add_f32_e32 v0, v15, v0
	v_add_f32_e32 v0, v4, v0
	v_add_f32_e32 v0, v5, v0
	s_waitcnt lgkmcnt(0)
	s_nop 1
	v_add_f32_dpp v0, v0, v0 quad_perm:[1,0,3,2] row_mask:0xf bank_mask:0xf
	s_waitcnt lgkmcnt(0)
	s_nop 1
	v_add_f32_dpp v0, v0, v0 quad_perm:[2,3,0,1] row_mask:0xf bank_mask:0xf
	s_waitcnt lgkmcnt(0)
	s_nop 1
	v_add_f32_dpp v0, v0, v0 row_ror:4 row_mask:0xf bank_mask:0xf
	s_waitcnt lgkmcnt(0)
	s_nop 1
	v_add_f32_dpp v0, v0, v0 row_ror:8 row_mask:0xf bank_mask:0xf
	v_fmamk_f32 v0, v0, 0x3c2aaaab, v148
	v_mul_f32_e32 v2, 0x4b800000, v0
	v_cmp_gt_f32_e64 s[0:1], s2, v0
	s_nop 1
	v_cndmask_b32_e64 v0, v0, v2, s[0:1]
	v_rsq_f32_e32 v0, v0
	s_nop 0
	v_mul_f32_e32 v2, 0x45800000, v0
	v_cndmask_b32_e64 v0, v0, v2, s[0:1]
	v_pk_mul_f32 v[2:3], v[72:73], v[0:1] op_sel_hi:[1,0]
	v_pk_mul_f32 v[4:5], v[74:75], v[0:1] op_sel_hi:[1,0]
	v_pk_mul_f32 v[8:9], v[76:77], v[0:1] op_sel_hi:[1,0]
	v_pk_mul_f32 v[14:15], v[78:79], v[0:1] op_sel_hi:[1,0]
	v_pk_mul_f32 v[2:3], v[6:7], v[2:3]
	v_pk_mul_f32 v[4:5], v[10:11], v[4:5]
	v_pk_mul_f32 v[6:7], v[12:13], v[8:9]
	v_pk_mul_f32 v[8:9], v[16:17], v[14:15]
	ds_bpermute_b32 v16, v71, v2
	ds_bpermute_b32 v17, v71, v3
	ds_bpermute_b32 v14, v71, v4
	ds_bpermute_b32 v15, v71, v5
	ds_bpermute_b32 v12, v71, v6
	ds_bpermute_b32 v13, v71, v7
	ds_bpermute_b32 v10, v71, v8
	ds_bpermute_b32 v11, v71, v9
	v_or_b32_e32 v0, 60, v81
	s_and_saveexec_b64 s[0:1], s[26:27]
	s_cbranch_execz .LBB0_914
	v_lshlrev_b32_e32 v18, 6, v0
	v_cndmask_b32_e64 v18, v18, v67, s[44:45]
	v_add_u32_e32 v30, 0, v18
	ds_read_b128 v[18:21], v30
	ds_read_b128 v[22:25], v30 offset:16
	ds_read_b128 v[26:29], v30 offset:32
	ds_read_b128 v[30:33], v30 offset:48
	s_waitcnt lgkmcnt(3)
	v_mov_b32_e32 v34, v19
	v_mov_b32_e32 v35, v21
	v_pk_mul_f32 v[16:17], v[34:35], v[16:17]
	v_mov_b32_e32 v19, v20
	v_cndmask_b32_e64 v17, v17, -v17, s[42:43]
	v_cndmask_b32_e64 v16, v16, -v16, s[42:43]
	v_pk_fma_f32 v[2:3], v[2:3], v[18:19], v[16:17]
	s_waitcnt lgkmcnt(2)
	v_mov_b32_e32 v16, v23
	v_mov_b32_e32 v17, v25
	v_pk_mul_f32 v[14:15], v[16:17], v[14:15]
	v_mov_b32_e32 v23, v24
	v_cndmask_b32_e64 v15, v15, -v15, s[42:43]
	v_cndmask_b32_e64 v14, v14, -v14, s[42:43]
	v_pk_fma_f32 v[4:5], v[4:5], v[22:23], v[14:15]
	s_waitcnt lgkmcnt(1)
	v_mov_b32_e32 v14, v27
	v_mov_b32_e32 v15, v29
	v_pk_mul_f32 v[12:13], v[14:15], v[12:13]
	v_mov_b32_e32 v27, v28
	v_cndmask_b32_e64 v13, v13, -v13, s[42:43]
	v_cndmask_b32_e64 v12, v12, -v12, s[42:43]
	v_pk_fma_f32 v[6:7], v[6:7], v[26:27], v[12:13]
	s_waitcnt lgkmcnt(0)
	v_mov_b32_e32 v12, v31
	v_mov_b32_e32 v13, v33
	v_pk_mul_f32 v[10:11], v[12:13], v[10:11]
	v_mov_b32_e32 v31, v32
	v_cndmask_b32_e64 v11, v11, -v11, s[42:43]
	v_cndmask_b32_e64 v10, v10, -v10, s[42:43]
	v_pk_fma_f32 v[8:9], v[8:9], v[30:31], v[10:11]
